# attention: separate loop bodies for the two wave halves (no per-iteration role branches)
# speedup vs baseline: 1.0042x; 1.0038x over previous
.Lattn_tb1_A:
	s_waitcnt lgkmcnt(5)
	v_mfma_f32_32x32x16_bf16 v[96:111], v[208:211], v[128:131], 0
	ds_read_b128 v[208:211], v185 offset:16384
	s_add_i32 s2, s42, 4
	s_and_b32 s2, s2, 31
	s_waitcnt lgkmcnt(5)
	v_mfma_f32_32x32x16_bf16 v[112:127], v[212:215], v[128:131], 0
	ds_read_b128 v[212:215], v185 offset:20480
	s_mul_i32 s2, s2, 0x44000
	s_add_u32 s48, s26, s2
	s_waitcnt lgkmcnt(5)
	v_mfma_f32_32x32x16_bf16 v[96:111], v[216:219], v[132:135], v[96:111]
	s_addc_u32 s49, s27, 0
	s_add_u32 s50, s48, 0x80
	s_waitcnt lgkmcnt(4)
	v_mfma_f32_32x32x16_bf16 v[112:127], v[220:223], v[132:135], v[112:127]
	s_addc_u32 s51, s49, 0
	s_add_i32 s2, s42, 2
	s_waitcnt lgkmcnt(3)
	v_mfma_f32_32x32x16_bf16 v[96:111], v[224:227], v[136:139], v[96:111]
	s_and_b32 s2, s2, 31
	s_lshl_b32 s2, s2, 7
	s_waitcnt lgkmcnt(2)
	v_mfma_f32_32x32x16_bf16 v[112:127], v[228:231], v[136:139], v[112:127]
	s_add_u32 s52, s10, s2
	s_addc_u32 s53, s11, 0
	s_waitcnt lgkmcnt(1)
	v_mfma_f32_32x32x16_bf16 v[96:111], v[208:211], v[140:143], v[96:111]
	s_add_u32 s54, s52, 0x204000
	s_addc_u32 s55, s53, 0
	s_waitcnt lgkmcnt(0)
	v_mfma_f32_32x32x16_bf16 v[112:127], v[212:215], v[140:143], v[112:127]
	ds_read_b128 v[216:219], v187 offset:0
	ds_read_b128 v[220:223], v187 offset:4096
	ds_read_b128 v[224:227], v187 offset:8192
	ds_read_b128 v[228:231], v187 offset:12288
	ds_read_b128 v[208:211], v188 offset:0
	ds_read_b128 v[212:215], v188 offset:4096
	v_max3_f32 v254, v64, v65, v66
	s_add_i32 m0, s5, 0
	v_max3_f32 v255, v80, v81, v82
	global_load_lds_dwordx4 v170, s[48:49]
	v_max3_f32 v254, v254, v67, v68
	s_add_i32 m0, s5, 8192
	v_max3_f32 v255, v255, v83, v84
	global_load_lds_dwordx4 v170, s[50:51]
	v_max3_f32 v254, v254, v69, v70
	s_add_i32 m0, s5, 98304
	v_max3_f32 v255, v255, v85, v86
	global_load_lds_dwordx4 v172, s[52:53]
	v_max3_f32 v254, v254, v71, v72
	s_add_i32 m0, s5, 106496
	v_max3_f32 v255, v255, v87, v88
	global_load_lds_dwordx4 v172, s[54:55]
	v_max3_f32 v254, v254, v73, v74
	v_max3_f32 v255, v255, v89, v90
	v_max3_f32 v254, v254, v75, v76
	v_max3_f32 v255, v255, v91, v92
	v_max3_f32 v254, v254, v77, v78
	v_max3_f32 v255, v255, v93, v94
	v_max3_f32 v254, v254, v79, v95
	v_max_f32_e32 v254, v254, v255
	v_mov_b32_e32 v180, 0xc2800000
	v_cmp_lt_f32_e32 vcc, 0x4138aa3b, v254
	v_cmp_gt_f32_e64 s[40:41], v180, v254
	s_nop 4
	s_or_b64 vcc, vcc, s[40:41]
	s_nop 0
	s_cbranch_vccnz .Lattn_sp_t0_A
	v_exp_f32_e32 v64, v64
	v_exp_f32_e32 v65, v65
	v_exp_f32_e32 v66, v66
	v_exp_f32_e32 v67, v67
	v_exp_f32_e32 v68, v68
	v_exp_f32_e32 v69, v69
	v_exp_f32_e32 v70, v70
	v_exp_f32_e32 v71, v71
	v_add_f32_e32 v190, v64, v65
	v_add_f32_e32 v191, v66, v67
	v_add_f32_e32 v190, v190, v68
	v_add_f32_e32 v191, v191, v69
	v_add_f32_e32 v190, v190, v70
	v_add_f32_e32 v191, v191, v71
	v_cvt_pk_bf16_f32 v144, v64, v65
	v_cvt_pk_bf16_f32 v145, v66, v67
	v_cvt_pk_bf16_f32 v146, v68, v69
	v_cvt_pk_bf16_f32 v147, v70, v71
	v_exp_f32_e32 v72, v72
	v_exp_f32_e32 v73, v73
	v_exp_f32_e32 v74, v74
	v_exp_f32_e32 v75, v75
	v_exp_f32_e32 v76, v76
	v_exp_f32_e32 v77, v77
	v_exp_f32_e32 v78, v78
	v_exp_f32_e32 v79, v79
	v_add_f32_e32 v190, v190, v72
	v_add_f32_e32 v191, v191, v73
	v_add_f32_e32 v190, v190, v74
	v_add_f32_e32 v191, v191, v75
	v_add_f32_e32 v190, v190, v76
	v_add_f32_e32 v191, v191, v77
	v_add_f32_e32 v190, v190, v78
	v_add_f32_e32 v191, v191, v79
	v_cvt_pk_bf16_f32 v148, v72, v73
	v_cvt_pk_bf16_f32 v149, v74, v75
	v_cvt_pk_bf16_f32 v150, v76, v77
	v_cvt_pk_bf16_f32 v151, v78, v79
	v_exp_f32_e32 v80, v80
	v_exp_f32_e32 v81, v81
	v_exp_f32_e32 v82, v82
	v_exp_f32_e32 v83, v83
	v_exp_f32_e32 v84, v84
	v_exp_f32_e32 v85, v85
	v_exp_f32_e32 v86, v86
	v_exp_f32_e32 v87, v87
	v_add_f32_e32 v190, v190, v80
	v_add_f32_e32 v191, v191, v81
	v_add_f32_e32 v190, v190, v82
	v_add_f32_e32 v191, v191, v83
	v_add_f32_e32 v190, v190, v84
	v_add_f32_e32 v191, v191, v85
	v_add_f32_e32 v190, v190, v86
	v_add_f32_e32 v191, v191, v87
	v_cvt_pk_bf16_f32 v152, v80, v81
	v_cvt_pk_bf16_f32 v153, v82, v83
	v_cvt_pk_bf16_f32 v154, v84, v85
	v_cvt_pk_bf16_f32 v155, v86, v87
	v_exp_f32_e32 v88, v88
	v_exp_f32_e32 v89, v89
	v_exp_f32_e32 v90, v90
	v_exp_f32_e32 v91, v91
	v_exp_f32_e32 v92, v92
	v_exp_f32_e32 v93, v93
	v_exp_f32_e32 v94, v94
	v_exp_f32_e32 v95, v95
	v_add_f32_e32 v190, v190, v88
	v_add_f32_e32 v191, v191, v89
	v_add_f32_e32 v190, v190, v90
	v_add_f32_e32 v191, v191, v91
	v_add_f32_e32 v190, v190, v92
	v_add_f32_e32 v191, v191, v93
	v_add_f32_e32 v190, v190, v94
	v_add_f32_e32 v191, v191, v95
	v_cvt_pk_bf16_f32 v156, v88, v89
	v_cvt_pk_bf16_f32 v157, v90, v91
	v_cvt_pk_bf16_f32 v158, v92, v93
	v_cvt_pk_bf16_f32 v159, v94, v95
	v_add_f32_e32 v190, v190, v191
	v_add_f32_e32 v167, v167, v190
	s_add_i32 s42, s31, 1
	s_movk_i32 s47, 7
.Lattn_loop_f_A:
	s_waitcnt vmcnt(4)
	s_barrier
.Lattn_tb3_A:
	s_waitcnt lgkmcnt(5)
	v_mfma_f32_32x32x16_bf16 v[48:63], v[216:219], v[144:147], v[48:63]
	ds_read_b128 v[216:219], v188 offset:8192
	s_add_i32 s2, s42, 4
	s_waitcnt lgkmcnt(5)
	v_mfma_f32_32x32x16_bf16 v[32:47], v[220:223], v[144:147], v[32:47]
	ds_read_b128 v[220:223], v188 offset:12288
	s_and_b32 s2, s2, 31
	s_waitcnt lgkmcnt(5)
	v_mfma_f32_32x32x16_bf16 v[16:31], v[224:227], v[144:147], v[16:31]
	ds_read_b128 v[224:227], v186 offset:0
	s_mul_i32 s2, s2, 0x44000
	s_waitcnt lgkmcnt(5)
	v_mfma_f32_32x32x16_bf16 v[0:15], v[228:231], v[144:147], v[0:15]
	ds_read_b128 v[228:231], v186 offset:4096
	s_add_u32 s48, s26, s2
	s_waitcnt lgkmcnt(5)
	v_mfma_f32_32x32x16_bf16 v[48:63], v[208:211], v[148:151], v[48:63]
	ds_read_b128 v[208:211], v186 offset:8192
	s_addc_u32 s49, s27, 0
	s_waitcnt lgkmcnt(5)
	v_mfma_f32_32x32x16_bf16 v[32:47], v[212:215], v[148:151], v[32:47]
	ds_read_b128 v[212:215], v186 offset:12288
	s_add_u32 s50, s48, 0x80
	s_waitcnt lgkmcnt(5)
	v_mfma_f32_32x32x16_bf16 v[16:31], v[216:219], v[148:151], v[16:31]
	ds_read_b128 v[216:219], v189 offset:0
	s_addc_u32 s51, s49, 0
	s_waitcnt lgkmcnt(5)
	v_mfma_f32_32x32x16_bf16 v[0:15], v[220:223], v[148:151], v[0:15]
	ds_read_b128 v[220:223], v189 offset:4096
	s_add_i32 s2, s42, 2
	s_waitcnt lgkmcnt(5)
	v_mfma_f32_32x32x16_bf16 v[48:63], v[224:227], v[152:155], v[48:63]
	ds_read_b128 v[224:227], v189 offset:8192
	s_and_b32 s2, s2, 31
	s_waitcnt lgkmcnt(5)
	v_mfma_f32_32x32x16_bf16 v[32:47], v[228:231], v[152:155], v[32:47]
	ds_read_b128 v[228:231], v189 offset:12288
	s_lshl_b32 s2, s2, 7
	s_waitcnt lgkmcnt(5)
	v_mfma_f32_32x32x16_bf16 v[16:31], v[208:211], v[152:155], v[16:31]
	ds_read_b128 v[208:211], v182 offset:32768
	s_add_u32 s52, s10, s2
	s_waitcnt lgkmcnt(5)
	v_mfma_f32_32x32x16_bf16 v[0:15], v[212:215], v[152:155], v[0:15]
	ds_read_b128 v[212:215], v182 offset:36864
	s_addc_u32 s53, s11, 0
	s_waitcnt lgkmcnt(5)
	v_mfma_f32_32x32x16_bf16 v[48:63], v[216:219], v[156:159], v[48:63]
	ds_read_b128 v[216:219], v183 offset:32768
	s_add_u32 s54, s52, 0x204000
	s_waitcnt lgkmcnt(5)
	v_mfma_f32_32x32x16_bf16 v[32:47], v[220:223], v[156:159], v[32:47]
	ds_read_b128 v[220:223], v183 offset:36864
	s_addc_u32 s55, s53, 0
	s_waitcnt lgkmcnt(5)
	v_mfma_f32_32x32x16_bf16 v[16:31], v[224:227], v[156:159], v[16:31]
	ds_read_b128 v[224:227], v184 offset:32768
	s_waitcnt lgkmcnt(5)
	v_mfma_f32_32x32x16_bf16 v[0:15], v[228:231], v[156:159], v[0:15]
	ds_read_b128 v[228:231], v184 offset:36864
	s_waitcnt lgkmcnt(5)
	v_mfma_f32_32x32x16_bf16 v[64:79], v[208:211], v[128:131], 0
	ds_read_b128 v[208:211], v185 offset:32768
	s_waitcnt lgkmcnt(5)
	v_mfma_f32_32x32x16_bf16 v[80:95], v[212:215], v[128:131], 0
	ds_read_b128 v[212:215], v185 offset:36864
	s_waitcnt lgkmcnt(5)
	v_mfma_f32_32x32x16_bf16 v[64:79], v[216:219], v[132:135], v[64:79]
	s_waitcnt lgkmcnt(4)
	v_mfma_f32_32x32x16_bf16 v[80:95], v[220:223], v[132:135], v[80:95]
	s_waitcnt lgkmcnt(3)
	v_mfma_f32_32x32x16_bf16 v[64:79], v[224:227], v[136:139], v[64:79]
	s_waitcnt lgkmcnt(2)
	v_mfma_f32_32x32x16_bf16 v[80:95], v[228:231], v[136:139], v[80:95]
	s_waitcnt lgkmcnt(1)
	v_mfma_f32_32x32x16_bf16 v[64:79], v[208:211], v[140:143], v[64:79]
	s_waitcnt lgkmcnt(0)
	v_mfma_f32_32x32x16_bf16 v[80:95], v[212:215], v[140:143], v[80:95]
	ds_read_b128 v[216:219], v187 offset:16384
	ds_read_b128 v[220:223], v187 offset:20480
	ds_read_b128 v[224:227], v187 offset:24576
	ds_read_b128 v[228:231], v187 offset:28672
	ds_read_b128 v[208:211], v188 offset:16384
	ds_read_b128 v[212:215], v188 offset:20480
	v_exp_f32_e32 v171, v96
	v_exp_f32_e32 v173, v97
	v_exp_f32_e32 v179, v98
	s_add_i32 m0, s5, 16384
	v_exp_f32_e32 v180, v99
	v_exp_f32_e32 v232, v100
	v_exp_f32_e32 v233, v101
	global_load_lds_dwordx4 v170, s[48:49]
	v_exp_f32_e32 v234, v102
	v_exp_f32_e32 v235, v103
	v_add_f32_e32 v190, v171, v173
	s_add_i32 m0, s5, 24576
	v_add_f32_e32 v191, v179, v180
	v_add_f32_e32 v190, v190, v232
	v_add_f32_e32 v191, v191, v233
	global_load_lds_dwordx4 v170, s[50:51]
	v_add_f32_e32 v190, v190, v234
	v_add_f32_e32 v191, v191, v235
	v_cvt_pk_bf16_f32 v144, v171, v173
	s_add_i32 m0, s5, 114688
	v_cvt_pk_bf16_f32 v145, v179, v180
	v_cvt_pk_bf16_f32 v146, v232, v233
	v_cvt_pk_bf16_f32 v147, v234, v235
	global_load_lds_dwordx4 v172, s[52:53]
	v_exp_f32_e32 v171, v104
	v_exp_f32_e32 v173, v105
	v_exp_f32_e32 v179, v106
	s_add_i32 m0, s5, 122880
	v_exp_f32_e32 v180, v107
	v_exp_f32_e32 v232, v108
	v_exp_f32_e32 v233, v109
	global_load_lds_dwordx4 v172, s[54:55]
	v_exp_f32_e32 v234, v110
	v_exp_f32_e32 v235, v111
	v_add_f32_e32 v190, v190, v171
	v_add_f32_e32 v191, v191, v173
	v_add_f32_e32 v190, v190, v179
	v_add_f32_e32 v191, v191, v180
	v_add_f32_e32 v190, v190, v232
	v_add_f32_e32 v191, v191, v233
	v_add_f32_e32 v190, v190, v234
	v_add_f32_e32 v191, v191, v235
	v_cvt_pk_bf16_f32 v148, v171, v173
	v_cvt_pk_bf16_f32 v149, v179, v180
	v_cvt_pk_bf16_f32 v150, v232, v233
	v_cvt_pk_bf16_f32 v151, v234, v235
	v_exp_f32_e32 v171, v112
	v_exp_f32_e32 v173, v113
	v_exp_f32_e32 v179, v114
	v_exp_f32_e32 v180, v115
	v_exp_f32_e32 v232, v116
	v_exp_f32_e32 v233, v117
	v_exp_f32_e32 v234, v118
	v_exp_f32_e32 v235, v119
	v_add_f32_e32 v190, v190, v171
	v_add_f32_e32 v191, v191, v173
	v_add_f32_e32 v190, v190, v179
	v_add_f32_e32 v191, v191, v180
	v_add_f32_e32 v190, v190, v232
	v_add_f32_e32 v191, v191, v233
	v_add_f32_e32 v190, v190, v234
	v_add_f32_e32 v191, v191, v235
	v_cvt_pk_bf16_f32 v152, v171, v173
	v_cvt_pk_bf16_f32 v153, v179, v180
	v_cvt_pk_bf16_f32 v154, v232, v233
	v_cvt_pk_bf16_f32 v155, v234, v235
	v_exp_f32_e32 v171, v120
	v_exp_f32_e32 v173, v121
	v_exp_f32_e32 v179, v122
	v_exp_f32_e32 v180, v123
	v_exp_f32_e32 v232, v124
	v_exp_f32_e32 v233, v125
	v_exp_f32_e32 v234, v126
	v_exp_f32_e32 v235, v127
	v_add_f32_e32 v190, v190, v171
	v_add_f32_e32 v191, v191, v173
	v_add_f32_e32 v190, v190, v179
	v_add_f32_e32 v191, v191, v180
	v_add_f32_e32 v190, v190, v232
	v_add_f32_e32 v191, v191, v233
	v_add_f32_e32 v190, v190, v234
	v_add_f32_e32 v191, v191, v235
	v_add_f32_e32 v190, v190, v191
	v_cmp_ngt_f32_e32 vcc, 0x71800000, v190
	v_cvt_pk_bf16_f32 v156, v171, v173
	v_cvt_pk_bf16_f32 v157, v179, v180
	v_cvt_pk_bf16_f32 v158, v232, v233
	v_cvt_pk_bf16_f32 v159, v234, v235
	s_nop 0
	s_cbranch_vccnz .Lattn_redo_L0_A
	v_add_f32_e32 v167, v167, v190
	s_waitcnt vmcnt(4)
	s_barrier
.Lattn_tb5_A:
	s_waitcnt lgkmcnt(5)
	v_mfma_f32_32x32x16_bf16 v[48:63], v[216:219], v[144:147], v[48:63]
	ds_read_b128 v[216:219], v188 offset:24576
	s_add_i32 s2, s42, 5
	s_waitcnt lgkmcnt(5)
	v_mfma_f32_32x32x16_bf16 v[32:47], v[220:223], v[144:147], v[32:47]
	ds_read_b128 v[220:223], v188 offset:28672
	s_and_b32 s2, s2, 31
	s_waitcnt lgkmcnt(5)
	v_mfma_f32_32x32x16_bf16 v[16:31], v[224:227], v[144:147], v[16:31]
	ds_read_b128 v[224:227], v186 offset:16384
	s_mul_i32 s2, s2, 0x44000
	s_waitcnt lgkmcnt(5)
	v_mfma_f32_32x32x16_bf16 v[0:15], v[228:231], v[144:147], v[0:15]
	ds_read_b128 v[228:231], v186 offset:20480
	s_add_u32 s48, s26, s2
	s_waitcnt lgkmcnt(5)
	v_mfma_f32_32x32x16_bf16 v[48:63], v[208:211], v[148:151], v[48:63]
	ds_read_b128 v[208:211], v186 offset:24576
	s_addc_u32 s49, s27, 0
	s_waitcnt lgkmcnt(5)
	v_mfma_f32_32x32x16_bf16 v[32:47], v[212:215], v[148:151], v[32:47]
	ds_read_b128 v[212:215], v186 offset:28672
	s_add_u32 s50, s48, 0x80
	s_waitcnt lgkmcnt(5)
	v_mfma_f32_32x32x16_bf16 v[16:31], v[216:219], v[148:151], v[16:31]
	ds_read_b128 v[216:219], v189 offset:16384
	s_addc_u32 s51, s49, 0
	s_waitcnt lgkmcnt(5)
	v_mfma_f32_32x32x16_bf16 v[0:15], v[220:223], v[148:151], v[0:15]
	ds_read_b128 v[220:223], v189 offset:20480
	s_add_i32 s2, s42, 3
	s_waitcnt lgkmcnt(5)
	v_mfma_f32_32x32x16_bf16 v[48:63], v[224:227], v[152:155], v[48:63]
	ds_read_b128 v[224:227], v189 offset:24576
	s_and_b32 s2, s2, 31
	s_waitcnt lgkmcnt(5)
	v_mfma_f32_32x32x16_bf16 v[32:47], v[228:231], v[152:155], v[32:47]
	ds_read_b128 v[228:231], v189 offset:28672
	s_lshl_b32 s2, s2, 7
	s_waitcnt lgkmcnt(5)
	v_mfma_f32_32x32x16_bf16 v[16:31], v[208:211], v[152:155], v[16:31]
	ds_read_b128 v[208:211], v182 offset:49152
	s_add_u32 s52, s10, s2
	s_waitcnt lgkmcnt(5)
	v_mfma_f32_32x32x16_bf16 v[0:15], v[212:215], v[152:155], v[0:15]
	ds_read_b128 v[212:215], v182 offset:53248
	s_addc_u32 s53, s11, 0
	s_waitcnt lgkmcnt(5)
	v_mfma_f32_32x32x16_bf16 v[48:63], v[216:219], v[156:159], v[48:63]
	ds_read_b128 v[216:219], v183 offset:49152
	s_add_u32 s54, s52, 0x204000
	s_waitcnt lgkmcnt(5)
	v_mfma_f32_32x32x16_bf16 v[32:47], v[220:223], v[156:159], v[32:47]
	ds_read_b128 v[220:223], v183 offset:53248
	s_addc_u32 s55, s53, 0
	s_waitcnt lgkmcnt(5)
	v_mfma_f32_32x32x16_bf16 v[16:31], v[224:227], v[156:159], v[16:31]
	ds_read_b128 v[224:227], v184 offset:49152
	s_waitcnt lgkmcnt(5)
	v_mfma_f32_32x32x16_bf16 v[0:15], v[228:231], v[156:159], v[0:15]
	ds_read_b128 v[228:231], v184 offset:53248
	s_waitcnt lgkmcnt(5)
	v_mfma_f32_32x32x16_bf16 v[96:111], v[208:211], v[128:131], 0
	ds_read_b128 v[208:211], v185 offset:49152
	s_waitcnt lgkmcnt(5)
	v_mfma_f32_32x32x16_bf16 v[112:127], v[212:215], v[128:131], 0
	ds_read_b128 v[212:215], v185 offset:53248
	s_waitcnt lgkmcnt(5)
	v_mfma_f32_32x32x16_bf16 v[96:111], v[216:219], v[132:135], v[96:111]
	s_waitcnt lgkmcnt(4)
	v_mfma_f32_32x32x16_bf16 v[112:127], v[220:223], v[132:135], v[112:127]
	s_waitcnt lgkmcnt(3)
	v_mfma_f32_32x32x16_bf16 v[96:111], v[224:227], v[136:139], v[96:111]
	s_waitcnt lgkmcnt(2)
	v_mfma_f32_32x32x16_bf16 v[112:127], v[228:231], v[136:139], v[112:127]
	s_waitcnt lgkmcnt(1)
	v_mfma_f32_32x32x16_bf16 v[96:111], v[208:211], v[140:143], v[96:111]
	s_waitcnt lgkmcnt(0)
	v_mfma_f32_32x32x16_bf16 v[112:127], v[212:215], v[140:143], v[112:127]
	ds_read_b128 v[216:219], v187 offset:32768
	ds_read_b128 v[220:223], v187 offset:36864
	ds_read_b128 v[224:227], v187 offset:40960
	ds_read_b128 v[228:231], v187 offset:45056
	ds_read_b128 v[208:211], v188 offset:32768
	ds_read_b128 v[212:215], v188 offset:36864
	v_exp_f32_e32 v171, v64
	v_exp_f32_e32 v173, v65
	v_exp_f32_e32 v179, v66
	s_add_i32 m0, s5, 32768
	v_exp_f32_e32 v180, v67
	v_exp_f32_e32 v232, v68
	v_exp_f32_e32 v233, v69
	global_load_lds_dwordx4 v170, s[48:49]
	v_exp_f32_e32 v234, v70
	v_exp_f32_e32 v235, v71
	v_add_f32_e32 v190, v171, v173
	s_add_i32 m0, s5, 40960
	v_add_f32_e32 v191, v179, v180
	v_add_f32_e32 v190, v190, v232
	v_add_f32_e32 v191, v191, v233
	global_load_lds_dwordx4 v170, s[50:51]
	v_add_f32_e32 v190, v190, v234
	v_add_f32_e32 v191, v191, v235
	v_cvt_pk_bf16_f32 v144, v171, v173
	s_add_i32 m0, s5, 65536
	v_cvt_pk_bf16_f32 v145, v179, v180
	v_cvt_pk_bf16_f32 v146, v232, v233
	v_cvt_pk_bf16_f32 v147, v234, v235
	global_load_lds_dwordx4 v172, s[52:53]
	v_exp_f32_e32 v171, v72
	v_exp_f32_e32 v173, v73
	v_exp_f32_e32 v179, v74
	s_add_i32 m0, s5, 73728
	v_exp_f32_e32 v180, v75
	v_exp_f32_e32 v232, v76
	v_exp_f32_e32 v233, v77
	global_load_lds_dwordx4 v172, s[54:55]
	v_exp_f32_e32 v234, v78
	v_exp_f32_e32 v235, v79
	v_add_f32_e32 v190, v190, v171
	v_add_f32_e32 v191, v191, v173
	v_add_f32_e32 v190, v190, v179
	v_add_f32_e32 v191, v191, v180
	v_add_f32_e32 v190, v190, v232
	v_add_f32_e32 v191, v191, v233
	v_add_f32_e32 v190, v190, v234
	v_add_f32_e32 v191, v191, v235
	v_cvt_pk_bf16_f32 v148, v171, v173
	v_cvt_pk_bf16_f32 v149, v179, v180
	v_cvt_pk_bf16_f32 v150, v232, v233
	v_cvt_pk_bf16_f32 v151, v234, v235
	v_exp_f32_e32 v171, v80
	v_exp_f32_e32 v173, v81
	v_exp_f32_e32 v179, v82
	v_exp_f32_e32 v180, v83
	v_exp_f32_e32 v232, v84
	v_exp_f32_e32 v233, v85
	v_exp_f32_e32 v234, v86
	v_exp_f32_e32 v235, v87
	v_add_f32_e32 v190, v190, v171
	v_add_f32_e32 v191, v191, v173
	v_add_f32_e32 v190, v190, v179
	v_add_f32_e32 v191, v191, v180
	v_add_f32_e32 v190, v190, v232
	v_add_f32_e32 v191, v191, v233
	v_add_f32_e32 v190, v190, v234
	v_add_f32_e32 v191, v191, v235
	v_cvt_pk_bf16_f32 v152, v171, v173
	v_cvt_pk_bf16_f32 v153, v179, v180
	v_cvt_pk_bf16_f32 v154, v232, v233
	v_cvt_pk_bf16_f32 v155, v234, v235
	v_exp_f32_e32 v171, v88
	v_exp_f32_e32 v173, v89
	v_exp_f32_e32 v179, v90
	v_exp_f32_e32 v180, v91
	v_exp_f32_e32 v232, v92
	v_exp_f32_e32 v233, v93
	v_exp_f32_e32 v234, v94
	v_exp_f32_e32 v235, v95
	v_add_f32_e32 v190, v190, v171
	v_add_f32_e32 v191, v191, v173
	v_add_f32_e32 v190, v190, v179
	v_add_f32_e32 v191, v191, v180
	v_add_f32_e32 v190, v190, v232
	v_add_f32_e32 v191, v191, v233
	v_add_f32_e32 v190, v190, v234
	v_add_f32_e32 v191, v191, v235
	v_add_f32_e32 v190, v190, v191
	v_cmp_ngt_f32_e32 vcc, 0x71800000, v190
	v_cvt_pk_bf16_f32 v156, v171, v173
	v_cvt_pk_bf16_f32 v157, v179, v180
	v_cvt_pk_bf16_f32 v158, v232, v233
	v_cvt_pk_bf16_f32 v159, v234, v235
	s_nop 0
	s_cbranch_vccnz .Lattn_redo_L1_A
	v_add_f32_e32 v167, v167, v190
	s_waitcnt vmcnt(4)
	s_barrier
.Lattn_tb7_A:
	s_waitcnt lgkmcnt(5)
	v_mfma_f32_32x32x16_bf16 v[48:63], v[216:219], v[144:147], v[48:63]
	ds_read_b128 v[216:219], v188 offset:40960
	s_add_i32 s2, s42, 6
	s_waitcnt lgkmcnt(5)
	v_mfma_f32_32x32x16_bf16 v[32:47], v[220:223], v[144:147], v[32:47]
	ds_read_b128 v[220:223], v188 offset:45056
	s_and_b32 s2, s2, 31
	s_waitcnt lgkmcnt(5)
	v_mfma_f32_32x32x16_bf16 v[16:31], v[224:227], v[144:147], v[16:31]
	ds_read_b128 v[224:227], v186 offset:32768
	s_mul_i32 s2, s2, 0x44000
	s_waitcnt lgkmcnt(5)
	v_mfma_f32_32x32x16_bf16 v[0:15], v[228:231], v[144:147], v[0:15]
	ds_read_b128 v[228:231], v186 offset:36864
	s_add_u32 s48, s26, s2
	s_waitcnt lgkmcnt(5)
	v_mfma_f32_32x32x16_bf16 v[48:63], v[208:211], v[148:151], v[48:63]
	ds_read_b128 v[208:211], v186 offset:40960
	s_addc_u32 s49, s27, 0
	s_waitcnt lgkmcnt(5)
	v_mfma_f32_32x32x16_bf16 v[32:47], v[212:215], v[148:151], v[32:47]
	ds_read_b128 v[212:215], v186 offset:45056
	s_add_u32 s50, s48, 0x80
	s_waitcnt lgkmcnt(5)
	v_mfma_f32_32x32x16_bf16 v[16:31], v[216:219], v[148:151], v[16:31]
	ds_read_b128 v[216:219], v189 offset:32768
	s_addc_u32 s51, s49, 0
	s_waitcnt lgkmcnt(5)
	v_mfma_f32_32x32x16_bf16 v[0:15], v[220:223], v[148:151], v[0:15]
	ds_read_b128 v[220:223], v189 offset:36864
	s_add_i32 s2, s42, 4
	s_waitcnt lgkmcnt(5)
	v_mfma_f32_32x32x16_bf16 v[48:63], v[224:227], v[152:155], v[48:63]
	ds_read_b128 v[224:227], v189 offset:40960
	s_and_b32 s2, s2, 31
	s_waitcnt lgkmcnt(5)
	v_mfma_f32_32x32x16_bf16 v[32:47], v[228:231], v[152:155], v[32:47]
	ds_read_b128 v[228:231], v189 offset:45056
	s_lshl_b32 s2, s2, 7
	s_waitcnt lgkmcnt(5)
	v_mfma_f32_32x32x16_bf16 v[16:31], v[208:211], v[152:155], v[16:31]
	ds_read_b128 v[208:211], v182 offset:0
	s_add_u32 s52, s10, s2
	s_waitcnt lgkmcnt(5)
	v_mfma_f32_32x32x16_bf16 v[0:15], v[212:215], v[152:155], v[0:15]
	ds_read_b128 v[212:215], v182 offset:4096
	s_addc_u32 s53, s11, 0
	s_waitcnt lgkmcnt(5)
	v_mfma_f32_32x32x16_bf16 v[48:63], v[216:219], v[156:159], v[48:63]
	ds_read_b128 v[216:219], v183 offset:0
	s_add_u32 s54, s52, 0x204000
	s_waitcnt lgkmcnt(5)
	v_mfma_f32_32x32x16_bf16 v[32:47], v[220:223], v[156:159], v[32:47]
	ds_read_b128 v[220:223], v183 offset:4096
	s_addc_u32 s55, s53, 0
	s_waitcnt lgkmcnt(5)
	v_mfma_f32_32x32x16_bf16 v[16:31], v[224:227], v[156:159], v[16:31]
	ds_read_b128 v[224:227], v184 offset:0
	s_waitcnt lgkmcnt(5)
	v_mfma_f32_32x32x16_bf16 v[0:15], v[228:231], v[156:159], v[0:15]
	ds_read_b128 v[228:231], v184 offset:4096
	s_waitcnt lgkmcnt(5)
	v_mfma_f32_32x32x16_bf16 v[64:79], v[208:211], v[128:131], 0
	ds_read_b128 v[208:211], v185 offset:0
	s_waitcnt lgkmcnt(5)
	v_mfma_f32_32x32x16_bf16 v[80:95], v[212:215], v[128:131], 0
	ds_read_b128 v[212:215], v185 offset:4096
	s_waitcnt lgkmcnt(5)
	v_mfma_f32_32x32x16_bf16 v[64:79], v[216:219], v[132:135], v[64:79]
	s_waitcnt lgkmcnt(4)
	v_mfma_f32_32x32x16_bf16 v[80:95], v[220:223], v[132:135], v[80:95]
	s_waitcnt lgkmcnt(3)
	v_mfma_f32_32x32x16_bf16 v[64:79], v[224:227], v[136:139], v[64:79]
	s_waitcnt lgkmcnt(2)
	v_mfma_f32_32x32x16_bf16 v[80:95], v[228:231], v[136:139], v[80:95]
	s_waitcnt lgkmcnt(1)
	v_mfma_f32_32x32x16_bf16 v[64:79], v[208:211], v[140:143], v[64:79]
	s_waitcnt lgkmcnt(0)
	v_mfma_f32_32x32x16_bf16 v[80:95], v[212:215], v[140:143], v[80:95]
	ds_read_b128 v[216:219], v187 offset:49152
	ds_read_b128 v[220:223], v187 offset:53248
	ds_read_b128 v[224:227], v187 offset:57344
	ds_read_b128 v[228:231], v187 offset:61440
	ds_read_b128 v[208:211], v188 offset:49152
	ds_read_b128 v[212:215], v188 offset:53248
	v_exp_f32_e32 v171, v96
	v_exp_f32_e32 v173, v97
	v_exp_f32_e32 v179, v98
	s_add_i32 m0, s5, 49152
	v_exp_f32_e32 v180, v99
	v_exp_f32_e32 v232, v100
	v_exp_f32_e32 v233, v101
	global_load_lds_dwordx4 v170, s[48:49]
	v_exp_f32_e32 v234, v102
	v_exp_f32_e32 v235, v103
	v_add_f32_e32 v190, v171, v173
	s_add_i32 m0, s5, 57344
	v_add_f32_e32 v191, v179, v180
	v_add_f32_e32 v190, v190, v232
	v_add_f32_e32 v191, v191, v233
	global_load_lds_dwordx4 v170, s[50:51]
	v_add_f32_e32 v190, v190, v234
	v_add_f32_e32 v191, v191, v235
	v_cvt_pk_bf16_f32 v144, v171, v173
	s_add_i32 m0, s5, 81920
	v_cvt_pk_bf16_f32 v145, v179, v180
	v_cvt_pk_bf16_f32 v146, v232, v233
	v_cvt_pk_bf16_f32 v147, v234, v235
	global_load_lds_dwordx4 v172, s[52:53]
	v_exp_f32_e32 v171, v104
	v_exp_f32_e32 v173, v105
	v_exp_f32_e32 v179, v106
	s_add_i32 m0, s5, 90112
	v_exp_f32_e32 v180, v107
	v_exp_f32_e32 v232, v108
	v_exp_f32_e32 v233, v109
	global_load_lds_dwordx4 v172, s[54:55]
	v_exp_f32_e32 v234, v110
	v_exp_f32_e32 v235, v111
	v_add_f32_e32 v190, v190, v171
	v_add_f32_e32 v191, v191, v173
	v_add_f32_e32 v190, v190, v179
	v_add_f32_e32 v191, v191, v180
	v_add_f32_e32 v190, v190, v232
	v_add_f32_e32 v191, v191, v233
	v_add_f32_e32 v190, v190, v234
	v_add_f32_e32 v191, v191, v235
	v_cvt_pk_bf16_f32 v148, v171, v173
	v_cvt_pk_bf16_f32 v149, v179, v180
	v_cvt_pk_bf16_f32 v150, v232, v233
	v_cvt_pk_bf16_f32 v151, v234, v235
	v_exp_f32_e32 v171, v112
	v_exp_f32_e32 v173, v113
	v_exp_f32_e32 v179, v114
	v_exp_f32_e32 v180, v115
	v_exp_f32_e32 v232, v116
	v_exp_f32_e32 v233, v117
	v_exp_f32_e32 v234, v118
	v_exp_f32_e32 v235, v119
	v_add_f32_e32 v190, v190, v171
	v_add_f32_e32 v191, v191, v173
	v_add_f32_e32 v190, v190, v179
	v_add_f32_e32 v191, v191, v180
	v_add_f32_e32 v190, v190, v232
	v_add_f32_e32 v191, v191, v233
	v_add_f32_e32 v190, v190, v234
	v_add_f32_e32 v191, v191, v235
	v_cvt_pk_bf16_f32 v152, v171, v173
	v_cvt_pk_bf16_f32 v153, v179, v180
	v_cvt_pk_bf16_f32 v154, v232, v233
	v_cvt_pk_bf16_f32 v155, v234, v235
	v_exp_f32_e32 v171, v120
	v_exp_f32_e32 v173, v121
	v_exp_f32_e32 v179, v122
	v_exp_f32_e32 v180, v123
	v_exp_f32_e32 v232, v124
	v_exp_f32_e32 v233, v125
	v_exp_f32_e32 v234, v126
	v_exp_f32_e32 v235, v127
	v_add_f32_e32 v190, v190, v171
	v_add_f32_e32 v191, v191, v173
	v_add_f32_e32 v190, v190, v179
	v_add_f32_e32 v191, v191, v180
	v_add_f32_e32 v190, v190, v232
	v_add_f32_e32 v191, v191, v233
	v_add_f32_e32 v190, v190, v234
	v_add_f32_e32 v191, v191, v235
	v_add_f32_e32 v190, v190, v191
	v_cmp_ngt_f32_e32 vcc, 0x71800000, v190
	v_cvt_pk_bf16_f32 v156, v171, v173
	v_cvt_pk_bf16_f32 v157, v179, v180
	v_cvt_pk_bf16_f32 v158, v232, v233
	v_cvt_pk_bf16_f32 v159, v234, v235
	s_nop 0
	s_cbranch_vccnz .Lattn_redo_L2_A
	v_add_f32_e32 v167, v167, v190
	s_waitcnt vmcnt(4)
	s_barrier
.Lattn_tb9_A:
	s_waitcnt lgkmcnt(5)
	v_mfma_f32_32x32x16_bf16 v[48:63], v[216:219], v[144:147], v[48:63]
	ds_read_b128 v[216:219], v188 offset:57344
	s_add_i32 s2, s42, 7
	s_waitcnt lgkmcnt(5)
	v_mfma_f32_32x32x16_bf16 v[32:47], v[220:223], v[144:147], v[32:47]
	ds_read_b128 v[220:223], v188 offset:61440
	s_and_b32 s2, s2, 31
	s_waitcnt lgkmcnt(5)
	v_mfma_f32_32x32x16_bf16 v[16:31], v[224:227], v[144:147], v[16:31]
	ds_read_b128 v[224:227], v186 offset:49152
	s_mul_i32 s2, s2, 0x44000
	s_waitcnt lgkmcnt(5)
	v_mfma_f32_32x32x16_bf16 v[0:15], v[228:231], v[144:147], v[0:15]
	ds_read_b128 v[228:231], v186 offset:53248
	s_add_u32 s48, s26, s2
	s_waitcnt lgkmcnt(5)
	v_mfma_f32_32x32x16_bf16 v[48:63], v[208:211], v[148:151], v[48:63]
	ds_read_b128 v[208:211], v186 offset:57344
	s_addc_u32 s49, s27, 0
	s_waitcnt lgkmcnt(5)
	v_mfma_f32_32x32x16_bf16 v[32:47], v[212:215], v[148:151], v[32:47]
	ds_read_b128 v[212:215], v186 offset:61440
	s_add_u32 s50, s48, 0x80
	s_waitcnt lgkmcnt(5)
	v_mfma_f32_32x32x16_bf16 v[16:31], v[216:219], v[148:151], v[16:31]
	ds_read_b128 v[216:219], v189 offset:49152
	s_addc_u32 s51, s49, 0
	s_waitcnt lgkmcnt(5)
	v_mfma_f32_32x32x16_bf16 v[0:15], v[220:223], v[148:151], v[0:15]
	ds_read_b128 v[220:223], v189 offset:53248
	s_add_i32 s2, s42, 5
	s_waitcnt lgkmcnt(5)
	v_mfma_f32_32x32x16_bf16 v[48:63], v[224:227], v[152:155], v[48:63]
	ds_read_b128 v[224:227], v189 offset:57344
	s_and_b32 s2, s2, 31
	s_waitcnt lgkmcnt(5)
	v_mfma_f32_32x32x16_bf16 v[32:47], v[228:231], v[152:155], v[32:47]
	ds_read_b128 v[228:231], v189 offset:61440
	s_lshl_b32 s2, s2, 7
	s_waitcnt lgkmcnt(5)
	v_mfma_f32_32x32x16_bf16 v[16:31], v[208:211], v[152:155], v[16:31]
	ds_read_b128 v[208:211], v182 offset:16384
	s_add_u32 s52, s10, s2
	s_waitcnt lgkmcnt(5)
	v_mfma_f32_32x32x16_bf16 v[0:15], v[212:215], v[152:155], v[0:15]
	ds_read_b128 v[212:215], v182 offset:20480
	s_addc_u32 s53, s11, 0
	s_waitcnt lgkmcnt(5)
	v_mfma_f32_32x32x16_bf16 v[48:63], v[216:219], v[156:159], v[48:63]
	ds_read_b128 v[216:219], v183 offset:16384
	s_add_u32 s54, s52, 0x204000
	s_waitcnt lgkmcnt(5)
	v_mfma_f32_32x32x16_bf16 v[32:47], v[220:223], v[156:159], v[32:47]
	ds_read_b128 v[220:223], v183 offset:20480
	s_addc_u32 s55, s53, 0
	s_waitcnt lgkmcnt(5)
	v_mfma_f32_32x32x16_bf16 v[16:31], v[224:227], v[156:159], v[16:31]
	ds_read_b128 v[224:227], v184 offset:16384
	s_waitcnt lgkmcnt(5)
	v_mfma_f32_32x32x16_bf16 v[0:15], v[228:231], v[156:159], v[0:15]
	ds_read_b128 v[228:231], v184 offset:20480
	s_waitcnt lgkmcnt(5)
	v_mfma_f32_32x32x16_bf16 v[96:111], v[208:211], v[128:131], 0
	ds_read_b128 v[208:211], v185 offset:16384
	s_waitcnt lgkmcnt(5)
	v_mfma_f32_32x32x16_bf16 v[112:127], v[212:215], v[128:131], 0
	ds_read_b128 v[212:215], v185 offset:20480
	s_waitcnt lgkmcnt(5)
	v_mfma_f32_32x32x16_bf16 v[96:111], v[216:219], v[132:135], v[96:111]
	s_waitcnt lgkmcnt(4)
	v_mfma_f32_32x32x16_bf16 v[112:127], v[220:223], v[132:135], v[112:127]
	s_waitcnt lgkmcnt(3)
	v_mfma_f32_32x32x16_bf16 v[96:111], v[224:227], v[136:139], v[96:111]
	s_waitcnt lgkmcnt(2)
	v_mfma_f32_32x32x16_bf16 v[112:127], v[228:231], v[136:139], v[112:127]
	s_waitcnt lgkmcnt(1)
	v_mfma_f32_32x32x16_bf16 v[96:111], v[208:211], v[140:143], v[96:111]
	s_waitcnt lgkmcnt(0)
	v_mfma_f32_32x32x16_bf16 v[112:127], v[212:215], v[140:143], v[112:127]
	ds_read_b128 v[216:219], v187 offset:0
	ds_read_b128 v[220:223], v187 offset:4096
	ds_read_b128 v[224:227], v187 offset:8192
	ds_read_b128 v[228:231], v187 offset:12288
	ds_read_b128 v[208:211], v188 offset:0
	ds_read_b128 v[212:215], v188 offset:4096
	v_exp_f32_e32 v171, v64
	v_exp_f32_e32 v173, v65
	v_exp_f32_e32 v179, v66
	s_add_i32 m0, s5, 0
	v_exp_f32_e32 v180, v67
	v_exp_f32_e32 v232, v68
	v_exp_f32_e32 v233, v69
	global_load_lds_dwordx4 v170, s[48:49]
	v_exp_f32_e32 v234, v70
	v_exp_f32_e32 v235, v71
	v_add_f32_e32 v190, v171, v173
	s_add_i32 m0, s5, 8192
	v_add_f32_e32 v191, v179, v180
	v_add_f32_e32 v190, v190, v232
	v_add_f32_e32 v191, v191, v233
	global_load_lds_dwordx4 v170, s[50:51]
	v_add_f32_e32 v190, v190, v234
	v_add_f32_e32 v191, v191, v235
	v_cvt_pk_bf16_f32 v144, v171, v173
	s_add_i32 m0, s5, 98304
	v_cvt_pk_bf16_f32 v145, v179, v180
	v_cvt_pk_bf16_f32 v146, v232, v233
	v_cvt_pk_bf16_f32 v147, v234, v235
	global_load_lds_dwordx4 v172, s[52:53]
	v_exp_f32_e32 v171, v72
	v_exp_f32_e32 v173, v73
	v_exp_f32_e32 v179, v74
	s_add_i32 m0, s5, 106496
	v_exp_f32_e32 v180, v75
	v_exp_f32_e32 v232, v76
	v_exp_f32_e32 v233, v77
	global_load_lds_dwordx4 v172, s[54:55]
	v_exp_f32_e32 v234, v78
	v_exp_f32_e32 v235, v79
	v_add_f32_e32 v190, v190, v171
	v_add_f32_e32 v191, v191, v173
	v_add_f32_e32 v190, v190, v179
	v_add_f32_e32 v191, v191, v180
	v_add_f32_e32 v190, v190, v232
	v_add_f32_e32 v191, v191, v233
	v_add_f32_e32 v190, v190, v234
	v_add_f32_e32 v191, v191, v235
	v_cvt_pk_bf16_f32 v148, v171, v173
	v_cvt_pk_bf16_f32 v149, v179, v180
	v_cvt_pk_bf16_f32 v150, v232, v233
	v_cvt_pk_bf16_f32 v151, v234, v235
	v_exp_f32_e32 v171, v80
	v_exp_f32_e32 v173, v81
	v_exp_f32_e32 v179, v82
	v_exp_f32_e32 v180, v83
	v_exp_f32_e32 v232, v84
	v_exp_f32_e32 v233, v85
	v_exp_f32_e32 v234, v86
	v_exp_f32_e32 v235, v87
	v_add_f32_e32 v190, v190, v171
	v_add_f32_e32 v191, v191, v173
	v_add_f32_e32 v190, v190, v179
	v_add_f32_e32 v191, v191, v180
	v_add_f32_e32 v190, v190, v232
	v_add_f32_e32 v191, v191, v233
	v_add_f32_e32 v190, v190, v234
	v_add_f32_e32 v191, v191, v235
	v_cvt_pk_bf16_f32 v152, v171, v173
	v_cvt_pk_bf16_f32 v153, v179, v180
	v_cvt_pk_bf16_f32 v154, v232, v233
	v_cvt_pk_bf16_f32 v155, v234, v235
	v_exp_f32_e32 v171, v88
	v_exp_f32_e32 v173, v89
	v_exp_f32_e32 v179, v90
	v_exp_f32_e32 v180, v91
	v_exp_f32_e32 v232, v92
	v_exp_f32_e32 v233, v93
	v_exp_f32_e32 v234, v94
	v_exp_f32_e32 v235, v95
	v_add_f32_e32 v190, v190, v171
	v_add_f32_e32 v191, v191, v173
	v_add_f32_e32 v190, v190, v179
	v_add_f32_e32 v191, v191, v180
	v_add_f32_e32 v190, v190, v232
	v_add_f32_e32 v191, v191, v233
	v_add_f32_e32 v190, v190, v234
	v_add_f32_e32 v191, v191, v235
	v_add_f32_e32 v190, v190, v191
	v_cmp_ngt_f32_e32 vcc, 0x71800000, v190
	v_cvt_pk_bf16_f32 v156, v171, v173
	v_cvt_pk_bf16_f32 v157, v179, v180
	v_cvt_pk_bf16_f32 v158, v232, v233
	v_cvt_pk_bf16_f32 v159, v234, v235
	s_nop 0
	s_cbranch_vccnz .Lattn_redo_L3_A
	v_add_f32_e32 v167, v167, v190
	s_add_i32 s42, s42, 4
	s_add_i32 s47, s47, -1
	s_cmp_lg_u32 s47, 0
	s_cbranch_scc1 .Lattn_loop_f_A
	s_waitcnt vmcnt(4)
	s_barrier
.Lattn_tb11_A:
	s_waitcnt lgkmcnt(5)
	v_mfma_f32_32x32x16_bf16 v[48:63], v[216:219], v[144:147], v[48:63]
	ds_read_b128 v[216:219], v188 offset:8192
	s_add_i32 s2, s42, 2
	s_waitcnt lgkmcnt(5)
	v_mfma_f32_32x32x16_bf16 v[32:47], v[220:223], v[144:147], v[32:47]
	ds_read_b128 v[220:223], v188 offset:12288
	s_and_b32 s2, s2, 31
	s_waitcnt lgkmcnt(5)
	v_mfma_f32_32x32x16_bf16 v[16:31], v[224:227], v[144:147], v[16:31]
	ds_read_b128 v[224:227], v186 offset:0
	s_lshl_b32 s2, s2, 7
	s_waitcnt lgkmcnt(5)
	v_mfma_f32_32x32x16_bf16 v[0:15], v[228:231], v[144:147], v[0:15]
	ds_read_b128 v[228:231], v186 offset:4096
	s_add_u32 s52, s10, s2
	s_waitcnt lgkmcnt(5)
	v_mfma_f32_32x32x16_bf16 v[48:63], v[208:211], v[148:151], v[48:63]
	ds_read_b128 v[208:211], v186 offset:8192
	s_addc_u32 s53, s11, 0
	s_waitcnt lgkmcnt(5)
	v_mfma_f32_32x32x16_bf16 v[32:47], v[212:215], v[148:151], v[32:47]
	ds_read_b128 v[212:215], v186 offset:12288
	s_add_u32 s54, s52, 0x204000
	s_waitcnt lgkmcnt(5)
	v_mfma_f32_32x32x16_bf16 v[16:31], v[216:219], v[148:151], v[16:31]
	ds_read_b128 v[216:219], v189 offset:0
	s_addc_u32 s55, s53, 0
	s_waitcnt lgkmcnt(5)
	v_mfma_f32_32x32x16_bf16 v[0:15], v[220:223], v[148:151], v[0:15]
	ds_read_b128 v[220:223], v189 offset:4096
	s_waitcnt lgkmcnt(5)
	v_mfma_f32_32x32x16_bf16 v[48:63], v[224:227], v[152:155], v[48:63]
	ds_read_b128 v[224:227], v189 offset:8192
	s_waitcnt lgkmcnt(5)
	v_mfma_f32_32x32x16_bf16 v[32:47], v[228:231], v[152:155], v[32:47]
	ds_read_b128 v[228:231], v189 offset:12288
	s_waitcnt lgkmcnt(5)
	v_mfma_f32_32x32x16_bf16 v[16:31], v[208:211], v[152:155], v[16:31]
	ds_read_b128 v[208:211], v182 offset:32768
	s_waitcnt lgkmcnt(5)
	v_mfma_f32_32x32x16_bf16 v[0:15], v[212:215], v[152:155], v[0:15]
	ds_read_b128 v[212:215], v182 offset:36864
	s_waitcnt lgkmcnt(5)
	v_mfma_f32_32x32x16_bf16 v[48:63], v[216:219], v[156:159], v[48:63]
	ds_read_b128 v[216:219], v183 offset:32768
	s_waitcnt lgkmcnt(5)
	v_mfma_f32_32x32x16_bf16 v[32:47], v[220:223], v[156:159], v[32:47]
	ds_read_b128 v[220:223], v183 offset:36864
	s_waitcnt lgkmcnt(5)
	v_mfma_f32_32x32x16_bf16 v[16:31], v[224:227], v[156:159], v[16:31]
	ds_read_b128 v[224:227], v184 offset:32768
	s_waitcnt lgkmcnt(5)
	v_mfma_f32_32x32x16_bf16 v[0:15], v[228:231], v[156:159], v[0:15]
	ds_read_b128 v[228:231], v184 offset:36864
	s_waitcnt lgkmcnt(5)
	v_mfma_f32_32x32x16_bf16 v[64:79], v[208:211], v[128:131], 0
	ds_read_b128 v[208:211], v185 offset:32768
	s_waitcnt lgkmcnt(5)
	v_mfma_f32_32x32x16_bf16 v[80:95], v[212:215], v[128:131], 0
	ds_read_b128 v[212:215], v185 offset:36864
	s_waitcnt lgkmcnt(5)
	v_mfma_f32_32x32x16_bf16 v[64:79], v[216:219], v[132:135], v[64:79]
	s_waitcnt lgkmcnt(4)
	v_mfma_f32_32x32x16_bf16 v[80:95], v[220:223], v[132:135], v[80:95]
	s_waitcnt lgkmcnt(3)
	v_mfma_f32_32x32x16_bf16 v[64:79], v[224:227], v[136:139], v[64:79]
	s_waitcnt lgkmcnt(2)
	v_mfma_f32_32x32x16_bf16 v[80:95], v[228:231], v[136:139], v[80:95]
	s_waitcnt lgkmcnt(1)
	v_mfma_f32_32x32x16_bf16 v[64:79], v[208:211], v[140:143], v[64:79]
	s_waitcnt lgkmcnt(0)
	v_mfma_f32_32x32x16_bf16 v[80:95], v[212:215], v[140:143], v[80:95]
	ds_read_b128 v[216:219], v187 offset:16384
	ds_read_b128 v[220:223], v187 offset:20480
	ds_read_b128 v[224:227], v187 offset:24576
	ds_read_b128 v[228:231], v187 offset:28672
	ds_read_b128 v[208:211], v188 offset:16384
	ds_read_b128 v[212:215], v188 offset:20480
	v_exp_f32_e32 v171, v96
	v_exp_f32_e32 v173, v97
	v_exp_f32_e32 v179, v98
	s_add_i32 m0, s5, 114688
	v_exp_f32_e32 v180, v99
	v_exp_f32_e32 v232, v100
	v_exp_f32_e32 v233, v101
	global_load_lds_dwordx4 v172, s[52:53]
	v_exp_f32_e32 v234, v102
	v_exp_f32_e32 v235, v103
	v_add_f32_e32 v190, v171, v173
	s_add_i32 m0, s5, 122880
	v_add_f32_e32 v191, v179, v180
	v_add_f32_e32 v190, v190, v232
	v_add_f32_e32 v191, v191, v233
	global_load_lds_dwordx4 v172, s[54:55]
	v_add_f32_e32 v190, v190, v234
	v_add_f32_e32 v191, v191, v235
	v_cvt_pk_bf16_f32 v144, v171, v173
	v_cvt_pk_bf16_f32 v145, v179, v180
	v_cvt_pk_bf16_f32 v146, v232, v233
	v_cvt_pk_bf16_f32 v147, v234, v235
	v_exp_f32_e32 v171, v104
	v_exp_f32_e32 v173, v105
	v_exp_f32_e32 v179, v106
	v_exp_f32_e32 v180, v107
	v_exp_f32_e32 v232, v108
	v_exp_f32_e32 v233, v109
	v_exp_f32_e32 v234, v110
	v_exp_f32_e32 v235, v111
	v_add_f32_e32 v190, v190, v171
	v_add_f32_e32 v191, v191, v173
	v_add_f32_e32 v190, v190, v179
	v_add_f32_e32 v191, v191, v180
	v_add_f32_e32 v190, v190, v232
	v_add_f32_e32 v191, v191, v233
	v_add_f32_e32 v190, v190, v234
	v_add_f32_e32 v191, v191, v235
	v_cvt_pk_bf16_f32 v148, v171, v173
	v_cvt_pk_bf16_f32 v149, v179, v180
	v_cvt_pk_bf16_f32 v150, v232, v233
	v_cvt_pk_bf16_f32 v151, v234, v235
	v_exp_f32_e32 v171, v112
	v_exp_f32_e32 v173, v113
	v_exp_f32_e32 v179, v114
	v_exp_f32_e32 v180, v115
	v_exp_f32_e32 v232, v116
	v_exp_f32_e32 v233, v117
	v_exp_f32_e32 v234, v118
	v_exp_f32_e32 v235, v119
	v_add_f32_e32 v190, v190, v171
	v_add_f32_e32 v191, v191, v173
	v_add_f32_e32 v190, v190, v179
	v_add_f32_e32 v191, v191, v180
	v_add_f32_e32 v190, v190, v232
	v_add_f32_e32 v191, v191, v233
	v_add_f32_e32 v190, v190, v234
	v_add_f32_e32 v191, v191, v235
	v_cvt_pk_bf16_f32 v152, v171, v173
	v_cvt_pk_bf16_f32 v153, v179, v180
	v_cvt_pk_bf16_f32 v154, v232, v233
	v_cvt_pk_bf16_f32 v155, v234, v235
	v_exp_f32_e32 v171, v120
	v_exp_f32_e32 v173, v121
	v_exp_f32_e32 v179, v122
	v_exp_f32_e32 v180, v123
	v_exp_f32_e32 v232, v124
	v_exp_f32_e32 v233, v125
	v_exp_f32_e32 v234, v126
	v_exp_f32_e32 v235, v127
	v_add_f32_e32 v190, v190, v171
	v_add_f32_e32 v191, v191, v173
	v_add_f32_e32 v190, v190, v179
	v_add_f32_e32 v191, v191, v180
	v_add_f32_e32 v190, v190, v232
	v_add_f32_e32 v191, v191, v233
	v_add_f32_e32 v190, v190, v234
	v_add_f32_e32 v191, v191, v235
	v_add_f32_e32 v190, v190, v191
	v_cmp_ngt_f32_e32 vcc, 0x71800000, v190
	v_cvt_pk_bf16_f32 v156, v171, v173
	v_cvt_pk_bf16_f32 v157, v179, v180
	v_cvt_pk_bf16_f32 v158, v232, v233
	v_cvt_pk_bf16_f32 v159, v234, v235
	s_nop 0
	s_cbranch_vccnz .Lattn_redo_T29_A
	v_add_f32_e32 v167, v167, v190
	s_waitcnt vmcnt(2)
	s_barrier
.Lattn_tb13_A:
	s_waitcnt lgkmcnt(5)
	v_mfma_f32_32x32x16_bf16 v[48:63], v[216:219], v[144:147], v[48:63]
	ds_read_b128 v[216:219], v188 offset:24576
	s_waitcnt lgkmcnt(5)
	v_mfma_f32_32x32x16_bf16 v[32:47], v[220:223], v[144:147], v[32:47]
	ds_read_b128 v[220:223], v188 offset:28672
	s_waitcnt lgkmcnt(5)
	v_mfma_f32_32x32x16_bf16 v[16:31], v[224:227], v[144:147], v[16:31]
	ds_read_b128 v[224:227], v186 offset:16384
	s_waitcnt lgkmcnt(5)
	v_mfma_f32_32x32x16_bf16 v[0:15], v[228:231], v[144:147], v[0:15]
	ds_read_b128 v[228:231], v186 offset:20480
	s_waitcnt lgkmcnt(5)
	v_mfma_f32_32x32x16_bf16 v[48:63], v[208:211], v[148:151], v[48:63]
	ds_read_b128 v[208:211], v186 offset:24576
	s_waitcnt lgkmcnt(5)
	v_mfma_f32_32x32x16_bf16 v[32:47], v[212:215], v[148:151], v[32:47]
	ds_read_b128 v[212:215], v186 offset:28672
	s_waitcnt lgkmcnt(5)
	v_mfma_f32_32x32x16_bf16 v[16:31], v[216:219], v[148:151], v[16:31]
	ds_read_b128 v[216:219], v189 offset:16384
	s_waitcnt lgkmcnt(5)
	v_mfma_f32_32x32x16_bf16 v[0:15], v[220:223], v[148:151], v[0:15]
	ds_read_b128 v[220:223], v189 offset:20480
	s_waitcnt lgkmcnt(5)
	v_mfma_f32_32x32x16_bf16 v[48:63], v[224:227], v[152:155], v[48:63]
	ds_read_b128 v[224:227], v189 offset:24576
	s_waitcnt lgkmcnt(5)
	v_mfma_f32_32x32x16_bf16 v[32:47], v[228:231], v[152:155], v[32:47]
	ds_read_b128 v[228:231], v189 offset:28672
	s_waitcnt lgkmcnt(5)
	v_mfma_f32_32x32x16_bf16 v[16:31], v[208:211], v[152:155], v[16:31]
	ds_read_b128 v[208:211], v182 offset:49152
	s_waitcnt lgkmcnt(5)
	v_mfma_f32_32x32x16_bf16 v[0:15], v[212:215], v[152:155], v[0:15]
	ds_read_b128 v[212:215], v182 offset:53248
	s_waitcnt lgkmcnt(5)
	v_mfma_f32_32x32x16_bf16 v[48:63], v[216:219], v[156:159], v[48:63]
	ds_read_b128 v[216:219], v183 offset:49152
	s_waitcnt lgkmcnt(5)
	v_mfma_f32_32x32x16_bf16 v[32:47], v[220:223], v[156:159], v[32:47]
	ds_read_b128 v[220:223], v183 offset:53248
	s_waitcnt lgkmcnt(5)
	v_mfma_f32_32x32x16_bf16 v[16:31], v[224:227], v[156:159], v[16:31]
	ds_read_b128 v[224:227], v184 offset:49152
	s_waitcnt lgkmcnt(5)
	v_mfma_f32_32x32x16_bf16 v[0:15], v[228:231], v[156:159], v[0:15]
	ds_read_b128 v[228:231], v184 offset:53248
	s_waitcnt lgkmcnt(5)
	v_mfma_f32_32x32x16_bf16 v[96:111], v[208:211], v[128:131], 0
	ds_read_b128 v[208:211], v185 offset:49152
	s_waitcnt lgkmcnt(5)
	v_mfma_f32_32x32x16_bf16 v[112:127], v[212:215], v[128:131], 0
	ds_read_b128 v[212:215], v185 offset:53248
	s_waitcnt lgkmcnt(5)
	v_mfma_f32_32x32x16_bf16 v[96:111], v[216:219], v[132:135], v[96:111]
	s_waitcnt lgkmcnt(4)
	v_mfma_f32_32x32x16_bf16 v[112:127], v[220:223], v[132:135], v[112:127]
	s_waitcnt lgkmcnt(3)
	v_mfma_f32_32x32x16_bf16 v[96:111], v[224:227], v[136:139], v[96:111]
	s_waitcnt lgkmcnt(2)
	v_mfma_f32_32x32x16_bf16 v[112:127], v[228:231], v[136:139], v[112:127]
	s_waitcnt lgkmcnt(1)
	v_mfma_f32_32x32x16_bf16 v[96:111], v[208:211], v[140:143], v[96:111]
	s_waitcnt lgkmcnt(0)
	v_mfma_f32_32x32x16_bf16 v[112:127], v[212:215], v[140:143], v[112:127]
	ds_read_b128 v[216:219], v187 offset:32768
	ds_read_b128 v[220:223], v187 offset:36864
	ds_read_b128 v[224:227], v187 offset:40960
	ds_read_b128 v[228:231], v187 offset:45056
	ds_read_b128 v[208:211], v188 offset:32768
	ds_read_b128 v[212:215], v188 offset:36864
	v_exp_f32_e32 v171, v64
	v_exp_f32_e32 v173, v65
	v_exp_f32_e32 v179, v66
	v_readlane_b32 s2, v253, 52
	s_add_i32 s36, s46, 1
	s_mul_i32 s36, s36, s56
	s_add_i32 s36, s36, s0
	s_cmp_lg_u32 s2, 0
	s_cselect_b32 s2, 1, 0
	s_cmpk_lt_i32 s36, 0x400
	s_cselect_b32 s36, 1, 0
	s_and_b32 s35, s2, s36
	v_exp_f32_e32 v180, v67
	v_exp_f32_e32 v232, v68
	v_exp_f32_e32 v233, v69
	s_cmp_lg_u32 s35, 0
	s_cbranch_scc0 .Lattn_pfka_f_A
	s_add_i32 s2, s31, 0
	s_and_b32 s2, s2, 31
	s_mul_i32 s2, s2, 0x44000
	s_add_i32 m0, s5, 0
	s_add_u32 s40, s26, s2
	s_addc_u32 s41, s27, 0
	s_add_u32 s40, s40, 0x1100000
	s_addc_u32 s41, s41, 0
	global_load_lds_dwordx4 v170, s[40:41]
	s_add_i32 m0, s5, 8192
	s_add_u32 s40, s40, 0x80
	s_addc_u32 s41, s41, 0
	global_load_lds_dwordx4 v170, s[40:41]

.Lattn_pfvt_f_A:
	v_add_f32_e32 v190, v190, v234
	v_add_f32_e32 v191, v191, v235
	v_cvt_pk_bf16_f32 v144, v171, v173
	v_cvt_pk_bf16_f32 v145, v179, v180
	v_cvt_pk_bf16_f32 v146, v232, v233
	v_cvt_pk_bf16_f32 v147, v234, v235
	v_exp_f32_e32 v171, v72
	v_exp_f32_e32 v173, v73
	v_exp_f32_e32 v179, v74
	v_exp_f32_e32 v180, v75
	v_exp_f32_e32 v232, v76
	v_exp_f32_e32 v233, v77
	v_exp_f32_e32 v234, v78
	v_exp_f32_e32 v235, v79
	v_add_f32_e32 v190, v190, v171
	v_add_f32_e32 v191, v191, v173
	v_add_f32_e32 v190, v190, v179
	v_add_f32_e32 v191, v191, v180
	v_add_f32_e32 v190, v190, v232
	v_add_f32_e32 v191, v191, v233
	v_add_f32_e32 v190, v190, v234
	v_add_f32_e32 v191, v191, v235
	v_cvt_pk_bf16_f32 v148, v171, v173
	v_cvt_pk_bf16_f32 v149, v179, v180
	v_cvt_pk_bf16_f32 v150, v232, v233
	v_cvt_pk_bf16_f32 v151, v234, v235
	v_exp_f32_e32 v171, v80
	v_exp_f32_e32 v173, v81
	v_exp_f32_e32 v179, v82
	v_exp_f32_e32 v180, v83
	v_exp_f32_e32 v232, v84
	v_exp_f32_e32 v233, v85
	v_exp_f32_e32 v234, v86
	v_exp_f32_e32 v235, v87
	v_add_f32_e32 v190, v190, v171
	v_add_f32_e32 v191, v191, v173
	v_add_f32_e32 v190, v190, v179
	v_add_f32_e32 v191, v191, v180
	v_add_f32_e32 v190, v190, v232
	v_add_f32_e32 v191, v191, v233
	v_add_f32_e32 v190, v190, v234
	v_add_f32_e32 v191, v191, v235
	v_cvt_pk_bf16_f32 v152, v171, v173
	v_cvt_pk_bf16_f32 v153, v179, v180
	v_cvt_pk_bf16_f32 v154, v232, v233
	v_cvt_pk_bf16_f32 v155, v234, v235
	v_exp_f32_e32 v171, v88
	v_exp_f32_e32 v173, v89
	v_exp_f32_e32 v179, v90
	v_exp_f32_e32 v180, v91
	v_exp_f32_e32 v232, v92
	v_exp_f32_e32 v233, v93
	v_exp_f32_e32 v234, v94
	v_exp_f32_e32 v235, v95
	v_add_f32_e32 v190, v190, v171
	v_add_f32_e32 v191, v191, v173
	v_add_f32_e32 v190, v190, v179
	v_add_f32_e32 v191, v191, v180
	v_add_f32_e32 v190, v190, v232
	v_add_f32_e32 v191, v191, v233
	v_add_f32_e32 v190, v190, v234
	v_add_f32_e32 v191, v191, v235
	v_add_f32_e32 v190, v190, v191
	v_cmp_ngt_f32_e32 vcc, 0x71800000, v190
	v_cvt_pk_bf16_f32 v156, v171, v173
	v_cvt_pk_bf16_f32 v157, v179, v180
	v_cvt_pk_bf16_f32 v158, v232, v233
	v_cvt_pk_bf16_f32 v159, v234, v235
	s_nop 0
	s_cbranch_vccnz .Lattn_redo_T30_A
	v_add_f32_e32 v167, v167, v190
	s_cmp_lg_u32 s35, 0
	s_cbranch_scc1 .Lattn_tb15_w6_A
	s_waitcnt vmcnt(0)
	s_branch .Lattn_tb15_wd_A

.Lattn_tb15_A:
	s_waitcnt lgkmcnt(5)
	v_mfma_f32_32x32x16_bf16 v[48:63], v[216:219], v[144:147], v[48:63]
	ds_read_b128 v[216:219], v188 offset:40960
	s_waitcnt lgkmcnt(5)
	v_mfma_f32_32x32x16_bf16 v[32:47], v[220:223], v[144:147], v[32:47]
	ds_read_b128 v[220:223], v188 offset:45056
	s_waitcnt lgkmcnt(5)
	v_mfma_f32_32x32x16_bf16 v[16:31], v[224:227], v[144:147], v[16:31]
	ds_read_b128 v[224:227], v186 offset:32768
	s_waitcnt lgkmcnt(5)
	v_mfma_f32_32x32x16_bf16 v[0:15], v[228:231], v[144:147], v[0:15]
	ds_read_b128 v[228:231], v186 offset:36864
	s_waitcnt lgkmcnt(5)
	v_mfma_f32_32x32x16_bf16 v[48:63], v[208:211], v[148:151], v[48:63]
	ds_read_b128 v[208:211], v186 offset:40960
	s_waitcnt lgkmcnt(5)
	v_mfma_f32_32x32x16_bf16 v[32:47], v[212:215], v[148:151], v[32:47]
	ds_read_b128 v[212:215], v186 offset:45056
	s_waitcnt lgkmcnt(5)
	v_mfma_f32_32x32x16_bf16 v[16:31], v[216:219], v[148:151], v[16:31]
	ds_read_b128 v[216:219], v189 offset:32768
	s_waitcnt lgkmcnt(5)
	v_mfma_f32_32x32x16_bf16 v[0:15], v[220:223], v[148:151], v[0:15]
	ds_read_b128 v[220:223], v189 offset:36864
	s_waitcnt lgkmcnt(5)
	v_mfma_f32_32x32x16_bf16 v[48:63], v[224:227], v[152:155], v[48:63]
	ds_read_b128 v[224:227], v189 offset:40960
	s_waitcnt lgkmcnt(5)
	v_mfma_f32_32x32x16_bf16 v[32:47], v[228:231], v[152:155], v[32:47]
	ds_read_b128 v[228:231], v189 offset:45056
	s_waitcnt lgkmcnt(5)
	v_mfma_f32_32x32x16_bf16 v[16:31], v[208:211], v[152:155], v[16:31]
	s_waitcnt lgkmcnt(4)
	v_mfma_f32_32x32x16_bf16 v[0:15], v[212:215], v[152:155], v[0:15]
	s_waitcnt lgkmcnt(3)
	v_mfma_f32_32x32x16_bf16 v[48:63], v[216:219], v[156:159], v[48:63]
	s_waitcnt lgkmcnt(2)
	v_mfma_f32_32x32x16_bf16 v[32:47], v[220:223], v[156:159], v[32:47]
	s_waitcnt lgkmcnt(1)
	v_mfma_f32_32x32x16_bf16 v[16:31], v[224:227], v[156:159], v[16:31]
	s_waitcnt lgkmcnt(0)
	v_mfma_f32_32x32x16_bf16 v[0:15], v[228:231], v[156:159], v[0:15]
	ds_read_b128 v[208:211], v187 offset:49152
	ds_read_b128 v[212:215], v187 offset:53248
	ds_read_b128 v[216:219], v187 offset:57344
	ds_read_b128 v[220:223], v187 offset:61440
	ds_read_b128 v[224:227], v188 offset:49152
	ds_read_b128 v[228:231], v188 offset:53248
	v_exp_f32_e32 v171, v96
	v_exp_f32_e32 v173, v97
	v_exp_f32_e32 v179, v98
	s_cmp_lg_u32 s35, 0
	s_cbranch_scc0 .Lattn_pfq_f_A
	s_movk_i32 s2, 0x1100
	s_lshl_b32 s36, s14, 1
	v_mad_u32_u24 v72, v168, s2, v192
	s_add_i32 s36, s36, s30
	s_add_i32 s36, s36, 0x1100000
	s_nop 0
	v_add_u32_e32 v72, s36, v72
	s_nop 0
	global_load_dwordx4 v[64:67], v72, s[6:7]
	global_load_dwordx4 v[68:71], v72, s[6:7] offset:32
	global_load_dwordx4 v[136:139], v72, s[6:7] offset:64
	global_load_dwordx4 v[140:143], v72, s[6:7] offset:96

.Lattn_noresc_rT31_A:
	s_branch .Lattn_final_A
.Lattn_top_t0_A:
	s_barrier
.Lattn_tb17_A:
	s_waitcnt lgkmcnt(5)
	v_mfma_f32_32x32x16_bf16 v[96:111], v[208:211], v[128:131], 0
	ds_read_b128 v[208:211], v185 offset:16384
	s_add_i32 s2, s42, 4
	s_and_b32 s2, s2, 31
	s_waitcnt lgkmcnt(5)
	v_mfma_f32_32x32x16_bf16 v[112:127], v[212:215], v[128:131], 0
	ds_read_b128 v[212:215], v185 offset:20480
	s_mul_i32 s2, s2, 0x44000
	s_add_u32 s48, s26, s2
	s_waitcnt lgkmcnt(5)
	v_mfma_f32_32x32x16_bf16 v[96:111], v[216:219], v[132:135], v[96:111]
	s_addc_u32 s49, s27, 0
	s_add_u32 s50, s48, 0x80
	s_waitcnt lgkmcnt(4)
	v_mfma_f32_32x32x16_bf16 v[112:127], v[220:223], v[132:135], v[112:127]
	s_addc_u32 s51, s49, 0
	s_add_i32 s2, s42, 2
	s_waitcnt lgkmcnt(3)
	v_mfma_f32_32x32x16_bf16 v[96:111], v[224:227], v[136:139], v[96:111]
	s_and_b32 s2, s2, 31
	s_lshl_b32 s2, s2, 7
	s_waitcnt lgkmcnt(2)
	v_mfma_f32_32x32x16_bf16 v[112:127], v[228:231], v[136:139], v[112:127]
	s_add_u32 s52, s10, s2
	s_addc_u32 s53, s11, 0
	s_waitcnt lgkmcnt(1)
	v_mfma_f32_32x32x16_bf16 v[96:111], v[208:211], v[140:143], v[96:111]
	s_add_u32 s54, s52, 0x204000
	s_addc_u32 s55, s53, 0
	s_waitcnt lgkmcnt(0)
	v_mfma_f32_32x32x16_bf16 v[112:127], v[212:215], v[140:143], v[112:127]
	ds_read_b128 v[216:219], v187 offset:0
	ds_read_b128 v[220:223], v187 offset:4096
	ds_read_b128 v[224:227], v187 offset:8192
	ds_read_b128 v[228:231], v187 offset:12288
	ds_read_b128 v[208:211], v188 offset:0
	ds_read_b128 v[212:215], v188 offset:4096
	v_max3_f32 v254, v64, v65, v66
	s_add_i32 m0, s5, 0
	v_max3_f32 v255, v80, v81, v82
	global_load_lds_dwordx4 v170, s[48:49]
	v_max3_f32 v254, v254, v67, v68
	s_add_i32 m0, s5, 8192
	v_max3_f32 v255, v255, v83, v84
	global_load_lds_dwordx4 v170, s[50:51]
	v_max3_f32 v254, v254, v69, v70
	s_add_i32 m0, s5, 98304
	v_max3_f32 v255, v255, v85, v86
	global_load_lds_dwordx4 v172, s[52:53]
	v_max3_f32 v254, v254, v71, v72
	s_add_i32 m0, s5, 106496
	v_max3_f32 v255, v255, v87, v88
	global_load_lds_dwordx4 v172, s[54:55]
	v_max3_f32 v254, v254, v73, v74
	v_max3_f32 v255, v255, v89, v90
	v_max3_f32 v254, v254, v75, v76
	v_max3_f32 v255, v255, v91, v92
	v_max3_f32 v254, v254, v77, v78
	v_max3_f32 v255, v255, v93, v94
	v_max3_f32 v254, v254, v79, v95
	v_max_f32_e32 v254, v254, v255
	v_mov_b32_e32 v180, 0xc2800000
	v_cmp_lt_f32_e32 vcc, 0x4138aa3b, v254
	v_cmp_gt_f32_e64 s[40:41], v180, v254
	s_nop 4
	s_or_b64 vcc, vcc, s[40:41]
	s_nop 0

.Lattn_loop_s_A:
.Lattn_top_L0_A:
	s_waitcnt vmcnt(4)
	s_barrier
.Lattn_tb19_A:
	s_waitcnt lgkmcnt(5)
	v_mfma_f32_32x32x16_bf16 v[48:63], v[216:219], v[144:147], v[48:63]
	ds_read_b128 v[216:219], v188 offset:8192
	s_add_i32 s2, s42, 4
	s_waitcnt lgkmcnt(5)
	v_mfma_f32_32x32x16_bf16 v[32:47], v[220:223], v[144:147], v[32:47]
	ds_read_b128 v[220:223], v188 offset:12288
	s_and_b32 s2, s2, 31
	s_waitcnt lgkmcnt(5)
	v_mfma_f32_32x32x16_bf16 v[16:31], v[224:227], v[144:147], v[16:31]
	ds_read_b128 v[224:227], v186 offset:0
	s_mul_i32 s2, s2, 0x44000
	s_waitcnt lgkmcnt(5)
	v_mfma_f32_32x32x16_bf16 v[0:15], v[228:231], v[144:147], v[0:15]
	ds_read_b128 v[228:231], v186 offset:4096
	s_add_u32 s48, s26, s2
	s_waitcnt lgkmcnt(5)
	v_mfma_f32_32x32x16_bf16 v[48:63], v[208:211], v[148:151], v[48:63]
	ds_read_b128 v[208:211], v186 offset:8192
	s_addc_u32 s49, s27, 0
	s_waitcnt lgkmcnt(5)
	v_mfma_f32_32x32x16_bf16 v[32:47], v[212:215], v[148:151], v[32:47]
	ds_read_b128 v[212:215], v186 offset:12288
	s_add_u32 s50, s48, 0x80
	s_waitcnt lgkmcnt(5)
	v_mfma_f32_32x32x16_bf16 v[16:31], v[216:219], v[148:151], v[16:31]
	ds_read_b128 v[216:219], v189 offset:0
	s_addc_u32 s51, s49, 0
	s_waitcnt lgkmcnt(5)
	v_mfma_f32_32x32x16_bf16 v[0:15], v[220:223], v[148:151], v[0:15]
	ds_read_b128 v[220:223], v189 offset:4096
	s_add_i32 s2, s42, 2
	s_waitcnt lgkmcnt(5)
	v_mfma_f32_32x32x16_bf16 v[48:63], v[224:227], v[152:155], v[48:63]
	ds_read_b128 v[224:227], v189 offset:8192
	s_and_b32 s2, s2, 31
	s_waitcnt lgkmcnt(5)
	v_mfma_f32_32x32x16_bf16 v[32:47], v[228:231], v[152:155], v[32:47]
	ds_read_b128 v[228:231], v189 offset:12288
	s_lshl_b32 s2, s2, 7
	s_waitcnt lgkmcnt(5)
	v_mfma_f32_32x32x16_bf16 v[16:31], v[208:211], v[152:155], v[16:31]
	ds_read_b128 v[208:211], v182 offset:32768
	s_add_u32 s52, s10, s2
	s_waitcnt lgkmcnt(5)
	v_mfma_f32_32x32x16_bf16 v[0:15], v[212:215], v[152:155], v[0:15]
	ds_read_b128 v[212:215], v182 offset:36864
	s_addc_u32 s53, s11, 0
	s_waitcnt lgkmcnt(5)
	v_mfma_f32_32x32x16_bf16 v[48:63], v[216:219], v[156:159], v[48:63]
	ds_read_b128 v[216:219], v183 offset:32768
	s_add_u32 s54, s52, 0x204000
	s_waitcnt lgkmcnt(5)
	v_mfma_f32_32x32x16_bf16 v[32:47], v[220:223], v[156:159], v[32:47]
	ds_read_b128 v[220:223], v183 offset:36864
	s_addc_u32 s55, s53, 0
	s_waitcnt lgkmcnt(5)
	v_mfma_f32_32x32x16_bf16 v[16:31], v[224:227], v[156:159], v[16:31]
	ds_read_b128 v[224:227], v184 offset:32768
	s_waitcnt lgkmcnt(5)
	v_mfma_f32_32x32x16_bf16 v[0:15], v[228:231], v[156:159], v[0:15]
	ds_read_b128 v[228:231], v184 offset:36864
	s_waitcnt lgkmcnt(5)
	v_mfma_f32_32x32x16_bf16 v[64:79], v[208:211], v[128:131], 0
	ds_read_b128 v[208:211], v185 offset:32768
	s_waitcnt lgkmcnt(5)
	v_mfma_f32_32x32x16_bf16 v[80:95], v[212:215], v[128:131], 0
	ds_read_b128 v[212:215], v185 offset:36864
	s_waitcnt lgkmcnt(5)
	v_mfma_f32_32x32x16_bf16 v[64:79], v[216:219], v[132:135], v[64:79]
	s_waitcnt lgkmcnt(4)
	v_mfma_f32_32x32x16_bf16 v[80:95], v[220:223], v[132:135], v[80:95]
	s_waitcnt lgkmcnt(3)
	v_mfma_f32_32x32x16_bf16 v[64:79], v[224:227], v[136:139], v[64:79]
	s_waitcnt lgkmcnt(2)
	v_mfma_f32_32x32x16_bf16 v[80:95], v[228:231], v[136:139], v[80:95]
	s_waitcnt lgkmcnt(1)
	v_mfma_f32_32x32x16_bf16 v[64:79], v[208:211], v[140:143], v[64:79]
	s_waitcnt lgkmcnt(0)
	v_mfma_f32_32x32x16_bf16 v[80:95], v[212:215], v[140:143], v[80:95]
	ds_read_b128 v[216:219], v187 offset:16384
	ds_read_b128 v[220:223], v187 offset:20480
	ds_read_b128 v[224:227], v187 offset:24576
	ds_read_b128 v[228:231], v187 offset:28672
	ds_read_b128 v[208:211], v188 offset:16384
	ds_read_b128 v[212:215], v188 offset:20480
	v_max3_f32 v254, v96, v97, v98
	s_add_i32 m0, s5, 16384
	v_max3_f32 v255, v112, v113, v114
	global_load_lds_dwordx4 v170, s[48:49]
	v_max3_f32 v254, v254, v99, v100
	s_add_i32 m0, s5, 24576
	v_max3_f32 v255, v255, v115, v116
	global_load_lds_dwordx4 v170, s[50:51]
	v_max3_f32 v254, v254, v101, v102
	s_add_i32 m0, s5, 114688
	v_max3_f32 v255, v255, v117, v118
	global_load_lds_dwordx4 v172, s[52:53]
	v_max3_f32 v254, v254, v103, v104
	s_add_i32 m0, s5, 122880
	v_max3_f32 v255, v255, v119, v120
	global_load_lds_dwordx4 v172, s[54:55]
	v_max3_f32 v254, v254, v105, v106
	v_max3_f32 v255, v255, v121, v122
	v_max3_f32 v254, v254, v107, v108
	v_max3_f32 v255, v255, v123, v124
	v_max3_f32 v254, v254, v109, v110
	v_max3_f32 v255, v255, v125, v126
	v_max3_f32 v254, v254, v111, v127
	v_max_f32_e32 v254, v254, v255
	v_mov_b32_e32 v255, v254
	s_nop 1
	v_permlane32_swap_b32_e32 v254, v255
	v_max_f32_e32 v254, v254, v255
	v_add_f32_e32 v180, 0x4138aa3b, v175
	v_cmp_gt_f32_e32 vcc, v254, v180
	s_nop 1
	v_cndmask_b32_e32 v180, v175, v254, vcc
	v_sub_f32_e32 v255, v175, v180
	v_exp_f32_e32 v174, v255
	v_mov_b32_e32 v175, v180
	v_sub_f32_e32 v96, v96, v175
	v_sub_f32_e32 v97, v97, v175
	v_sub_f32_e32 v98, v98, v175
	v_sub_f32_e32 v99, v99, v175
	v_sub_f32_e32 v100, v100, v175
	v_sub_f32_e32 v101, v101, v175
	v_sub_f32_e32 v102, v102, v175
	v_sub_f32_e32 v103, v103, v175
	v_exp_f32_e32 v96, v96
	v_exp_f32_e32 v97, v97
	v_exp_f32_e32 v98, v98
	v_exp_f32_e32 v99, v99
	v_exp_f32_e32 v100, v100
	v_exp_f32_e32 v101, v101
	v_exp_f32_e32 v102, v102
	v_exp_f32_e32 v103, v103
	v_add_f32_e32 v190, v96, v97
	v_add_f32_e32 v191, v98, v99
	v_add_f32_e32 v190, v190, v100
	v_add_f32_e32 v191, v191, v101
	v_add_f32_e32 v190, v190, v102
	v_add_f32_e32 v191, v191, v103
	v_cvt_pk_bf16_f32 v144, v96, v97
	v_cvt_pk_bf16_f32 v145, v98, v99
	v_cvt_pk_bf16_f32 v146, v100, v101
	v_cvt_pk_bf16_f32 v147, v102, v103
	v_sub_f32_e32 v104, v104, v175
	v_sub_f32_e32 v105, v105, v175
	v_sub_f32_e32 v106, v106, v175
	v_sub_f32_e32 v107, v107, v175
	v_sub_f32_e32 v108, v108, v175
	v_sub_f32_e32 v109, v109, v175
	v_sub_f32_e32 v110, v110, v175
	v_sub_f32_e32 v111, v111, v175
	v_exp_f32_e32 v104, v104
	v_exp_f32_e32 v105, v105
	v_exp_f32_e32 v106, v106
	v_exp_f32_e32 v107, v107
	v_exp_f32_e32 v108, v108
	v_exp_f32_e32 v109, v109
	v_exp_f32_e32 v110, v110
	v_exp_f32_e32 v111, v111
	v_add_f32_e32 v190, v190, v104
	v_add_f32_e32 v191, v191, v105
	v_add_f32_e32 v190, v190, v106
	v_add_f32_e32 v191, v191, v107
	v_add_f32_e32 v190, v190, v108
	v_add_f32_e32 v191, v191, v109
	v_add_f32_e32 v190, v190, v110
	v_add_f32_e32 v191, v191, v111
	v_cvt_pk_bf16_f32 v148, v104, v105
	v_cvt_pk_bf16_f32 v149, v106, v107
	v_cvt_pk_bf16_f32 v150, v108, v109
	v_cvt_pk_bf16_f32 v151, v110, v111
	v_sub_f32_e32 v112, v112, v175
	v_sub_f32_e32 v113, v113, v175
	v_sub_f32_e32 v114, v114, v175
	v_sub_f32_e32 v115, v115, v175
	v_sub_f32_e32 v116, v116, v175
	v_sub_f32_e32 v117, v117, v175
	v_sub_f32_e32 v118, v118, v175
	v_sub_f32_e32 v119, v119, v175
	v_exp_f32_e32 v112, v112
	v_exp_f32_e32 v113, v113
	v_exp_f32_e32 v114, v114
	v_exp_f32_e32 v115, v115
	v_exp_f32_e32 v116, v116
	v_exp_f32_e32 v117, v117
	v_exp_f32_e32 v118, v118
	v_exp_f32_e32 v119, v119
	v_add_f32_e32 v190, v190, v112
	v_add_f32_e32 v191, v191, v113
	v_add_f32_e32 v190, v190, v114
	v_add_f32_e32 v191, v191, v115
	v_add_f32_e32 v190, v190, v116
	v_add_f32_e32 v191, v191, v117
	v_add_f32_e32 v190, v190, v118
	v_add_f32_e32 v191, v191, v119
	v_cvt_pk_bf16_f32 v152, v112, v113
	v_cvt_pk_bf16_f32 v153, v114, v115
	v_cvt_pk_bf16_f32 v154, v116, v117
	v_cvt_pk_bf16_f32 v155, v118, v119
	v_sub_f32_e32 v120, v120, v175
	v_sub_f32_e32 v121, v121, v175
	v_sub_f32_e32 v122, v122, v175
	v_sub_f32_e32 v123, v123, v175
	v_sub_f32_e32 v124, v124, v175
	v_sub_f32_e32 v125, v125, v175
	v_sub_f32_e32 v126, v126, v175
	v_sub_f32_e32 v127, v127, v175
	v_exp_f32_e32 v120, v120
	v_exp_f32_e32 v121, v121
	v_exp_f32_e32 v122, v122
	v_exp_f32_e32 v123, v123
	v_exp_f32_e32 v124, v124
	v_exp_f32_e32 v125, v125
	v_exp_f32_e32 v126, v126
	v_exp_f32_e32 v127, v127
	v_add_f32_e32 v190, v190, v120
	v_add_f32_e32 v191, v191, v121
	v_add_f32_e32 v190, v190, v122
	v_add_f32_e32 v191, v191, v123
	v_add_f32_e32 v190, v190, v124
	v_add_f32_e32 v191, v191, v125
	v_add_f32_e32 v190, v190, v126
	v_add_f32_e32 v191, v191, v127
	v_cvt_pk_bf16_f32 v156, v120, v121
	v_cvt_pk_bf16_f32 v157, v122, v123
	v_cvt_pk_bf16_f32 v158, v124, v125
	v_cvt_pk_bf16_f32 v159, v126, v127
	v_add_f32_e32 v190, v190, v191
	v_fma_f32 v167, v167, v174, v190
	s_cbranch_vccz .Lattn_noresc_L0_A
	s_nop 7
	s_nop 7
	v_pk_mul_f32 v[0:1], v[0:1], v[174:175] op_sel_hi:[1,0]
	v_pk_mul_f32 v[2:3], v[2:3], v[174:175] op_sel_hi:[1,0]
	v_pk_mul_f32 v[4:5], v[4:5], v[174:175] op_sel_hi:[1,0]
	v_pk_mul_f32 v[6:7], v[6:7], v[174:175] op_sel_hi:[1,0]
	v_pk_mul_f32 v[8:9], v[8:9], v[174:175] op_sel_hi:[1,0]
	v_pk_mul_f32 v[10:11], v[10:11], v[174:175] op_sel_hi:[1,0]
	v_pk_mul_f32 v[12:13], v[12:13], v[174:175] op_sel_hi:[1,0]
	v_pk_mul_f32 v[14:15], v[14:15], v[174:175] op_sel_hi:[1,0]
	v_pk_mul_f32 v[16:17], v[16:17], v[174:175] op_sel_hi:[1,0]
	v_pk_mul_f32 v[18:19], v[18:19], v[174:175] op_sel_hi:[1,0]
	v_pk_mul_f32 v[20:21], v[20:21], v[174:175] op_sel_hi:[1,0]
	v_pk_mul_f32 v[22:23], v[22:23], v[174:175] op_sel_hi:[1,0]
	v_pk_mul_f32 v[24:25], v[24:25], v[174:175] op_sel_hi:[1,0]
	v_pk_mul_f32 v[26:27], v[26:27], v[174:175] op_sel_hi:[1,0]
	v_pk_mul_f32 v[28:29], v[28:29], v[174:175] op_sel_hi:[1,0]
	v_pk_mul_f32 v[30:31], v[30:31], v[174:175] op_sel_hi:[1,0]
	v_pk_mul_f32 v[32:33], v[32:33], v[174:175] op_sel_hi:[1,0]
	v_pk_mul_f32 v[34:35], v[34:35], v[174:175] op_sel_hi:[1,0]
	v_pk_mul_f32 v[36:37], v[36:37], v[174:175] op_sel_hi:[1,0]
	v_pk_mul_f32 v[38:39], v[38:39], v[174:175] op_sel_hi:[1,0]
	v_pk_mul_f32 v[40:41], v[40:41], v[174:175] op_sel_hi:[1,0]
	v_pk_mul_f32 v[42:43], v[42:43], v[174:175] op_sel_hi:[1,0]
	v_pk_mul_f32 v[44:45], v[44:45], v[174:175] op_sel_hi:[1,0]
	v_pk_mul_f32 v[46:47], v[46:47], v[174:175] op_sel_hi:[1,0]
	v_pk_mul_f32 v[48:49], v[48:49], v[174:175] op_sel_hi:[1,0]
	v_pk_mul_f32 v[50:51], v[50:51], v[174:175] op_sel_hi:[1,0]
	v_pk_mul_f32 v[52:53], v[52:53], v[174:175] op_sel_hi:[1,0]
	v_pk_mul_f32 v[54:55], v[54:55], v[174:175] op_sel_hi:[1,0]
	v_pk_mul_f32 v[56:57], v[56:57], v[174:175] op_sel_hi:[1,0]
	v_pk_mul_f32 v[58:59], v[58:59], v[174:175] op_sel_hi:[1,0]
	v_pk_mul_f32 v[60:61], v[60:61], v[174:175] op_sel_hi:[1,0]
	v_pk_mul_f32 v[62:63], v[62:63], v[174:175] op_sel_hi:[1,0]
	s_nop 1

.Lattn_tb21_A:
	s_waitcnt lgkmcnt(5)
	v_mfma_f32_32x32x16_bf16 v[48:63], v[216:219], v[144:147], v[48:63]
	ds_read_b128 v[216:219], v188 offset:24576
	s_add_i32 s2, s42, 5
	s_waitcnt lgkmcnt(5)
	v_mfma_f32_32x32x16_bf16 v[32:47], v[220:223], v[144:147], v[32:47]
	ds_read_b128 v[220:223], v188 offset:28672
	s_and_b32 s2, s2, 31
	s_waitcnt lgkmcnt(5)
	v_mfma_f32_32x32x16_bf16 v[16:31], v[224:227], v[144:147], v[16:31]
	ds_read_b128 v[224:227], v186 offset:16384
	s_mul_i32 s2, s2, 0x44000
	s_waitcnt lgkmcnt(5)
	v_mfma_f32_32x32x16_bf16 v[0:15], v[228:231], v[144:147], v[0:15]
	ds_read_b128 v[228:231], v186 offset:20480
	s_add_u32 s48, s26, s2
	s_waitcnt lgkmcnt(5)
	v_mfma_f32_32x32x16_bf16 v[48:63], v[208:211], v[148:151], v[48:63]
	ds_read_b128 v[208:211], v186 offset:24576
	s_addc_u32 s49, s27, 0
	s_waitcnt lgkmcnt(5)
	v_mfma_f32_32x32x16_bf16 v[32:47], v[212:215], v[148:151], v[32:47]
	ds_read_b128 v[212:215], v186 offset:28672
	s_add_u32 s50, s48, 0x80
	s_waitcnt lgkmcnt(5)
	v_mfma_f32_32x32x16_bf16 v[16:31], v[216:219], v[148:151], v[16:31]
	ds_read_b128 v[216:219], v189 offset:16384
	s_addc_u32 s51, s49, 0
	s_waitcnt lgkmcnt(5)
	v_mfma_f32_32x32x16_bf16 v[0:15], v[220:223], v[148:151], v[0:15]
	ds_read_b128 v[220:223], v189 offset:20480
	s_add_i32 s2, s42, 3
	s_waitcnt lgkmcnt(5)
	v_mfma_f32_32x32x16_bf16 v[48:63], v[224:227], v[152:155], v[48:63]
	ds_read_b128 v[224:227], v189 offset:24576
	s_and_b32 s2, s2, 31
	s_waitcnt lgkmcnt(5)
	v_mfma_f32_32x32x16_bf16 v[32:47], v[228:231], v[152:155], v[32:47]
	ds_read_b128 v[228:231], v189 offset:28672
	s_lshl_b32 s2, s2, 7
	s_waitcnt lgkmcnt(5)
	v_mfma_f32_32x32x16_bf16 v[16:31], v[208:211], v[152:155], v[16:31]
	ds_read_b128 v[208:211], v182 offset:49152
	s_add_u32 s52, s10, s2
	s_waitcnt lgkmcnt(5)
	v_mfma_f32_32x32x16_bf16 v[0:15], v[212:215], v[152:155], v[0:15]
	ds_read_b128 v[212:215], v182 offset:53248
	s_addc_u32 s53, s11, 0
	s_waitcnt lgkmcnt(5)
	v_mfma_f32_32x32x16_bf16 v[48:63], v[216:219], v[156:159], v[48:63]
	ds_read_b128 v[216:219], v183 offset:49152
	s_add_u32 s54, s52, 0x204000
	s_waitcnt lgkmcnt(5)
	v_mfma_f32_32x32x16_bf16 v[32:47], v[220:223], v[156:159], v[32:47]
	ds_read_b128 v[220:223], v183 offset:53248
	s_addc_u32 s55, s53, 0
	s_waitcnt lgkmcnt(5)
	v_mfma_f32_32x32x16_bf16 v[16:31], v[224:227], v[156:159], v[16:31]
	ds_read_b128 v[224:227], v184 offset:49152
	s_waitcnt lgkmcnt(5)
	v_mfma_f32_32x32x16_bf16 v[0:15], v[228:231], v[156:159], v[0:15]
	ds_read_b128 v[228:231], v184 offset:53248
	s_waitcnt lgkmcnt(5)
	v_mfma_f32_32x32x16_bf16 v[96:111], v[208:211], v[128:131], 0
	ds_read_b128 v[208:211], v185 offset:49152
	s_waitcnt lgkmcnt(5)
	v_mfma_f32_32x32x16_bf16 v[112:127], v[212:215], v[128:131], 0
	ds_read_b128 v[212:215], v185 offset:53248
	s_waitcnt lgkmcnt(5)
	v_mfma_f32_32x32x16_bf16 v[96:111], v[216:219], v[132:135], v[96:111]
	s_waitcnt lgkmcnt(4)
	v_mfma_f32_32x32x16_bf16 v[112:127], v[220:223], v[132:135], v[112:127]
	s_waitcnt lgkmcnt(3)
	v_mfma_f32_32x32x16_bf16 v[96:111], v[224:227], v[136:139], v[96:111]
	s_waitcnt lgkmcnt(2)
	v_mfma_f32_32x32x16_bf16 v[112:127], v[228:231], v[136:139], v[112:127]
	s_waitcnt lgkmcnt(1)
	v_mfma_f32_32x32x16_bf16 v[96:111], v[208:211], v[140:143], v[96:111]
	s_waitcnt lgkmcnt(0)
	v_mfma_f32_32x32x16_bf16 v[112:127], v[212:215], v[140:143], v[112:127]
	ds_read_b128 v[216:219], v187 offset:32768
	ds_read_b128 v[220:223], v187 offset:36864
	ds_read_b128 v[224:227], v187 offset:40960
	ds_read_b128 v[228:231], v187 offset:45056
	ds_read_b128 v[208:211], v188 offset:32768
	ds_read_b128 v[212:215], v188 offset:36864
	v_max3_f32 v254, v64, v65, v66
	s_add_i32 m0, s5, 32768
	v_max3_f32 v255, v80, v81, v82
	global_load_lds_dwordx4 v170, s[48:49]
	v_max3_f32 v254, v254, v67, v68
	s_add_i32 m0, s5, 40960
	v_max3_f32 v255, v255, v83, v84
	global_load_lds_dwordx4 v170, s[50:51]
	v_max3_f32 v254, v254, v69, v70
	s_add_i32 m0, s5, 65536
	v_max3_f32 v255, v255, v85, v86
	global_load_lds_dwordx4 v172, s[52:53]
	v_max3_f32 v254, v254, v71, v72
	s_add_i32 m0, s5, 73728
	v_max3_f32 v255, v255, v87, v88
	global_load_lds_dwordx4 v172, s[54:55]
	v_max3_f32 v254, v254, v73, v74
	v_max3_f32 v255, v255, v89, v90
	v_max3_f32 v254, v254, v75, v76
	v_max3_f32 v255, v255, v91, v92
	v_max3_f32 v254, v254, v77, v78
	v_max3_f32 v255, v255, v93, v94
	v_max3_f32 v254, v254, v79, v95
	v_max_f32_e32 v254, v254, v255
	v_mov_b32_e32 v255, v254
	s_nop 1
	v_permlane32_swap_b32_e32 v254, v255
	v_max_f32_e32 v254, v254, v255
	v_add_f32_e32 v180, 0x4138aa3b, v175
	v_cmp_gt_f32_e32 vcc, v254, v180
	s_nop 1
	v_cndmask_b32_e32 v180, v175, v254, vcc
	v_sub_f32_e32 v255, v175, v180
	v_exp_f32_e32 v174, v255
	v_mov_b32_e32 v175, v180
	v_sub_f32_e32 v64, v64, v175
	v_sub_f32_e32 v65, v65, v175
	v_sub_f32_e32 v66, v66, v175
	v_sub_f32_e32 v67, v67, v175
	v_sub_f32_e32 v68, v68, v175
	v_sub_f32_e32 v69, v69, v175
	v_sub_f32_e32 v70, v70, v175
	v_sub_f32_e32 v71, v71, v175
	v_exp_f32_e32 v64, v64
	v_exp_f32_e32 v65, v65
	v_exp_f32_e32 v66, v66
	v_exp_f32_e32 v67, v67
	v_exp_f32_e32 v68, v68
	v_exp_f32_e32 v69, v69
	v_exp_f32_e32 v70, v70
	v_exp_f32_e32 v71, v71
	v_add_f32_e32 v190, v64, v65
	v_add_f32_e32 v191, v66, v67
	v_add_f32_e32 v190, v190, v68
	v_add_f32_e32 v191, v191, v69
	v_add_f32_e32 v190, v190, v70
	v_add_f32_e32 v191, v191, v71
	v_cvt_pk_bf16_f32 v144, v64, v65
	v_cvt_pk_bf16_f32 v145, v66, v67
	v_cvt_pk_bf16_f32 v146, v68, v69
	v_cvt_pk_bf16_f32 v147, v70, v71
	v_sub_f32_e32 v72, v72, v175
	v_sub_f32_e32 v73, v73, v175
	v_sub_f32_e32 v74, v74, v175
	v_sub_f32_e32 v75, v75, v175
	v_sub_f32_e32 v76, v76, v175
	v_sub_f32_e32 v77, v77, v175
	v_sub_f32_e32 v78, v78, v175
	v_sub_f32_e32 v79, v79, v175
	v_exp_f32_e32 v72, v72
	v_exp_f32_e32 v73, v73
	v_exp_f32_e32 v74, v74
	v_exp_f32_e32 v75, v75
	v_exp_f32_e32 v76, v76
	v_exp_f32_e32 v77, v77
	v_exp_f32_e32 v78, v78
	v_exp_f32_e32 v79, v79
	v_add_f32_e32 v190, v190, v72
	v_add_f32_e32 v191, v191, v73
	v_add_f32_e32 v190, v190, v74
	v_add_f32_e32 v191, v191, v75
	v_add_f32_e32 v190, v190, v76
	v_add_f32_e32 v191, v191, v77
	v_add_f32_e32 v190, v190, v78
	v_add_f32_e32 v191, v191, v79
	v_cvt_pk_bf16_f32 v148, v72, v73
	v_cvt_pk_bf16_f32 v149, v74, v75
	v_cvt_pk_bf16_f32 v150, v76, v77
	v_cvt_pk_bf16_f32 v151, v78, v79
	v_sub_f32_e32 v80, v80, v175
	v_sub_f32_e32 v81, v81, v175
	v_sub_f32_e32 v82, v82, v175
	v_sub_f32_e32 v83, v83, v175
	v_sub_f32_e32 v84, v84, v175
	v_sub_f32_e32 v85, v85, v175
	v_sub_f32_e32 v86, v86, v175
	v_sub_f32_e32 v87, v87, v175
	v_exp_f32_e32 v80, v80
	v_exp_f32_e32 v81, v81
	v_exp_f32_e32 v82, v82
	v_exp_f32_e32 v83, v83
	v_exp_f32_e32 v84, v84
	v_exp_f32_e32 v85, v85
	v_exp_f32_e32 v86, v86
	v_exp_f32_e32 v87, v87
	v_add_f32_e32 v190, v190, v80
	v_add_f32_e32 v191, v191, v81
	v_add_f32_e32 v190, v190, v82
	v_add_f32_e32 v191, v191, v83
	v_add_f32_e32 v190, v190, v84
	v_add_f32_e32 v191, v191, v85
	v_add_f32_e32 v190, v190, v86
	v_add_f32_e32 v191, v191, v87
	v_cvt_pk_bf16_f32 v152, v80, v81
	v_cvt_pk_bf16_f32 v153, v82, v83
	v_cvt_pk_bf16_f32 v154, v84, v85
	v_cvt_pk_bf16_f32 v155, v86, v87
	v_sub_f32_e32 v88, v88, v175
	v_sub_f32_e32 v89, v89, v175
	v_sub_f32_e32 v90, v90, v175
	v_sub_f32_e32 v91, v91, v175
	v_sub_f32_e32 v92, v92, v175
	v_sub_f32_e32 v93, v93, v175
	v_sub_f32_e32 v94, v94, v175
	v_sub_f32_e32 v95, v95, v175
	v_exp_f32_e32 v88, v88
	v_exp_f32_e32 v89, v89
	v_exp_f32_e32 v90, v90
	v_exp_f32_e32 v91, v91
	v_exp_f32_e32 v92, v92
	v_exp_f32_e32 v93, v93
	v_exp_f32_e32 v94, v94
	v_exp_f32_e32 v95, v95
	v_add_f32_e32 v190, v190, v88
	v_add_f32_e32 v191, v191, v89
	v_add_f32_e32 v190, v190, v90
	v_add_f32_e32 v191, v191, v91
	v_add_f32_e32 v190, v190, v92
	v_add_f32_e32 v191, v191, v93
	v_add_f32_e32 v190, v190, v94
	v_add_f32_e32 v191, v191, v95
	v_cvt_pk_bf16_f32 v156, v88, v89
	v_cvt_pk_bf16_f32 v157, v90, v91
	v_cvt_pk_bf16_f32 v158, v92, v93
	v_cvt_pk_bf16_f32 v159, v94, v95
	v_add_f32_e32 v190, v190, v191
	v_fma_f32 v167, v167, v174, v190
	s_cbranch_vccz .Lattn_noresc_L1_A
	s_nop 7
	s_nop 7
	v_pk_mul_f32 v[0:1], v[0:1], v[174:175] op_sel_hi:[1,0]
	v_pk_mul_f32 v[2:3], v[2:3], v[174:175] op_sel_hi:[1,0]
	v_pk_mul_f32 v[4:5], v[4:5], v[174:175] op_sel_hi:[1,0]
	v_pk_mul_f32 v[6:7], v[6:7], v[174:175] op_sel_hi:[1,0]
	v_pk_mul_f32 v[8:9], v[8:9], v[174:175] op_sel_hi:[1,0]
	v_pk_mul_f32 v[10:11], v[10:11], v[174:175] op_sel_hi:[1,0]
	v_pk_mul_f32 v[12:13], v[12:13], v[174:175] op_sel_hi:[1,0]
	v_pk_mul_f32 v[14:15], v[14:15], v[174:175] op_sel_hi:[1,0]
	v_pk_mul_f32 v[16:17], v[16:17], v[174:175] op_sel_hi:[1,0]
	v_pk_mul_f32 v[18:19], v[18:19], v[174:175] op_sel_hi:[1,0]
	v_pk_mul_f32 v[20:21], v[20:21], v[174:175] op_sel_hi:[1,0]
	v_pk_mul_f32 v[22:23], v[22:23], v[174:175] op_sel_hi:[1,0]
	v_pk_mul_f32 v[24:25], v[24:25], v[174:175] op_sel_hi:[1,0]
	v_pk_mul_f32 v[26:27], v[26:27], v[174:175] op_sel_hi:[1,0]
	v_pk_mul_f32 v[28:29], v[28:29], v[174:175] op_sel_hi:[1,0]
	v_pk_mul_f32 v[30:31], v[30:31], v[174:175] op_sel_hi:[1,0]
	v_pk_mul_f32 v[32:33], v[32:33], v[174:175] op_sel_hi:[1,0]
	v_pk_mul_f32 v[34:35], v[34:35], v[174:175] op_sel_hi:[1,0]
	v_pk_mul_f32 v[36:37], v[36:37], v[174:175] op_sel_hi:[1,0]
	v_pk_mul_f32 v[38:39], v[38:39], v[174:175] op_sel_hi:[1,0]
	v_pk_mul_f32 v[40:41], v[40:41], v[174:175] op_sel_hi:[1,0]
	v_pk_mul_f32 v[42:43], v[42:43], v[174:175] op_sel_hi:[1,0]
	v_pk_mul_f32 v[44:45], v[44:45], v[174:175] op_sel_hi:[1,0]
	v_pk_mul_f32 v[46:47], v[46:47], v[174:175] op_sel_hi:[1,0]
	v_pk_mul_f32 v[48:49], v[48:49], v[174:175] op_sel_hi:[1,0]
	v_pk_mul_f32 v[50:51], v[50:51], v[174:175] op_sel_hi:[1,0]
	v_pk_mul_f32 v[52:53], v[52:53], v[174:175] op_sel_hi:[1,0]
	v_pk_mul_f32 v[54:55], v[54:55], v[174:175] op_sel_hi:[1,0]
	v_pk_mul_f32 v[56:57], v[56:57], v[174:175] op_sel_hi:[1,0]
	v_pk_mul_f32 v[58:59], v[58:59], v[174:175] op_sel_hi:[1,0]
	v_pk_mul_f32 v[60:61], v[60:61], v[174:175] op_sel_hi:[1,0]
	v_pk_mul_f32 v[62:63], v[62:63], v[174:175] op_sel_hi:[1,0]
	s_nop 1

.Lattn_tb23_A:
	s_waitcnt lgkmcnt(5)
	v_mfma_f32_32x32x16_bf16 v[48:63], v[216:219], v[144:147], v[48:63]
	ds_read_b128 v[216:219], v188 offset:40960
	s_add_i32 s2, s42, 6
	s_waitcnt lgkmcnt(5)
	v_mfma_f32_32x32x16_bf16 v[32:47], v[220:223], v[144:147], v[32:47]
	ds_read_b128 v[220:223], v188 offset:45056
	s_and_b32 s2, s2, 31
	s_waitcnt lgkmcnt(5)
	v_mfma_f32_32x32x16_bf16 v[16:31], v[224:227], v[144:147], v[16:31]
	ds_read_b128 v[224:227], v186 offset:32768
	s_mul_i32 s2, s2, 0x44000
	s_waitcnt lgkmcnt(5)
	v_mfma_f32_32x32x16_bf16 v[0:15], v[228:231], v[144:147], v[0:15]
	ds_read_b128 v[228:231], v186 offset:36864
	s_add_u32 s48, s26, s2
	s_waitcnt lgkmcnt(5)
	v_mfma_f32_32x32x16_bf16 v[48:63], v[208:211], v[148:151], v[48:63]
	ds_read_b128 v[208:211], v186 offset:40960
	s_addc_u32 s49, s27, 0
	s_waitcnt lgkmcnt(5)
	v_mfma_f32_32x32x16_bf16 v[32:47], v[212:215], v[148:151], v[32:47]
	ds_read_b128 v[212:215], v186 offset:45056
	s_add_u32 s50, s48, 0x80
	s_waitcnt lgkmcnt(5)
	v_mfma_f32_32x32x16_bf16 v[16:31], v[216:219], v[148:151], v[16:31]
	ds_read_b128 v[216:219], v189 offset:32768
	s_addc_u32 s51, s49, 0
	s_waitcnt lgkmcnt(5)
	v_mfma_f32_32x32x16_bf16 v[0:15], v[220:223], v[148:151], v[0:15]
	ds_read_b128 v[220:223], v189 offset:36864
	s_add_i32 s2, s42, 4
	s_waitcnt lgkmcnt(5)
	v_mfma_f32_32x32x16_bf16 v[48:63], v[224:227], v[152:155], v[48:63]
	ds_read_b128 v[224:227], v189 offset:40960
	s_and_b32 s2, s2, 31
	s_waitcnt lgkmcnt(5)
	v_mfma_f32_32x32x16_bf16 v[32:47], v[228:231], v[152:155], v[32:47]
	ds_read_b128 v[228:231], v189 offset:45056
	s_lshl_b32 s2, s2, 7
	s_waitcnt lgkmcnt(5)
	v_mfma_f32_32x32x16_bf16 v[16:31], v[208:211], v[152:155], v[16:31]
	ds_read_b128 v[208:211], v182 offset:0
	s_add_u32 s52, s10, s2
	s_waitcnt lgkmcnt(5)
	v_mfma_f32_32x32x16_bf16 v[0:15], v[212:215], v[152:155], v[0:15]
	ds_read_b128 v[212:215], v182 offset:4096
	s_addc_u32 s53, s11, 0
	s_waitcnt lgkmcnt(5)
	v_mfma_f32_32x32x16_bf16 v[48:63], v[216:219], v[156:159], v[48:63]
	ds_read_b128 v[216:219], v183 offset:0
	s_add_u32 s54, s52, 0x204000
	s_waitcnt lgkmcnt(5)
	v_mfma_f32_32x32x16_bf16 v[32:47], v[220:223], v[156:159], v[32:47]
	ds_read_b128 v[220:223], v183 offset:4096
	s_addc_u32 s55, s53, 0
	s_waitcnt lgkmcnt(5)
	v_mfma_f32_32x32x16_bf16 v[16:31], v[224:227], v[156:159], v[16:31]
	ds_read_b128 v[224:227], v184 offset:0
	s_waitcnt lgkmcnt(5)
	v_mfma_f32_32x32x16_bf16 v[0:15], v[228:231], v[156:159], v[0:15]
	ds_read_b128 v[228:231], v184 offset:4096
	s_waitcnt lgkmcnt(5)
	v_mfma_f32_32x32x16_bf16 v[64:79], v[208:211], v[128:131], 0
	ds_read_b128 v[208:211], v185 offset:0
	s_waitcnt lgkmcnt(5)
	v_mfma_f32_32x32x16_bf16 v[80:95], v[212:215], v[128:131], 0
	ds_read_b128 v[212:215], v185 offset:4096
	s_waitcnt lgkmcnt(5)
	v_mfma_f32_32x32x16_bf16 v[64:79], v[216:219], v[132:135], v[64:79]
	s_waitcnt lgkmcnt(4)
	v_mfma_f32_32x32x16_bf16 v[80:95], v[220:223], v[132:135], v[80:95]
	s_waitcnt lgkmcnt(3)
	v_mfma_f32_32x32x16_bf16 v[64:79], v[224:227], v[136:139], v[64:79]
	s_waitcnt lgkmcnt(2)
	v_mfma_f32_32x32x16_bf16 v[80:95], v[228:231], v[136:139], v[80:95]
	s_waitcnt lgkmcnt(1)
	v_mfma_f32_32x32x16_bf16 v[64:79], v[208:211], v[140:143], v[64:79]
	s_waitcnt lgkmcnt(0)
	v_mfma_f32_32x32x16_bf16 v[80:95], v[212:215], v[140:143], v[80:95]
	ds_read_b128 v[216:219], v187 offset:49152
	ds_read_b128 v[220:223], v187 offset:53248
	ds_read_b128 v[224:227], v187 offset:57344
	ds_read_b128 v[228:231], v187 offset:61440
	ds_read_b128 v[208:211], v188 offset:49152
	ds_read_b128 v[212:215], v188 offset:53248
	v_max3_f32 v254, v96, v97, v98
	s_add_i32 m0, s5, 49152
	v_max3_f32 v255, v112, v113, v114
	global_load_lds_dwordx4 v170, s[48:49]
	v_max3_f32 v254, v254, v99, v100
	s_add_i32 m0, s5, 57344
	v_max3_f32 v255, v255, v115, v116
	global_load_lds_dwordx4 v170, s[50:51]
	v_max3_f32 v254, v254, v101, v102
	s_add_i32 m0, s5, 81920
	v_max3_f32 v255, v255, v117, v118
	global_load_lds_dwordx4 v172, s[52:53]
	v_max3_f32 v254, v254, v103, v104
	s_add_i32 m0, s5, 90112
	v_max3_f32 v255, v255, v119, v120
	global_load_lds_dwordx4 v172, s[54:55]
	v_max3_f32 v254, v254, v105, v106
	v_max3_f32 v255, v255, v121, v122
	v_max3_f32 v254, v254, v107, v108
	v_max3_f32 v255, v255, v123, v124
	v_max3_f32 v254, v254, v109, v110
	v_max3_f32 v255, v255, v125, v126
	v_max3_f32 v254, v254, v111, v127
	v_max_f32_e32 v254, v254, v255
	v_mov_b32_e32 v255, v254
	s_nop 1
	v_permlane32_swap_b32_e32 v254, v255
	v_max_f32_e32 v254, v254, v255
	v_add_f32_e32 v180, 0x4138aa3b, v175
	v_cmp_gt_f32_e32 vcc, v254, v180
	s_nop 1
	v_cndmask_b32_e32 v180, v175, v254, vcc
	v_sub_f32_e32 v255, v175, v180
	v_exp_f32_e32 v174, v255
	v_mov_b32_e32 v175, v180
	v_sub_f32_e32 v96, v96, v175
	v_sub_f32_e32 v97, v97, v175
	v_sub_f32_e32 v98, v98, v175
	v_sub_f32_e32 v99, v99, v175
	v_sub_f32_e32 v100, v100, v175
	v_sub_f32_e32 v101, v101, v175
	v_sub_f32_e32 v102, v102, v175
	v_sub_f32_e32 v103, v103, v175
	v_exp_f32_e32 v96, v96
	v_exp_f32_e32 v97, v97
	v_exp_f32_e32 v98, v98
	v_exp_f32_e32 v99, v99
	v_exp_f32_e32 v100, v100
	v_exp_f32_e32 v101, v101
	v_exp_f32_e32 v102, v102
	v_exp_f32_e32 v103, v103
	v_add_f32_e32 v190, v96, v97
	v_add_f32_e32 v191, v98, v99
	v_add_f32_e32 v190, v190, v100
	v_add_f32_e32 v191, v191, v101
	v_add_f32_e32 v190, v190, v102
	v_add_f32_e32 v191, v191, v103
	v_cvt_pk_bf16_f32 v144, v96, v97
	v_cvt_pk_bf16_f32 v145, v98, v99
	v_cvt_pk_bf16_f32 v146, v100, v101
	v_cvt_pk_bf16_f32 v147, v102, v103
	v_sub_f32_e32 v104, v104, v175
	v_sub_f32_e32 v105, v105, v175
	v_sub_f32_e32 v106, v106, v175
	v_sub_f32_e32 v107, v107, v175
	v_sub_f32_e32 v108, v108, v175
	v_sub_f32_e32 v109, v109, v175
	v_sub_f32_e32 v110, v110, v175
	v_sub_f32_e32 v111, v111, v175
	v_exp_f32_e32 v104, v104
	v_exp_f32_e32 v105, v105
	v_exp_f32_e32 v106, v106
	v_exp_f32_e32 v107, v107
	v_exp_f32_e32 v108, v108
	v_exp_f32_e32 v109, v109
	v_exp_f32_e32 v110, v110
	v_exp_f32_e32 v111, v111
	v_add_f32_e32 v190, v190, v104
	v_add_f32_e32 v191, v191, v105
	v_add_f32_e32 v190, v190, v106
	v_add_f32_e32 v191, v191, v107
	v_add_f32_e32 v190, v190, v108
	v_add_f32_e32 v191, v191, v109
	v_add_f32_e32 v190, v190, v110
	v_add_f32_e32 v191, v191, v111
	v_cvt_pk_bf16_f32 v148, v104, v105
	v_cvt_pk_bf16_f32 v149, v106, v107
	v_cvt_pk_bf16_f32 v150, v108, v109
	v_cvt_pk_bf16_f32 v151, v110, v111
	v_sub_f32_e32 v112, v112, v175
	v_sub_f32_e32 v113, v113, v175
	v_sub_f32_e32 v114, v114, v175
	v_sub_f32_e32 v115, v115, v175
	v_sub_f32_e32 v116, v116, v175
	v_sub_f32_e32 v117, v117, v175
	v_sub_f32_e32 v118, v118, v175
	v_sub_f32_e32 v119, v119, v175
	v_exp_f32_e32 v112, v112
	v_exp_f32_e32 v113, v113
	v_exp_f32_e32 v114, v114
	v_exp_f32_e32 v115, v115
	v_exp_f32_e32 v116, v116
	v_exp_f32_e32 v117, v117
	v_exp_f32_e32 v118, v118
	v_exp_f32_e32 v119, v119
	v_add_f32_e32 v190, v190, v112
	v_add_f32_e32 v191, v191, v113
	v_add_f32_e32 v190, v190, v114
	v_add_f32_e32 v191, v191, v115
	v_add_f32_e32 v190, v190, v116
	v_add_f32_e32 v191, v191, v117
	v_add_f32_e32 v190, v190, v118
	v_add_f32_e32 v191, v191, v119
	v_cvt_pk_bf16_f32 v152, v112, v113
	v_cvt_pk_bf16_f32 v153, v114, v115
	v_cvt_pk_bf16_f32 v154, v116, v117
	v_cvt_pk_bf16_f32 v155, v118, v119
	v_sub_f32_e32 v120, v120, v175
	v_sub_f32_e32 v121, v121, v175
	v_sub_f32_e32 v122, v122, v175
	v_sub_f32_e32 v123, v123, v175
	v_sub_f32_e32 v124, v124, v175
	v_sub_f32_e32 v125, v125, v175
	v_sub_f32_e32 v126, v126, v175
	v_sub_f32_e32 v127, v127, v175
	v_exp_f32_e32 v120, v120
	v_exp_f32_e32 v121, v121
	v_exp_f32_e32 v122, v122
	v_exp_f32_e32 v123, v123
	v_exp_f32_e32 v124, v124
	v_exp_f32_e32 v125, v125
	v_exp_f32_e32 v126, v126
	v_exp_f32_e32 v127, v127
	v_add_f32_e32 v190, v190, v120
	v_add_f32_e32 v191, v191, v121
	v_add_f32_e32 v190, v190, v122
	v_add_f32_e32 v191, v191, v123
	v_add_f32_e32 v190, v190, v124
	v_add_f32_e32 v191, v191, v125
	v_add_f32_e32 v190, v190, v126
	v_add_f32_e32 v191, v191, v127
	v_cvt_pk_bf16_f32 v156, v120, v121
	v_cvt_pk_bf16_f32 v157, v122, v123
	v_cvt_pk_bf16_f32 v158, v124, v125
	v_cvt_pk_bf16_f32 v159, v126, v127
	v_add_f32_e32 v190, v190, v191
	v_fma_f32 v167, v167, v174, v190
	s_cbranch_vccz .Lattn_noresc_L2_A
	s_nop 7
	s_nop 7
	v_pk_mul_f32 v[0:1], v[0:1], v[174:175] op_sel_hi:[1,0]
	v_pk_mul_f32 v[2:3], v[2:3], v[174:175] op_sel_hi:[1,0]
	v_pk_mul_f32 v[4:5], v[4:5], v[174:175] op_sel_hi:[1,0]
	v_pk_mul_f32 v[6:7], v[6:7], v[174:175] op_sel_hi:[1,0]
	v_pk_mul_f32 v[8:9], v[8:9], v[174:175] op_sel_hi:[1,0]
	v_pk_mul_f32 v[10:11], v[10:11], v[174:175] op_sel_hi:[1,0]
	v_pk_mul_f32 v[12:13], v[12:13], v[174:175] op_sel_hi:[1,0]
	v_pk_mul_f32 v[14:15], v[14:15], v[174:175] op_sel_hi:[1,0]
	v_pk_mul_f32 v[16:17], v[16:17], v[174:175] op_sel_hi:[1,0]
	v_pk_mul_f32 v[18:19], v[18:19], v[174:175] op_sel_hi:[1,0]
	v_pk_mul_f32 v[20:21], v[20:21], v[174:175] op_sel_hi:[1,0]
	v_pk_mul_f32 v[22:23], v[22:23], v[174:175] op_sel_hi:[1,0]
	v_pk_mul_f32 v[24:25], v[24:25], v[174:175] op_sel_hi:[1,0]
	v_pk_mul_f32 v[26:27], v[26:27], v[174:175] op_sel_hi:[1,0]
	v_pk_mul_f32 v[28:29], v[28:29], v[174:175] op_sel_hi:[1,0]
	v_pk_mul_f32 v[30:31], v[30:31], v[174:175] op_sel_hi:[1,0]
	v_pk_mul_f32 v[32:33], v[32:33], v[174:175] op_sel_hi:[1,0]
	v_pk_mul_f32 v[34:35], v[34:35], v[174:175] op_sel_hi:[1,0]
	v_pk_mul_f32 v[36:37], v[36:37], v[174:175] op_sel_hi:[1,0]
	v_pk_mul_f32 v[38:39], v[38:39], v[174:175] op_sel_hi:[1,0]
	v_pk_mul_f32 v[40:41], v[40:41], v[174:175] op_sel_hi:[1,0]
	v_pk_mul_f32 v[42:43], v[42:43], v[174:175] op_sel_hi:[1,0]
	v_pk_mul_f32 v[44:45], v[44:45], v[174:175] op_sel_hi:[1,0]
	v_pk_mul_f32 v[46:47], v[46:47], v[174:175] op_sel_hi:[1,0]
	v_pk_mul_f32 v[48:49], v[48:49], v[174:175] op_sel_hi:[1,0]
	v_pk_mul_f32 v[50:51], v[50:51], v[174:175] op_sel_hi:[1,0]
	v_pk_mul_f32 v[52:53], v[52:53], v[174:175] op_sel_hi:[1,0]
	v_pk_mul_f32 v[54:55], v[54:55], v[174:175] op_sel_hi:[1,0]
	v_pk_mul_f32 v[56:57], v[56:57], v[174:175] op_sel_hi:[1,0]
	v_pk_mul_f32 v[58:59], v[58:59], v[174:175] op_sel_hi:[1,0]
	v_pk_mul_f32 v[60:61], v[60:61], v[174:175] op_sel_hi:[1,0]
	v_pk_mul_f32 v[62:63], v[62:63], v[174:175] op_sel_hi:[1,0]
	s_nop 1

.Lattn_tb25_A:
	s_waitcnt lgkmcnt(5)
	v_mfma_f32_32x32x16_bf16 v[48:63], v[216:219], v[144:147], v[48:63]
	ds_read_b128 v[216:219], v188 offset:57344
	s_add_i32 s2, s42, 7
	s_waitcnt lgkmcnt(5)
	v_mfma_f32_32x32x16_bf16 v[32:47], v[220:223], v[144:147], v[32:47]
	ds_read_b128 v[220:223], v188 offset:61440
	s_and_b32 s2, s2, 31
	s_waitcnt lgkmcnt(5)
	v_mfma_f32_32x32x16_bf16 v[16:31], v[224:227], v[144:147], v[16:31]
	ds_read_b128 v[224:227], v186 offset:49152
	s_mul_i32 s2, s2, 0x44000
	s_waitcnt lgkmcnt(5)
	v_mfma_f32_32x32x16_bf16 v[0:15], v[228:231], v[144:147], v[0:15]
	ds_read_b128 v[228:231], v186 offset:53248
	s_add_u32 s48, s26, s2
	s_waitcnt lgkmcnt(5)
	v_mfma_f32_32x32x16_bf16 v[48:63], v[208:211], v[148:151], v[48:63]
	ds_read_b128 v[208:211], v186 offset:57344
	s_addc_u32 s49, s27, 0
	s_waitcnt lgkmcnt(5)
	v_mfma_f32_32x32x16_bf16 v[32:47], v[212:215], v[148:151], v[32:47]
	ds_read_b128 v[212:215], v186 offset:61440
	s_add_u32 s50, s48, 0x80
	s_waitcnt lgkmcnt(5)
	v_mfma_f32_32x32x16_bf16 v[16:31], v[216:219], v[148:151], v[16:31]
	ds_read_b128 v[216:219], v189 offset:49152
	s_addc_u32 s51, s49, 0
	s_waitcnt lgkmcnt(5)
	v_mfma_f32_32x32x16_bf16 v[0:15], v[220:223], v[148:151], v[0:15]
	ds_read_b128 v[220:223], v189 offset:53248
	s_add_i32 s2, s42, 5
	s_waitcnt lgkmcnt(5)
	v_mfma_f32_32x32x16_bf16 v[48:63], v[224:227], v[152:155], v[48:63]
	ds_read_b128 v[224:227], v189 offset:57344
	s_and_b32 s2, s2, 31
	s_waitcnt lgkmcnt(5)
	v_mfma_f32_32x32x16_bf16 v[32:47], v[228:231], v[152:155], v[32:47]
	ds_read_b128 v[228:231], v189 offset:61440
	s_lshl_b32 s2, s2, 7
	s_waitcnt lgkmcnt(5)
	v_mfma_f32_32x32x16_bf16 v[16:31], v[208:211], v[152:155], v[16:31]
	ds_read_b128 v[208:211], v182 offset:16384
	s_add_u32 s52, s10, s2
	s_waitcnt lgkmcnt(5)
	v_mfma_f32_32x32x16_bf16 v[0:15], v[212:215], v[152:155], v[0:15]
	ds_read_b128 v[212:215], v182 offset:20480
	s_addc_u32 s53, s11, 0
	s_waitcnt lgkmcnt(5)
	v_mfma_f32_32x32x16_bf16 v[48:63], v[216:219], v[156:159], v[48:63]
	ds_read_b128 v[216:219], v183 offset:16384
	s_add_u32 s54, s52, 0x204000
	s_waitcnt lgkmcnt(5)
	v_mfma_f32_32x32x16_bf16 v[32:47], v[220:223], v[156:159], v[32:47]
	ds_read_b128 v[220:223], v183 offset:20480
	s_addc_u32 s55, s53, 0
	s_waitcnt lgkmcnt(5)
	v_mfma_f32_32x32x16_bf16 v[16:31], v[224:227], v[156:159], v[16:31]
	ds_read_b128 v[224:227], v184 offset:16384
	s_waitcnt lgkmcnt(5)
	v_mfma_f32_32x32x16_bf16 v[0:15], v[228:231], v[156:159], v[0:15]
	ds_read_b128 v[228:231], v184 offset:20480
	s_waitcnt lgkmcnt(5)
	v_mfma_f32_32x32x16_bf16 v[96:111], v[208:211], v[128:131], 0
	ds_read_b128 v[208:211], v185 offset:16384
	s_waitcnt lgkmcnt(5)
	v_mfma_f32_32x32x16_bf16 v[112:127], v[212:215], v[128:131], 0
	ds_read_b128 v[212:215], v185 offset:20480
	s_waitcnt lgkmcnt(5)
	v_mfma_f32_32x32x16_bf16 v[96:111], v[216:219], v[132:135], v[96:111]
	s_waitcnt lgkmcnt(4)
	v_mfma_f32_32x32x16_bf16 v[112:127], v[220:223], v[132:135], v[112:127]
	s_waitcnt lgkmcnt(3)
	v_mfma_f32_32x32x16_bf16 v[96:111], v[224:227], v[136:139], v[96:111]
	s_waitcnt lgkmcnt(2)
	v_mfma_f32_32x32x16_bf16 v[112:127], v[228:231], v[136:139], v[112:127]
	s_waitcnt lgkmcnt(1)
	v_mfma_f32_32x32x16_bf16 v[96:111], v[208:211], v[140:143], v[96:111]
	s_waitcnt lgkmcnt(0)
	v_mfma_f32_32x32x16_bf16 v[112:127], v[212:215], v[140:143], v[112:127]
	ds_read_b128 v[216:219], v187 offset:0
	ds_read_b128 v[220:223], v187 offset:4096
	ds_read_b128 v[224:227], v187 offset:8192
	ds_read_b128 v[228:231], v187 offset:12288
	ds_read_b128 v[208:211], v188 offset:0
	ds_read_b128 v[212:215], v188 offset:4096
	v_max3_f32 v254, v64, v65, v66
	s_add_i32 m0, s5, 0
	v_max3_f32 v255, v80, v81, v82
	global_load_lds_dwordx4 v170, s[48:49]
	v_max3_f32 v254, v254, v67, v68
	s_add_i32 m0, s5, 8192
	v_max3_f32 v255, v255, v83, v84
	global_load_lds_dwordx4 v170, s[50:51]
	v_max3_f32 v254, v254, v69, v70
	s_add_i32 m0, s5, 98304
	v_max3_f32 v255, v255, v85, v86
	global_load_lds_dwordx4 v172, s[52:53]
	v_max3_f32 v254, v254, v71, v72
	s_add_i32 m0, s5, 106496
	v_max3_f32 v255, v255, v87, v88
	global_load_lds_dwordx4 v172, s[54:55]
	v_max3_f32 v254, v254, v73, v74
	v_max3_f32 v255, v255, v89, v90
	v_max3_f32 v254, v254, v75, v76
	v_max3_f32 v255, v255, v91, v92
	v_max3_f32 v254, v254, v77, v78
	v_max3_f32 v255, v255, v93, v94
	v_max3_f32 v254, v254, v79, v95
	v_max_f32_e32 v254, v254, v255
	v_mov_b32_e32 v255, v254
	s_nop 1
	v_permlane32_swap_b32_e32 v254, v255
	v_max_f32_e32 v254, v254, v255
	v_add_f32_e32 v180, 0x4138aa3b, v175
	v_cmp_gt_f32_e32 vcc, v254, v180
	s_nop 1
	v_cndmask_b32_e32 v180, v175, v254, vcc
	v_sub_f32_e32 v255, v175, v180
	v_exp_f32_e32 v174, v255
	v_mov_b32_e32 v175, v180
	v_sub_f32_e32 v64, v64, v175
	v_sub_f32_e32 v65, v65, v175
	v_sub_f32_e32 v66, v66, v175
	v_sub_f32_e32 v67, v67, v175
	v_sub_f32_e32 v68, v68, v175
	v_sub_f32_e32 v69, v69, v175
	v_sub_f32_e32 v70, v70, v175
	v_sub_f32_e32 v71, v71, v175
	v_exp_f32_e32 v64, v64
	v_exp_f32_e32 v65, v65
	v_exp_f32_e32 v66, v66
	v_exp_f32_e32 v67, v67
	v_exp_f32_e32 v68, v68
	v_exp_f32_e32 v69, v69
	v_exp_f32_e32 v70, v70
	v_exp_f32_e32 v71, v71
	v_add_f32_e32 v190, v64, v65
	v_add_f32_e32 v191, v66, v67
	v_add_f32_e32 v190, v190, v68
	v_add_f32_e32 v191, v191, v69
	v_add_f32_e32 v190, v190, v70
	v_add_f32_e32 v191, v191, v71
	v_cvt_pk_bf16_f32 v144, v64, v65
	v_cvt_pk_bf16_f32 v145, v66, v67
	v_cvt_pk_bf16_f32 v146, v68, v69
	v_cvt_pk_bf16_f32 v147, v70, v71
	v_sub_f32_e32 v72, v72, v175
	v_sub_f32_e32 v73, v73, v175
	v_sub_f32_e32 v74, v74, v175
	v_sub_f32_e32 v75, v75, v175
	v_sub_f32_e32 v76, v76, v175
	v_sub_f32_e32 v77, v77, v175
	v_sub_f32_e32 v78, v78, v175
	v_sub_f32_e32 v79, v79, v175
	v_exp_f32_e32 v72, v72
	v_exp_f32_e32 v73, v73
	v_exp_f32_e32 v74, v74
	v_exp_f32_e32 v75, v75
	v_exp_f32_e32 v76, v76
	v_exp_f32_e32 v77, v77
	v_exp_f32_e32 v78, v78
	v_exp_f32_e32 v79, v79
	v_add_f32_e32 v190, v190, v72
	v_add_f32_e32 v191, v191, v73
	v_add_f32_e32 v190, v190, v74
	v_add_f32_e32 v191, v191, v75
	v_add_f32_e32 v190, v190, v76
	v_add_f32_e32 v191, v191, v77
	v_add_f32_e32 v190, v190, v78
	v_add_f32_e32 v191, v191, v79
	v_cvt_pk_bf16_f32 v148, v72, v73
	v_cvt_pk_bf16_f32 v149, v74, v75
	v_cvt_pk_bf16_f32 v150, v76, v77
	v_cvt_pk_bf16_f32 v151, v78, v79
	v_sub_f32_e32 v80, v80, v175
	v_sub_f32_e32 v81, v81, v175
	v_sub_f32_e32 v82, v82, v175
	v_sub_f32_e32 v83, v83, v175
	v_sub_f32_e32 v84, v84, v175
	v_sub_f32_e32 v85, v85, v175
	v_sub_f32_e32 v86, v86, v175
	v_sub_f32_e32 v87, v87, v175
	v_exp_f32_e32 v80, v80
	v_exp_f32_e32 v81, v81
	v_exp_f32_e32 v82, v82
	v_exp_f32_e32 v83, v83
	v_exp_f32_e32 v84, v84
	v_exp_f32_e32 v85, v85
	v_exp_f32_e32 v86, v86
	v_exp_f32_e32 v87, v87
	v_add_f32_e32 v190, v190, v80
	v_add_f32_e32 v191, v191, v81
	v_add_f32_e32 v190, v190, v82
	v_add_f32_e32 v191, v191, v83
	v_add_f32_e32 v190, v190, v84
	v_add_f32_e32 v191, v191, v85
	v_add_f32_e32 v190, v190, v86
	v_add_f32_e32 v191, v191, v87
	v_cvt_pk_bf16_f32 v152, v80, v81
	v_cvt_pk_bf16_f32 v153, v82, v83
	v_cvt_pk_bf16_f32 v154, v84, v85
	v_cvt_pk_bf16_f32 v155, v86, v87
	v_sub_f32_e32 v88, v88, v175
	v_sub_f32_e32 v89, v89, v175
	v_sub_f32_e32 v90, v90, v175
	v_sub_f32_e32 v91, v91, v175
	v_sub_f32_e32 v92, v92, v175
	v_sub_f32_e32 v93, v93, v175
	v_sub_f32_e32 v94, v94, v175
	v_sub_f32_e32 v95, v95, v175
	v_exp_f32_e32 v88, v88
	v_exp_f32_e32 v89, v89
	v_exp_f32_e32 v90, v90
	v_exp_f32_e32 v91, v91
	v_exp_f32_e32 v92, v92
	v_exp_f32_e32 v93, v93
	v_exp_f32_e32 v94, v94
	v_exp_f32_e32 v95, v95
	v_add_f32_e32 v190, v190, v88
	v_add_f32_e32 v191, v191, v89
	v_add_f32_e32 v190, v190, v90
	v_add_f32_e32 v191, v191, v91
	v_add_f32_e32 v190, v190, v92
	v_add_f32_e32 v191, v191, v93
	v_add_f32_e32 v190, v190, v94
	v_add_f32_e32 v191, v191, v95
	v_cvt_pk_bf16_f32 v156, v88, v89
	v_cvt_pk_bf16_f32 v157, v90, v91
	v_cvt_pk_bf16_f32 v158, v92, v93
	v_cvt_pk_bf16_f32 v159, v94, v95
	v_add_f32_e32 v190, v190, v191
	v_fma_f32 v167, v167, v174, v190
	s_cbranch_vccz .Lattn_noresc_L3_A
	s_nop 7
	s_nop 7
	v_pk_mul_f32 v[0:1], v[0:1], v[174:175] op_sel_hi:[1,0]
	v_pk_mul_f32 v[2:3], v[2:3], v[174:175] op_sel_hi:[1,0]
	v_pk_mul_f32 v[4:5], v[4:5], v[174:175] op_sel_hi:[1,0]
	v_pk_mul_f32 v[6:7], v[6:7], v[174:175] op_sel_hi:[1,0]
	v_pk_mul_f32 v[8:9], v[8:9], v[174:175] op_sel_hi:[1,0]
	v_pk_mul_f32 v[10:11], v[10:11], v[174:175] op_sel_hi:[1,0]
	v_pk_mul_f32 v[12:13], v[12:13], v[174:175] op_sel_hi:[1,0]
	v_pk_mul_f32 v[14:15], v[14:15], v[174:175] op_sel_hi:[1,0]
	v_pk_mul_f32 v[16:17], v[16:17], v[174:175] op_sel_hi:[1,0]
	v_pk_mul_f32 v[18:19], v[18:19], v[174:175] op_sel_hi:[1,0]
	v_pk_mul_f32 v[20:21], v[20:21], v[174:175] op_sel_hi:[1,0]
	v_pk_mul_f32 v[22:23], v[22:23], v[174:175] op_sel_hi:[1,0]
	v_pk_mul_f32 v[24:25], v[24:25], v[174:175] op_sel_hi:[1,0]
	v_pk_mul_f32 v[26:27], v[26:27], v[174:175] op_sel_hi:[1,0]
	v_pk_mul_f32 v[28:29], v[28:29], v[174:175] op_sel_hi:[1,0]
	v_pk_mul_f32 v[30:31], v[30:31], v[174:175] op_sel_hi:[1,0]
	v_pk_mul_f32 v[32:33], v[32:33], v[174:175] op_sel_hi:[1,0]
	v_pk_mul_f32 v[34:35], v[34:35], v[174:175] op_sel_hi:[1,0]
	v_pk_mul_f32 v[36:37], v[36:37], v[174:175] op_sel_hi:[1,0]
	v_pk_mul_f32 v[38:39], v[38:39], v[174:175] op_sel_hi:[1,0]
	v_pk_mul_f32 v[40:41], v[40:41], v[174:175] op_sel_hi:[1,0]
	v_pk_mul_f32 v[42:43], v[42:43], v[174:175] op_sel_hi:[1,0]
	v_pk_mul_f32 v[44:45], v[44:45], v[174:175] op_sel_hi:[1,0]
	v_pk_mul_f32 v[46:47], v[46:47], v[174:175] op_sel_hi:[1,0]
	v_pk_mul_f32 v[48:49], v[48:49], v[174:175] op_sel_hi:[1,0]
	v_pk_mul_f32 v[50:51], v[50:51], v[174:175] op_sel_hi:[1,0]
	v_pk_mul_f32 v[52:53], v[52:53], v[174:175] op_sel_hi:[1,0]
	v_pk_mul_f32 v[54:55], v[54:55], v[174:175] op_sel_hi:[1,0]
	v_pk_mul_f32 v[56:57], v[56:57], v[174:175] op_sel_hi:[1,0]
	v_pk_mul_f32 v[58:59], v[58:59], v[174:175] op_sel_hi:[1,0]
	v_pk_mul_f32 v[60:61], v[60:61], v[174:175] op_sel_hi:[1,0]
	v_pk_mul_f32 v[62:63], v[62:63], v[174:175] op_sel_hi:[1,0]
	s_nop 1

.Lattn_tb27_A:
	s_waitcnt lgkmcnt(5)
	v_mfma_f32_32x32x16_bf16 v[48:63], v[216:219], v[144:147], v[48:63]
	ds_read_b128 v[216:219], v188 offset:8192
	s_add_i32 s2, s42, 2
	s_waitcnt lgkmcnt(5)
	v_mfma_f32_32x32x16_bf16 v[32:47], v[220:223], v[144:147], v[32:47]
	ds_read_b128 v[220:223], v188 offset:12288
	s_and_b32 s2, s2, 31
	s_waitcnt lgkmcnt(5)
	v_mfma_f32_32x32x16_bf16 v[16:31], v[224:227], v[144:147], v[16:31]
	ds_read_b128 v[224:227], v186 offset:0
	s_lshl_b32 s2, s2, 7
	s_waitcnt lgkmcnt(5)
	v_mfma_f32_32x32x16_bf16 v[0:15], v[228:231], v[144:147], v[0:15]
	ds_read_b128 v[228:231], v186 offset:4096
	s_add_u32 s52, s10, s2
	s_waitcnt lgkmcnt(5)
	v_mfma_f32_32x32x16_bf16 v[48:63], v[208:211], v[148:151], v[48:63]
	ds_read_b128 v[208:211], v186 offset:8192
	s_addc_u32 s53, s11, 0
	s_waitcnt lgkmcnt(5)
	v_mfma_f32_32x32x16_bf16 v[32:47], v[212:215], v[148:151], v[32:47]
	ds_read_b128 v[212:215], v186 offset:12288
	s_add_u32 s54, s52, 0x204000
	s_waitcnt lgkmcnt(5)
	v_mfma_f32_32x32x16_bf16 v[16:31], v[216:219], v[148:151], v[16:31]
	ds_read_b128 v[216:219], v189 offset:0
	s_addc_u32 s55, s53, 0
	s_waitcnt lgkmcnt(5)
	v_mfma_f32_32x32x16_bf16 v[0:15], v[220:223], v[148:151], v[0:15]
	ds_read_b128 v[220:223], v189 offset:4096
	s_waitcnt lgkmcnt(5)
	v_mfma_f32_32x32x16_bf16 v[48:63], v[224:227], v[152:155], v[48:63]
	ds_read_b128 v[224:227], v189 offset:8192
	s_waitcnt lgkmcnt(5)
	v_mfma_f32_32x32x16_bf16 v[32:47], v[228:231], v[152:155], v[32:47]
	ds_read_b128 v[228:231], v189 offset:12288
	s_waitcnt lgkmcnt(5)
	v_mfma_f32_32x32x16_bf16 v[16:31], v[208:211], v[152:155], v[16:31]
	ds_read_b128 v[208:211], v182 offset:32768
	s_waitcnt lgkmcnt(5)
	v_mfma_f32_32x32x16_bf16 v[0:15], v[212:215], v[152:155], v[0:15]
	ds_read_b128 v[212:215], v182 offset:36864
	s_waitcnt lgkmcnt(5)
	v_mfma_f32_32x32x16_bf16 v[48:63], v[216:219], v[156:159], v[48:63]
	ds_read_b128 v[216:219], v183 offset:32768
	s_waitcnt lgkmcnt(5)
	v_mfma_f32_32x32x16_bf16 v[32:47], v[220:223], v[156:159], v[32:47]
	ds_read_b128 v[220:223], v183 offset:36864
	s_waitcnt lgkmcnt(5)
	v_mfma_f32_32x32x16_bf16 v[16:31], v[224:227], v[156:159], v[16:31]
	ds_read_b128 v[224:227], v184 offset:32768
	s_waitcnt lgkmcnt(5)
	v_mfma_f32_32x32x16_bf16 v[0:15], v[228:231], v[156:159], v[0:15]
	ds_read_b128 v[228:231], v184 offset:36864
	s_waitcnt lgkmcnt(5)
	v_mfma_f32_32x32x16_bf16 v[64:79], v[208:211], v[128:131], 0
	ds_read_b128 v[208:211], v185 offset:32768
	s_waitcnt lgkmcnt(5)
	v_mfma_f32_32x32x16_bf16 v[80:95], v[212:215], v[128:131], 0
	ds_read_b128 v[212:215], v185 offset:36864
	s_waitcnt lgkmcnt(5)
	v_mfma_f32_32x32x16_bf16 v[64:79], v[216:219], v[132:135], v[64:79]
	s_waitcnt lgkmcnt(4)
	v_mfma_f32_32x32x16_bf16 v[80:95], v[220:223], v[132:135], v[80:95]
	s_waitcnt lgkmcnt(3)
	v_mfma_f32_32x32x16_bf16 v[64:79], v[224:227], v[136:139], v[64:79]
	s_waitcnt lgkmcnt(2)
	v_mfma_f32_32x32x16_bf16 v[80:95], v[228:231], v[136:139], v[80:95]
	s_waitcnt lgkmcnt(1)
	v_mfma_f32_32x32x16_bf16 v[64:79], v[208:211], v[140:143], v[64:79]
	s_waitcnt lgkmcnt(0)
	v_mfma_f32_32x32x16_bf16 v[80:95], v[212:215], v[140:143], v[80:95]
	ds_read_b128 v[216:219], v187 offset:16384
	ds_read_b128 v[220:223], v187 offset:20480
	ds_read_b128 v[224:227], v187 offset:24576
	ds_read_b128 v[228:231], v187 offset:28672
	ds_read_b128 v[208:211], v188 offset:16384
	ds_read_b128 v[212:215], v188 offset:20480
	v_max3_f32 v254, v96, v97, v98
	s_add_i32 m0, s5, 114688
	v_max3_f32 v255, v112, v113, v114
	global_load_lds_dwordx4 v172, s[52:53]
	v_max3_f32 v254, v254, v99, v100
	s_add_i32 m0, s5, 122880
	v_max3_f32 v255, v255, v115, v116
	global_load_lds_dwordx4 v172, s[54:55]
	v_max3_f32 v254, v254, v101, v102
	v_max3_f32 v255, v255, v117, v118
	v_max3_f32 v254, v254, v103, v104
	v_max3_f32 v255, v255, v119, v120
	v_max3_f32 v254, v254, v105, v106
	v_max3_f32 v255, v255, v121, v122
	v_max3_f32 v254, v254, v107, v108
	v_max3_f32 v255, v255, v123, v124
	v_max3_f32 v254, v254, v109, v110
	v_max3_f32 v255, v255, v125, v126
	v_max3_f32 v254, v254, v111, v127
	v_max_f32_e32 v254, v254, v255
	v_mov_b32_e32 v255, v254
	s_nop 1
	v_permlane32_swap_b32_e32 v254, v255
	v_max_f32_e32 v254, v254, v255
	v_add_f32_e32 v180, 0x4138aa3b, v175
	v_cmp_gt_f32_e32 vcc, v254, v180
	s_nop 1
	v_cndmask_b32_e32 v180, v175, v254, vcc
	v_sub_f32_e32 v255, v175, v180
	v_exp_f32_e32 v174, v255
	v_mov_b32_e32 v175, v180
	v_sub_f32_e32 v96, v96, v175
	v_sub_f32_e32 v97, v97, v175
	v_sub_f32_e32 v98, v98, v175
	v_sub_f32_e32 v99, v99, v175
	v_sub_f32_e32 v100, v100, v175
	v_sub_f32_e32 v101, v101, v175
	v_sub_f32_e32 v102, v102, v175
	v_sub_f32_e32 v103, v103, v175
	v_exp_f32_e32 v96, v96
	v_exp_f32_e32 v97, v97
	v_exp_f32_e32 v98, v98
	v_exp_f32_e32 v99, v99
	v_exp_f32_e32 v100, v100
	v_exp_f32_e32 v101, v101
	v_exp_f32_e32 v102, v102
	v_exp_f32_e32 v103, v103
	v_add_f32_e32 v190, v96, v97
	v_add_f32_e32 v191, v98, v99
	v_add_f32_e32 v190, v190, v100
	v_add_f32_e32 v191, v191, v101
	v_add_f32_e32 v190, v190, v102
	v_add_f32_e32 v191, v191, v103
	v_cvt_pk_bf16_f32 v144, v96, v97
	v_cvt_pk_bf16_f32 v145, v98, v99
	v_cvt_pk_bf16_f32 v146, v100, v101
	v_cvt_pk_bf16_f32 v147, v102, v103
	v_sub_f32_e32 v104, v104, v175
	v_sub_f32_e32 v105, v105, v175
	v_sub_f32_e32 v106, v106, v175
	v_sub_f32_e32 v107, v107, v175
	v_sub_f32_e32 v108, v108, v175
	v_sub_f32_e32 v109, v109, v175
	v_sub_f32_e32 v110, v110, v175
	v_sub_f32_e32 v111, v111, v175
	v_exp_f32_e32 v104, v104
	v_exp_f32_e32 v105, v105
	v_exp_f32_e32 v106, v106
	v_exp_f32_e32 v107, v107
	v_exp_f32_e32 v108, v108
	v_exp_f32_e32 v109, v109
	v_exp_f32_e32 v110, v110
	v_exp_f32_e32 v111, v111
	v_add_f32_e32 v190, v190, v104
	v_add_f32_e32 v191, v191, v105
	v_add_f32_e32 v190, v190, v106
	v_add_f32_e32 v191, v191, v107
	v_add_f32_e32 v190, v190, v108
	v_add_f32_e32 v191, v191, v109
	v_add_f32_e32 v190, v190, v110
	v_add_f32_e32 v191, v191, v111
	v_cvt_pk_bf16_f32 v148, v104, v105
	v_cvt_pk_bf16_f32 v149, v106, v107
	v_cvt_pk_bf16_f32 v150, v108, v109
	v_cvt_pk_bf16_f32 v151, v110, v111
	v_sub_f32_e32 v112, v112, v175
	v_sub_f32_e32 v113, v113, v175
	v_sub_f32_e32 v114, v114, v175
	v_sub_f32_e32 v115, v115, v175
	v_sub_f32_e32 v116, v116, v175
	v_sub_f32_e32 v117, v117, v175
	v_sub_f32_e32 v118, v118, v175
	v_sub_f32_e32 v119, v119, v175
	v_exp_f32_e32 v112, v112
	v_exp_f32_e32 v113, v113
	v_exp_f32_e32 v114, v114
	v_exp_f32_e32 v115, v115
	v_exp_f32_e32 v116, v116
	v_exp_f32_e32 v117, v117
	v_exp_f32_e32 v118, v118
	v_exp_f32_e32 v119, v119
	v_add_f32_e32 v190, v190, v112
	v_add_f32_e32 v191, v191, v113
	v_add_f32_e32 v190, v190, v114
	v_add_f32_e32 v191, v191, v115
	v_add_f32_e32 v190, v190, v116
	v_add_f32_e32 v191, v191, v117
	v_add_f32_e32 v190, v190, v118
	v_add_f32_e32 v191, v191, v119
	v_cvt_pk_bf16_f32 v152, v112, v113
	v_cvt_pk_bf16_f32 v153, v114, v115
	v_cvt_pk_bf16_f32 v154, v116, v117
	v_cvt_pk_bf16_f32 v155, v118, v119
	v_sub_f32_e32 v120, v120, v175
	v_sub_f32_e32 v121, v121, v175
	v_sub_f32_e32 v122, v122, v175
	v_sub_f32_e32 v123, v123, v175
	v_sub_f32_e32 v124, v124, v175
	v_sub_f32_e32 v125, v125, v175
	v_sub_f32_e32 v126, v126, v175
	v_sub_f32_e32 v127, v127, v175
	v_exp_f32_e32 v120, v120
	v_exp_f32_e32 v121, v121
	v_exp_f32_e32 v122, v122
	v_exp_f32_e32 v123, v123
	v_exp_f32_e32 v124, v124
	v_exp_f32_e32 v125, v125
	v_exp_f32_e32 v126, v126
	v_exp_f32_e32 v127, v127
	v_add_f32_e32 v190, v190, v120
	v_add_f32_e32 v191, v191, v121
	v_add_f32_e32 v190, v190, v122
	v_add_f32_e32 v191, v191, v123
	v_add_f32_e32 v190, v190, v124
	v_add_f32_e32 v191, v191, v125
	v_add_f32_e32 v190, v190, v126
	v_add_f32_e32 v191, v191, v127
	v_cvt_pk_bf16_f32 v156, v120, v121
	v_cvt_pk_bf16_f32 v157, v122, v123
	v_cvt_pk_bf16_f32 v158, v124, v125
	v_cvt_pk_bf16_f32 v159, v126, v127
	v_add_f32_e32 v190, v190, v191
	v_fma_f32 v167, v167, v174, v190
	s_cbranch_vccz .Lattn_noresc_T29_A
	s_nop 7
	s_nop 7
	v_pk_mul_f32 v[0:1], v[0:1], v[174:175] op_sel_hi:[1,0]
	v_pk_mul_f32 v[2:3], v[2:3], v[174:175] op_sel_hi:[1,0]
	v_pk_mul_f32 v[4:5], v[4:5], v[174:175] op_sel_hi:[1,0]
	v_pk_mul_f32 v[6:7], v[6:7], v[174:175] op_sel_hi:[1,0]
	v_pk_mul_f32 v[8:9], v[8:9], v[174:175] op_sel_hi:[1,0]
	v_pk_mul_f32 v[10:11], v[10:11], v[174:175] op_sel_hi:[1,0]
	v_pk_mul_f32 v[12:13], v[12:13], v[174:175] op_sel_hi:[1,0]
	v_pk_mul_f32 v[14:15], v[14:15], v[174:175] op_sel_hi:[1,0]
	v_pk_mul_f32 v[16:17], v[16:17], v[174:175] op_sel_hi:[1,0]
	v_pk_mul_f32 v[18:19], v[18:19], v[174:175] op_sel_hi:[1,0]
	v_pk_mul_f32 v[20:21], v[20:21], v[174:175] op_sel_hi:[1,0]
	v_pk_mul_f32 v[22:23], v[22:23], v[174:175] op_sel_hi:[1,0]
	v_pk_mul_f32 v[24:25], v[24:25], v[174:175] op_sel_hi:[1,0]
	v_pk_mul_f32 v[26:27], v[26:27], v[174:175] op_sel_hi:[1,0]
	v_pk_mul_f32 v[28:29], v[28:29], v[174:175] op_sel_hi:[1,0]
	v_pk_mul_f32 v[30:31], v[30:31], v[174:175] op_sel_hi:[1,0]
	v_pk_mul_f32 v[32:33], v[32:33], v[174:175] op_sel_hi:[1,0]
	v_pk_mul_f32 v[34:35], v[34:35], v[174:175] op_sel_hi:[1,0]
	v_pk_mul_f32 v[36:37], v[36:37], v[174:175] op_sel_hi:[1,0]
	v_pk_mul_f32 v[38:39], v[38:39], v[174:175] op_sel_hi:[1,0]
	v_pk_mul_f32 v[40:41], v[40:41], v[174:175] op_sel_hi:[1,0]
	v_pk_mul_f32 v[42:43], v[42:43], v[174:175] op_sel_hi:[1,0]
	v_pk_mul_f32 v[44:45], v[44:45], v[174:175] op_sel_hi:[1,0]
	v_pk_mul_f32 v[46:47], v[46:47], v[174:175] op_sel_hi:[1,0]
	v_pk_mul_f32 v[48:49], v[48:49], v[174:175] op_sel_hi:[1,0]
	v_pk_mul_f32 v[50:51], v[50:51], v[174:175] op_sel_hi:[1,0]
	v_pk_mul_f32 v[52:53], v[52:53], v[174:175] op_sel_hi:[1,0]
	v_pk_mul_f32 v[54:55], v[54:55], v[174:175] op_sel_hi:[1,0]
	v_pk_mul_f32 v[56:57], v[56:57], v[174:175] op_sel_hi:[1,0]
	v_pk_mul_f32 v[58:59], v[58:59], v[174:175] op_sel_hi:[1,0]
	v_pk_mul_f32 v[60:61], v[60:61], v[174:175] op_sel_hi:[1,0]
	v_pk_mul_f32 v[62:63], v[62:63], v[174:175] op_sel_hi:[1,0]
	s_nop 1
.Lattn_noresc_T29_A:
.Lattn_top_T30_A:
	s_waitcnt vmcnt(2)
	s_barrier
.Lattn_tb29_A:
	s_waitcnt lgkmcnt(5)
	v_mfma_f32_32x32x16_bf16 v[48:63], v[216:219], v[144:147], v[48:63]
	ds_read_b128 v[216:219], v188 offset:24576
	s_waitcnt lgkmcnt(5)
	v_mfma_f32_32x32x16_bf16 v[32:47], v[220:223], v[144:147], v[32:47]
	ds_read_b128 v[220:223], v188 offset:28672
	s_waitcnt lgkmcnt(5)
	v_mfma_f32_32x32x16_bf16 v[16:31], v[224:227], v[144:147], v[16:31]
	ds_read_b128 v[224:227], v186 offset:16384
	s_waitcnt lgkmcnt(5)
	v_mfma_f32_32x32x16_bf16 v[0:15], v[228:231], v[144:147], v[0:15]
	ds_read_b128 v[228:231], v186 offset:20480
	s_waitcnt lgkmcnt(5)
	v_mfma_f32_32x32x16_bf16 v[48:63], v[208:211], v[148:151], v[48:63]
	ds_read_b128 v[208:211], v186 offset:24576
	s_waitcnt lgkmcnt(5)
	v_mfma_f32_32x32x16_bf16 v[32:47], v[212:215], v[148:151], v[32:47]
	ds_read_b128 v[212:215], v186 offset:28672
	s_waitcnt lgkmcnt(5)
	v_mfma_f32_32x32x16_bf16 v[16:31], v[216:219], v[148:151], v[16:31]
	ds_read_b128 v[216:219], v189 offset:16384
	s_waitcnt lgkmcnt(5)
	v_mfma_f32_32x32x16_bf16 v[0:15], v[220:223], v[148:151], v[0:15]
	ds_read_b128 v[220:223], v189 offset:20480
	s_waitcnt lgkmcnt(5)
	v_mfma_f32_32x32x16_bf16 v[48:63], v[224:227], v[152:155], v[48:63]
	ds_read_b128 v[224:227], v189 offset:24576
	s_waitcnt lgkmcnt(5)
	v_mfma_f32_32x32x16_bf16 v[32:47], v[228:231], v[152:155], v[32:47]
	ds_read_b128 v[228:231], v189 offset:28672
	s_waitcnt lgkmcnt(5)
	v_mfma_f32_32x32x16_bf16 v[16:31], v[208:211], v[152:155], v[16:31]
	ds_read_b128 v[208:211], v182 offset:49152
	s_waitcnt lgkmcnt(5)
	v_mfma_f32_32x32x16_bf16 v[0:15], v[212:215], v[152:155], v[0:15]
	ds_read_b128 v[212:215], v182 offset:53248
	s_waitcnt lgkmcnt(5)
	v_mfma_f32_32x32x16_bf16 v[48:63], v[216:219], v[156:159], v[48:63]
	ds_read_b128 v[216:219], v183 offset:49152
	s_waitcnt lgkmcnt(5)
	v_mfma_f32_32x32x16_bf16 v[32:47], v[220:223], v[156:159], v[32:47]
	ds_read_b128 v[220:223], v183 offset:53248
	s_waitcnt lgkmcnt(5)
	v_mfma_f32_32x32x16_bf16 v[16:31], v[224:227], v[156:159], v[16:31]
	ds_read_b128 v[224:227], v184 offset:49152
	s_waitcnt lgkmcnt(5)
	v_mfma_f32_32x32x16_bf16 v[0:15], v[228:231], v[156:159], v[0:15]
	ds_read_b128 v[228:231], v184 offset:53248
	s_waitcnt lgkmcnt(5)
	v_mfma_f32_32x32x16_bf16 v[96:111], v[208:211], v[128:131], 0
	ds_read_b128 v[208:211], v185 offset:49152
	s_waitcnt lgkmcnt(5)
	v_mfma_f32_32x32x16_bf16 v[112:127], v[212:215], v[128:131], 0
	ds_read_b128 v[212:215], v185 offset:53248
	s_waitcnt lgkmcnt(5)
	v_mfma_f32_32x32x16_bf16 v[96:111], v[216:219], v[132:135], v[96:111]
	s_waitcnt lgkmcnt(4)
	v_mfma_f32_32x32x16_bf16 v[112:127], v[220:223], v[132:135], v[112:127]
	s_waitcnt lgkmcnt(3)
	v_mfma_f32_32x32x16_bf16 v[96:111], v[224:227], v[136:139], v[96:111]
	s_waitcnt lgkmcnt(2)
	v_mfma_f32_32x32x16_bf16 v[112:127], v[228:231], v[136:139], v[112:127]
	s_waitcnt lgkmcnt(1)
	v_mfma_f32_32x32x16_bf16 v[96:111], v[208:211], v[140:143], v[96:111]
	s_waitcnt lgkmcnt(0)
	v_mfma_f32_32x32x16_bf16 v[112:127], v[212:215], v[140:143], v[112:127]
	ds_read_b128 v[216:219], v187 offset:32768
	ds_read_b128 v[220:223], v187 offset:36864
	ds_read_b128 v[224:227], v187 offset:40960
	ds_read_b128 v[228:231], v187 offset:45056
	ds_read_b128 v[208:211], v188 offset:32768
	ds_read_b128 v[212:215], v188 offset:36864
	v_max3_f32 v254, v64, v65, v66
	v_readlane_b32 s2, v253, 52
	s_add_i32 s36, s46, 1
	s_mul_i32 s36, s36, s56
	s_add_i32 s36, s36, s0
	s_cmp_lg_u32 s2, 0
	s_cselect_b32 s2, 1, 0
	s_cmpk_lt_i32 s36, 0x400
	s_cselect_b32 s36, 1, 0
	s_and_b32 s35, s2, s36
	v_max3_f32 v255, v80, v81, v82
	s_cmp_lg_u32 s35, 0
	s_cbranch_scc0 .Lattn_pfka_s_A
	s_add_i32 s2, s31, 0
	s_and_b32 s2, s2, 31
	s_mul_i32 s2, s2, 0x44000
	s_add_i32 m0, s5, 0
	s_add_u32 s40, s26, s2
	s_addc_u32 s41, s27, 0
	s_add_u32 s40, s40, 0x1100000
	s_addc_u32 s41, s41, 0
	global_load_lds_dwordx4 v170, s[40:41]
	s_add_i32 m0, s5, 8192
	s_add_u32 s40, s40, 0x80
	s_addc_u32 s41, s41, 0
	global_load_lds_dwordx4 v170, s[40:41]

.Lattn_tb31_A:
	s_waitcnt lgkmcnt(5)
	v_mfma_f32_32x32x16_bf16 v[48:63], v[216:219], v[144:147], v[48:63]
	ds_read_b128 v[216:219], v188 offset:40960
	s_waitcnt lgkmcnt(5)
	v_mfma_f32_32x32x16_bf16 v[32:47], v[220:223], v[144:147], v[32:47]
	ds_read_b128 v[220:223], v188 offset:45056
	s_waitcnt lgkmcnt(5)
	v_mfma_f32_32x32x16_bf16 v[16:31], v[224:227], v[144:147], v[16:31]
	ds_read_b128 v[224:227], v186 offset:32768
	s_waitcnt lgkmcnt(5)
	v_mfma_f32_32x32x16_bf16 v[0:15], v[228:231], v[144:147], v[0:15]
	ds_read_b128 v[228:231], v186 offset:36864
	s_waitcnt lgkmcnt(5)
	v_mfma_f32_32x32x16_bf16 v[48:63], v[208:211], v[148:151], v[48:63]
	ds_read_b128 v[208:211], v186 offset:40960
	s_waitcnt lgkmcnt(5)
	v_mfma_f32_32x32x16_bf16 v[32:47], v[212:215], v[148:151], v[32:47]
	ds_read_b128 v[212:215], v186 offset:45056
	s_waitcnt lgkmcnt(5)
	v_mfma_f32_32x32x16_bf16 v[16:31], v[216:219], v[148:151], v[16:31]
	ds_read_b128 v[216:219], v189 offset:32768
	s_waitcnt lgkmcnt(5)
	v_mfma_f32_32x32x16_bf16 v[0:15], v[220:223], v[148:151], v[0:15]
	ds_read_b128 v[220:223], v189 offset:36864
	s_waitcnt lgkmcnt(5)
	v_mfma_f32_32x32x16_bf16 v[48:63], v[224:227], v[152:155], v[48:63]
	ds_read_b128 v[224:227], v189 offset:40960
	s_waitcnt lgkmcnt(5)
	v_mfma_f32_32x32x16_bf16 v[32:47], v[228:231], v[152:155], v[32:47]
	ds_read_b128 v[228:231], v189 offset:45056
	s_waitcnt lgkmcnt(5)
	v_mfma_f32_32x32x16_bf16 v[16:31], v[208:211], v[152:155], v[16:31]
	s_waitcnt lgkmcnt(4)
	v_mfma_f32_32x32x16_bf16 v[0:15], v[212:215], v[152:155], v[0:15]
	s_waitcnt lgkmcnt(3)
	v_mfma_f32_32x32x16_bf16 v[48:63], v[216:219], v[156:159], v[48:63]
	s_waitcnt lgkmcnt(2)
	v_mfma_f32_32x32x16_bf16 v[32:47], v[220:223], v[156:159], v[32:47]
	s_waitcnt lgkmcnt(1)
	v_mfma_f32_32x32x16_bf16 v[16:31], v[224:227], v[156:159], v[16:31]
	s_waitcnt lgkmcnt(0)
	v_mfma_f32_32x32x16_bf16 v[0:15], v[228:231], v[156:159], v[0:15]
	ds_read_b128 v[208:211], v187 offset:49152
	ds_read_b128 v[212:215], v187 offset:53248
	ds_read_b128 v[216:219], v187 offset:57344
	ds_read_b128 v[220:223], v187 offset:61440
	ds_read_b128 v[224:227], v188 offset:49152
	ds_read_b128 v[228:231], v188 offset:53248
	v_max3_f32 v254, v96, v97, v98
	s_cmp_lg_u32 s35, 0
	s_cbranch_scc0 .Lattn_pfq_s_A
	s_movk_i32 s2, 0x1100
	s_lshl_b32 s36, s14, 1
	v_mad_u32_u24 v72, v168, s2, v192
	s_add_i32 s36, s36, s30
	s_add_i32 s36, s36, 0x1100000
	s_nop 0
	v_add_u32_e32 v72, s36, v72
	s_nop 0
	global_load_dwordx4 v[64:67], v72, s[6:7]
	global_load_dwordx4 v[68:71], v72, s[6:7] offset:32
	global_load_dwordx4 v[136:139], v72, s[6:7] offset:64
	global_load_dwordx4 v[140:143], v72, s[6:7] offset:96

.Lattn_bodyB:
	s_waitcnt lgkmcnt(5)
	v_mfma_f32_32x32x16_bf16 v[96:111], v[208:211], v[128:131], 0
	ds_read_b128 v[208:211], v185 offset:16384
	s_add_i32 s2, s42, 4
	s_and_b32 s2, s2, 31
	s_waitcnt lgkmcnt(5)
	v_mfma_f32_32x32x16_bf16 v[112:127], v[212:215], v[128:131], 0
	ds_read_b128 v[212:215], v185 offset:20480
	s_mul_i32 s2, s2, 0x44000
	s_add_u32 s48, s26, s2
	s_waitcnt lgkmcnt(5)
	v_mfma_f32_32x32x16_bf16 v[96:111], v[216:219], v[132:135], v[96:111]
	s_addc_u32 s49, s27, 0
	s_add_u32 s50, s48, 0x80
	s_waitcnt lgkmcnt(4)
	v_mfma_f32_32x32x16_bf16 v[112:127], v[220:223], v[132:135], v[112:127]
	s_addc_u32 s51, s49, 0
	s_add_i32 s2, s42, 2
	s_waitcnt lgkmcnt(3)
	v_mfma_f32_32x32x16_bf16 v[96:111], v[224:227], v[136:139], v[96:111]
	s_and_b32 s2, s2, 31
	s_lshl_b32 s2, s2, 7
	s_waitcnt lgkmcnt(2)
	v_mfma_f32_32x32x16_bf16 v[112:127], v[228:231], v[136:139], v[112:127]
	s_add_u32 s52, s10, s2
	s_addc_u32 s53, s11, 0
	s_waitcnt lgkmcnt(1)
	v_mfma_f32_32x32x16_bf16 v[96:111], v[208:211], v[140:143], v[96:111]
	s_add_u32 s54, s52, 0x204000
	s_addc_u32 s55, s53, 0
	s_waitcnt lgkmcnt(0)
	v_mfma_f32_32x32x16_bf16 v[112:127], v[212:215], v[140:143], v[112:127]
	s_barrier

.Lattn_loop_f_B:
	s_waitcnt lgkmcnt(5)
	v_mfma_f32_32x32x16_bf16 v[48:63], v[216:219], v[144:147], v[48:63]
	ds_read_b128 v[216:219], v188 offset:8192
	s_add_i32 s2, s42, 4
	s_waitcnt lgkmcnt(5)
	v_mfma_f32_32x32x16_bf16 v[32:47], v[220:223], v[144:147], v[32:47]
	ds_read_b128 v[220:223], v188 offset:12288
	s_and_b32 s2, s2, 31
	s_waitcnt lgkmcnt(5)
	v_mfma_f32_32x32x16_bf16 v[16:31], v[224:227], v[144:147], v[16:31]
	ds_read_b128 v[224:227], v186 offset:0
	s_mul_i32 s2, s2, 0x44000
	s_waitcnt lgkmcnt(5)
	v_mfma_f32_32x32x16_bf16 v[0:15], v[228:231], v[144:147], v[0:15]
	ds_read_b128 v[228:231], v186 offset:4096
	s_add_u32 s48, s26, s2
	s_waitcnt lgkmcnt(5)
	v_mfma_f32_32x32x16_bf16 v[48:63], v[208:211], v[148:151], v[48:63]
	ds_read_b128 v[208:211], v186 offset:8192
	s_addc_u32 s49, s27, 0
	s_waitcnt lgkmcnt(5)
	v_mfma_f32_32x32x16_bf16 v[32:47], v[212:215], v[148:151], v[32:47]
	ds_read_b128 v[212:215], v186 offset:12288
	s_add_u32 s50, s48, 0x80
	s_waitcnt lgkmcnt(5)
	v_mfma_f32_32x32x16_bf16 v[16:31], v[216:219], v[148:151], v[16:31]
	ds_read_b128 v[216:219], v189 offset:0
	s_addc_u32 s51, s49, 0
	s_waitcnt lgkmcnt(5)
	v_mfma_f32_32x32x16_bf16 v[0:15], v[220:223], v[148:151], v[0:15]
	ds_read_b128 v[220:223], v189 offset:4096
	s_add_i32 s2, s42, 2
	s_waitcnt lgkmcnt(5)
	v_mfma_f32_32x32x16_bf16 v[48:63], v[224:227], v[152:155], v[48:63]
	ds_read_b128 v[224:227], v189 offset:8192
	s_and_b32 s2, s2, 31
	s_waitcnt lgkmcnt(5)
	v_mfma_f32_32x32x16_bf16 v[32:47], v[228:231], v[152:155], v[32:47]
	ds_read_b128 v[228:231], v189 offset:12288
	s_lshl_b32 s2, s2, 7
	s_waitcnt lgkmcnt(5)
	v_mfma_f32_32x32x16_bf16 v[16:31], v[208:211], v[152:155], v[16:31]
	ds_read_b128 v[208:211], v182 offset:32768
	s_add_u32 s52, s10, s2
	s_waitcnt lgkmcnt(5)
	v_mfma_f32_32x32x16_bf16 v[0:15], v[212:215], v[152:155], v[0:15]
	ds_read_b128 v[212:215], v182 offset:36864
	s_addc_u32 s53, s11, 0
	s_waitcnt lgkmcnt(5)
	v_mfma_f32_32x32x16_bf16 v[48:63], v[216:219], v[156:159], v[48:63]
	ds_read_b128 v[216:219], v183 offset:32768
	s_add_u32 s54, s52, 0x204000
	s_waitcnt lgkmcnt(5)
	v_mfma_f32_32x32x16_bf16 v[32:47], v[220:223], v[156:159], v[32:47]
	ds_read_b128 v[220:223], v183 offset:36864
	s_addc_u32 s55, s53, 0
	s_waitcnt lgkmcnt(5)
	v_mfma_f32_32x32x16_bf16 v[16:31], v[224:227], v[156:159], v[16:31]
	ds_read_b128 v[224:227], v184 offset:32768
	s_waitcnt lgkmcnt(5)
	v_mfma_f32_32x32x16_bf16 v[0:15], v[228:231], v[156:159], v[0:15]
	ds_read_b128 v[228:231], v184 offset:36864
	s_waitcnt lgkmcnt(5)
	v_mfma_f32_32x32x16_bf16 v[64:79], v[208:211], v[128:131], 0
	ds_read_b128 v[208:211], v185 offset:32768
	s_waitcnt lgkmcnt(5)
	v_mfma_f32_32x32x16_bf16 v[80:95], v[212:215], v[128:131], 0
	ds_read_b128 v[212:215], v185 offset:36864
	s_waitcnt lgkmcnt(5)
	v_mfma_f32_32x32x16_bf16 v[64:79], v[216:219], v[132:135], v[64:79]
	s_waitcnt lgkmcnt(4)
	v_mfma_f32_32x32x16_bf16 v[80:95], v[220:223], v[132:135], v[80:95]
	s_waitcnt lgkmcnt(3)
	v_mfma_f32_32x32x16_bf16 v[64:79], v[224:227], v[136:139], v[64:79]
	s_waitcnt lgkmcnt(2)
	v_mfma_f32_32x32x16_bf16 v[80:95], v[228:231], v[136:139], v[80:95]
	s_waitcnt lgkmcnt(1)
	v_mfma_f32_32x32x16_bf16 v[64:79], v[208:211], v[140:143], v[64:79]
	s_waitcnt lgkmcnt(0)
	v_mfma_f32_32x32x16_bf16 v[80:95], v[212:215], v[140:143], v[80:95]
	s_waitcnt vmcnt(4)
	s_barrier
.Lattn_tb36_B:
	ds_read_b128 v[216:219], v187 offset:16384
	ds_read_b128 v[220:223], v187 offset:20480
	ds_read_b128 v[224:227], v187 offset:24576
	ds_read_b128 v[228:231], v187 offset:28672
	ds_read_b128 v[208:211], v188 offset:16384
	ds_read_b128 v[212:215], v188 offset:20480
	v_exp_f32_e32 v171, v96
	v_exp_f32_e32 v173, v97
	v_exp_f32_e32 v179, v98
	s_add_i32 m0, s5, 16384
	v_exp_f32_e32 v180, v99
	v_exp_f32_e32 v232, v100
	v_exp_f32_e32 v233, v101
	global_load_lds_dwordx4 v170, s[48:49]
	v_exp_f32_e32 v234, v102
	v_exp_f32_e32 v235, v103
	v_add_f32_e32 v190, v171, v173
	s_add_i32 m0, s5, 24576
	v_add_f32_e32 v191, v179, v180
	v_add_f32_e32 v190, v190, v232
	v_add_f32_e32 v191, v191, v233
	global_load_lds_dwordx4 v170, s[50:51]
	v_add_f32_e32 v190, v190, v234
	v_add_f32_e32 v191, v191, v235
	v_cvt_pk_bf16_f32 v144, v171, v173
	s_add_i32 m0, s5, 114688
	v_cvt_pk_bf16_f32 v145, v179, v180
	v_cvt_pk_bf16_f32 v146, v232, v233
	v_cvt_pk_bf16_f32 v147, v234, v235
	global_load_lds_dwordx4 v172, s[52:53]
	v_exp_f32_e32 v171, v104
	v_exp_f32_e32 v173, v105
	v_exp_f32_e32 v179, v106
	s_add_i32 m0, s5, 122880
	v_exp_f32_e32 v180, v107
	v_exp_f32_e32 v232, v108
	v_exp_f32_e32 v233, v109
	global_load_lds_dwordx4 v172, s[54:55]
	v_exp_f32_e32 v234, v110
	v_exp_f32_e32 v235, v111
	v_add_f32_e32 v190, v190, v171
	v_add_f32_e32 v191, v191, v173
	v_add_f32_e32 v190, v190, v179
	v_add_f32_e32 v191, v191, v180
	v_add_f32_e32 v190, v190, v232
	v_add_f32_e32 v191, v191, v233
	v_add_f32_e32 v190, v190, v234
	v_add_f32_e32 v191, v191, v235
	v_cvt_pk_bf16_f32 v148, v171, v173
	v_cvt_pk_bf16_f32 v149, v179, v180
	v_cvt_pk_bf16_f32 v150, v232, v233
	v_cvt_pk_bf16_f32 v151, v234, v235
	v_exp_f32_e32 v171, v112
	v_exp_f32_e32 v173, v113
	v_exp_f32_e32 v179, v114
	v_exp_f32_e32 v180, v115
	v_exp_f32_e32 v232, v116
	v_exp_f32_e32 v233, v117
	v_exp_f32_e32 v234, v118
	v_exp_f32_e32 v235, v119
	v_add_f32_e32 v190, v190, v171
	v_add_f32_e32 v191, v191, v173
	v_add_f32_e32 v190, v190, v179
	v_add_f32_e32 v191, v191, v180
	v_add_f32_e32 v190, v190, v232
	v_add_f32_e32 v191, v191, v233
	v_add_f32_e32 v190, v190, v234
	v_add_f32_e32 v191, v191, v235
	v_cvt_pk_bf16_f32 v152, v171, v173
	v_cvt_pk_bf16_f32 v153, v179, v180
	v_cvt_pk_bf16_f32 v154, v232, v233
	v_cvt_pk_bf16_f32 v155, v234, v235
	v_exp_f32_e32 v171, v120
	v_exp_f32_e32 v173, v121
	v_exp_f32_e32 v179, v122
	v_exp_f32_e32 v180, v123
	v_exp_f32_e32 v232, v124
	v_exp_f32_e32 v233, v125
	v_exp_f32_e32 v234, v126
	v_exp_f32_e32 v235, v127
	v_add_f32_e32 v190, v190, v171
	v_add_f32_e32 v191, v191, v173
	v_add_f32_e32 v190, v190, v179
	v_add_f32_e32 v191, v191, v180
	v_add_f32_e32 v190, v190, v232
	v_add_f32_e32 v191, v191, v233
	v_add_f32_e32 v190, v190, v234
	v_add_f32_e32 v191, v191, v235
	v_add_f32_e32 v190, v190, v191
	v_cmp_ngt_f32_e32 vcc, 0x71800000, v190
	v_cvt_pk_bf16_f32 v156, v171, v173
	v_cvt_pk_bf16_f32 v157, v179, v180
	v_cvt_pk_bf16_f32 v158, v232, v233
	v_cvt_pk_bf16_f32 v159, v234, v235
	s_nop 0
	s_cbranch_vccnz .Lattn_redo_L0_B
	v_add_f32_e32 v167, v167, v190
	s_waitcnt lgkmcnt(5)
	v_mfma_f32_32x32x16_bf16 v[48:63], v[216:219], v[144:147], v[48:63]
	ds_read_b128 v[216:219], v188 offset:24576
	s_add_i32 s2, s42, 5
	s_waitcnt lgkmcnt(5)
	v_mfma_f32_32x32x16_bf16 v[32:47], v[220:223], v[144:147], v[32:47]
	ds_read_b128 v[220:223], v188 offset:28672
	s_and_b32 s2, s2, 31
	s_waitcnt lgkmcnt(5)
	v_mfma_f32_32x32x16_bf16 v[16:31], v[224:227], v[144:147], v[16:31]
	ds_read_b128 v[224:227], v186 offset:16384
	s_mul_i32 s2, s2, 0x44000
	s_waitcnt lgkmcnt(5)
	v_mfma_f32_32x32x16_bf16 v[0:15], v[228:231], v[144:147], v[0:15]
	ds_read_b128 v[228:231], v186 offset:20480
	s_add_u32 s48, s26, s2
	s_waitcnt lgkmcnt(5)
	v_mfma_f32_32x32x16_bf16 v[48:63], v[208:211], v[148:151], v[48:63]
	ds_read_b128 v[208:211], v186 offset:24576
	s_addc_u32 s49, s27, 0
	s_waitcnt lgkmcnt(5)
	v_mfma_f32_32x32x16_bf16 v[32:47], v[212:215], v[148:151], v[32:47]
	ds_read_b128 v[212:215], v186 offset:28672
	s_add_u32 s50, s48, 0x80
	s_waitcnt lgkmcnt(5)
	v_mfma_f32_32x32x16_bf16 v[16:31], v[216:219], v[148:151], v[16:31]
	ds_read_b128 v[216:219], v189 offset:16384
	s_addc_u32 s51, s49, 0
	s_waitcnt lgkmcnt(5)
	v_mfma_f32_32x32x16_bf16 v[0:15], v[220:223], v[148:151], v[0:15]
	ds_read_b128 v[220:223], v189 offset:20480
	s_add_i32 s2, s42, 3
	s_waitcnt lgkmcnt(5)
	v_mfma_f32_32x32x16_bf16 v[48:63], v[224:227], v[152:155], v[48:63]
	ds_read_b128 v[224:227], v189 offset:24576
	s_and_b32 s2, s2, 31
	s_waitcnt lgkmcnt(5)
	v_mfma_f32_32x32x16_bf16 v[32:47], v[228:231], v[152:155], v[32:47]
	ds_read_b128 v[228:231], v189 offset:28672
	s_lshl_b32 s2, s2, 7
	s_waitcnt lgkmcnt(5)
	v_mfma_f32_32x32x16_bf16 v[16:31], v[208:211], v[152:155], v[16:31]
	ds_read_b128 v[208:211], v182 offset:49152
	s_add_u32 s52, s10, s2
	s_waitcnt lgkmcnt(5)
	v_mfma_f32_32x32x16_bf16 v[0:15], v[212:215], v[152:155], v[0:15]
	ds_read_b128 v[212:215], v182 offset:53248
	s_addc_u32 s53, s11, 0
	s_waitcnt lgkmcnt(5)
	v_mfma_f32_32x32x16_bf16 v[48:63], v[216:219], v[156:159], v[48:63]
	ds_read_b128 v[216:219], v183 offset:49152
	s_add_u32 s54, s52, 0x204000
	s_waitcnt lgkmcnt(5)
	v_mfma_f32_32x32x16_bf16 v[32:47], v[220:223], v[156:159], v[32:47]
	ds_read_b128 v[220:223], v183 offset:53248
	s_addc_u32 s55, s53, 0
	s_waitcnt lgkmcnt(5)
	v_mfma_f32_32x32x16_bf16 v[16:31], v[224:227], v[156:159], v[16:31]
	ds_read_b128 v[224:227], v184 offset:49152
	s_waitcnt lgkmcnt(5)
	v_mfma_f32_32x32x16_bf16 v[0:15], v[228:231], v[156:159], v[0:15]
	ds_read_b128 v[228:231], v184 offset:53248
	s_waitcnt lgkmcnt(5)
	v_mfma_f32_32x32x16_bf16 v[96:111], v[208:211], v[128:131], 0
	ds_read_b128 v[208:211], v185 offset:49152
	s_waitcnt lgkmcnt(5)
	v_mfma_f32_32x32x16_bf16 v[112:127], v[212:215], v[128:131], 0
	ds_read_b128 v[212:215], v185 offset:53248
	s_waitcnt lgkmcnt(5)
	v_mfma_f32_32x32x16_bf16 v[96:111], v[216:219], v[132:135], v[96:111]
	s_waitcnt lgkmcnt(4)
	v_mfma_f32_32x32x16_bf16 v[112:127], v[220:223], v[132:135], v[112:127]
	s_waitcnt lgkmcnt(3)
	v_mfma_f32_32x32x16_bf16 v[96:111], v[224:227], v[136:139], v[96:111]
	s_waitcnt lgkmcnt(2)
	v_mfma_f32_32x32x16_bf16 v[112:127], v[228:231], v[136:139], v[112:127]
	s_waitcnt lgkmcnt(1)
	v_mfma_f32_32x32x16_bf16 v[96:111], v[208:211], v[140:143], v[96:111]
	s_waitcnt lgkmcnt(0)
	v_mfma_f32_32x32x16_bf16 v[112:127], v[212:215], v[140:143], v[112:127]
	s_waitcnt vmcnt(4)
	s_barrier
.Lattn_tb38_B:
	ds_read_b128 v[216:219], v187 offset:32768
	ds_read_b128 v[220:223], v187 offset:36864
	ds_read_b128 v[224:227], v187 offset:40960
	ds_read_b128 v[228:231], v187 offset:45056
	ds_read_b128 v[208:211], v188 offset:32768
	ds_read_b128 v[212:215], v188 offset:36864
	v_exp_f32_e32 v171, v64
	v_exp_f32_e32 v173, v65
	v_exp_f32_e32 v179, v66
	s_add_i32 m0, s5, 32768
	v_exp_f32_e32 v180, v67
	v_exp_f32_e32 v232, v68
	v_exp_f32_e32 v233, v69
	global_load_lds_dwordx4 v170, s[48:49]
	v_exp_f32_e32 v234, v70
	v_exp_f32_e32 v235, v71
	v_add_f32_e32 v190, v171, v173
	s_add_i32 m0, s5, 40960
	v_add_f32_e32 v191, v179, v180
	v_add_f32_e32 v190, v190, v232
	v_add_f32_e32 v191, v191, v233
	global_load_lds_dwordx4 v170, s[50:51]
	v_add_f32_e32 v190, v190, v234
	v_add_f32_e32 v191, v191, v235
	v_cvt_pk_bf16_f32 v144, v171, v173
	s_add_i32 m0, s5, 65536
	v_cvt_pk_bf16_f32 v145, v179, v180
	v_cvt_pk_bf16_f32 v146, v232, v233
	v_cvt_pk_bf16_f32 v147, v234, v235
	global_load_lds_dwordx4 v172, s[52:53]
	v_exp_f32_e32 v171, v72
	v_exp_f32_e32 v173, v73
	v_exp_f32_e32 v179, v74
	s_add_i32 m0, s5, 73728
	v_exp_f32_e32 v180, v75
	v_exp_f32_e32 v232, v76
	v_exp_f32_e32 v233, v77
	global_load_lds_dwordx4 v172, s[54:55]
	v_exp_f32_e32 v234, v78
	v_exp_f32_e32 v235, v79
	v_add_f32_e32 v190, v190, v171
	v_add_f32_e32 v191, v191, v173
	v_add_f32_e32 v190, v190, v179
	v_add_f32_e32 v191, v191, v180
	v_add_f32_e32 v190, v190, v232
	v_add_f32_e32 v191, v191, v233
	v_add_f32_e32 v190, v190, v234
	v_add_f32_e32 v191, v191, v235
	v_cvt_pk_bf16_f32 v148, v171, v173
	v_cvt_pk_bf16_f32 v149, v179, v180
	v_cvt_pk_bf16_f32 v150, v232, v233
	v_cvt_pk_bf16_f32 v151, v234, v235
	v_exp_f32_e32 v171, v80
	v_exp_f32_e32 v173, v81
	v_exp_f32_e32 v179, v82
	v_exp_f32_e32 v180, v83
	v_exp_f32_e32 v232, v84
	v_exp_f32_e32 v233, v85
	v_exp_f32_e32 v234, v86
	v_exp_f32_e32 v235, v87
	v_add_f32_e32 v190, v190, v171
	v_add_f32_e32 v191, v191, v173
	v_add_f32_e32 v190, v190, v179
	v_add_f32_e32 v191, v191, v180
	v_add_f32_e32 v190, v190, v232
	v_add_f32_e32 v191, v191, v233
	v_add_f32_e32 v190, v190, v234
	v_add_f32_e32 v191, v191, v235
	v_cvt_pk_bf16_f32 v152, v171, v173
	v_cvt_pk_bf16_f32 v153, v179, v180
	v_cvt_pk_bf16_f32 v154, v232, v233
	v_cvt_pk_bf16_f32 v155, v234, v235
	v_exp_f32_e32 v171, v88
	v_exp_f32_e32 v173, v89
	v_exp_f32_e32 v179, v90
	v_exp_f32_e32 v180, v91
	v_exp_f32_e32 v232, v92
	v_exp_f32_e32 v233, v93
	v_exp_f32_e32 v234, v94
	v_exp_f32_e32 v235, v95
	v_add_f32_e32 v190, v190, v171
	v_add_f32_e32 v191, v191, v173
	v_add_f32_e32 v190, v190, v179
	v_add_f32_e32 v191, v191, v180
	v_add_f32_e32 v190, v190, v232
	v_add_f32_e32 v191, v191, v233
	v_add_f32_e32 v190, v190, v234
	v_add_f32_e32 v191, v191, v235
	v_add_f32_e32 v190, v190, v191
	v_cmp_ngt_f32_e32 vcc, 0x71800000, v190
	v_cvt_pk_bf16_f32 v156, v171, v173
	v_cvt_pk_bf16_f32 v157, v179, v180
	v_cvt_pk_bf16_f32 v158, v232, v233
	v_cvt_pk_bf16_f32 v159, v234, v235
	s_nop 0
	s_cbranch_vccnz .Lattn_redo_L1_B
	v_add_f32_e32 v167, v167, v190
	s_waitcnt lgkmcnt(5)
	v_mfma_f32_32x32x16_bf16 v[48:63], v[216:219], v[144:147], v[48:63]
	ds_read_b128 v[216:219], v188 offset:40960
	s_add_i32 s2, s42, 6
	s_waitcnt lgkmcnt(5)
	v_mfma_f32_32x32x16_bf16 v[32:47], v[220:223], v[144:147], v[32:47]
	ds_read_b128 v[220:223], v188 offset:45056
	s_and_b32 s2, s2, 31
	s_waitcnt lgkmcnt(5)
	v_mfma_f32_32x32x16_bf16 v[16:31], v[224:227], v[144:147], v[16:31]
	ds_read_b128 v[224:227], v186 offset:32768
	s_mul_i32 s2, s2, 0x44000
	s_waitcnt lgkmcnt(5)
	v_mfma_f32_32x32x16_bf16 v[0:15], v[228:231], v[144:147], v[0:15]
	ds_read_b128 v[228:231], v186 offset:36864
	s_add_u32 s48, s26, s2
	s_waitcnt lgkmcnt(5)
	v_mfma_f32_32x32x16_bf16 v[48:63], v[208:211], v[148:151], v[48:63]
	ds_read_b128 v[208:211], v186 offset:40960
	s_addc_u32 s49, s27, 0
	s_waitcnt lgkmcnt(5)
	v_mfma_f32_32x32x16_bf16 v[32:47], v[212:215], v[148:151], v[32:47]
	ds_read_b128 v[212:215], v186 offset:45056
	s_add_u32 s50, s48, 0x80
	s_waitcnt lgkmcnt(5)
	v_mfma_f32_32x32x16_bf16 v[16:31], v[216:219], v[148:151], v[16:31]
	ds_read_b128 v[216:219], v189 offset:32768
	s_addc_u32 s51, s49, 0
	s_waitcnt lgkmcnt(5)
	v_mfma_f32_32x32x16_bf16 v[0:15], v[220:223], v[148:151], v[0:15]
	ds_read_b128 v[220:223], v189 offset:36864
	s_add_i32 s2, s42, 4
	s_waitcnt lgkmcnt(5)
	v_mfma_f32_32x32x16_bf16 v[48:63], v[224:227], v[152:155], v[48:63]
	ds_read_b128 v[224:227], v189 offset:40960
	s_and_b32 s2, s2, 31
	s_waitcnt lgkmcnt(5)
	v_mfma_f32_32x32x16_bf16 v[32:47], v[228:231], v[152:155], v[32:47]
	ds_read_b128 v[228:231], v189 offset:45056
	s_lshl_b32 s2, s2, 7
	s_waitcnt lgkmcnt(5)
	v_mfma_f32_32x32x16_bf16 v[16:31], v[208:211], v[152:155], v[16:31]
	ds_read_b128 v[208:211], v182 offset:0
	s_add_u32 s52, s10, s2
	s_waitcnt lgkmcnt(5)
	v_mfma_f32_32x32x16_bf16 v[0:15], v[212:215], v[152:155], v[0:15]
	ds_read_b128 v[212:215], v182 offset:4096
	s_addc_u32 s53, s11, 0
	s_waitcnt lgkmcnt(5)
	v_mfma_f32_32x32x16_bf16 v[48:63], v[216:219], v[156:159], v[48:63]
	ds_read_b128 v[216:219], v183 offset:0
	s_add_u32 s54, s52, 0x204000
	s_waitcnt lgkmcnt(5)
	v_mfma_f32_32x32x16_bf16 v[32:47], v[220:223], v[156:159], v[32:47]
	ds_read_b128 v[220:223], v183 offset:4096
	s_addc_u32 s55, s53, 0
	s_waitcnt lgkmcnt(5)
	v_mfma_f32_32x32x16_bf16 v[16:31], v[224:227], v[156:159], v[16:31]
	ds_read_b128 v[224:227], v184 offset:0
	s_waitcnt lgkmcnt(5)
	v_mfma_f32_32x32x16_bf16 v[0:15], v[228:231], v[156:159], v[0:15]
	ds_read_b128 v[228:231], v184 offset:4096
	s_waitcnt lgkmcnt(5)
	v_mfma_f32_32x32x16_bf16 v[64:79], v[208:211], v[128:131], 0
	ds_read_b128 v[208:211], v185 offset:0
	s_waitcnt lgkmcnt(5)
	v_mfma_f32_32x32x16_bf16 v[80:95], v[212:215], v[128:131], 0
	ds_read_b128 v[212:215], v185 offset:4096
	s_waitcnt lgkmcnt(5)
	v_mfma_f32_32x32x16_bf16 v[64:79], v[216:219], v[132:135], v[64:79]
	s_waitcnt lgkmcnt(4)
	v_mfma_f32_32x32x16_bf16 v[80:95], v[220:223], v[132:135], v[80:95]
	s_waitcnt lgkmcnt(3)
	v_mfma_f32_32x32x16_bf16 v[64:79], v[224:227], v[136:139], v[64:79]
	s_waitcnt lgkmcnt(2)
	v_mfma_f32_32x32x16_bf16 v[80:95], v[228:231], v[136:139], v[80:95]
	s_waitcnt lgkmcnt(1)
	v_mfma_f32_32x32x16_bf16 v[64:79], v[208:211], v[140:143], v[64:79]
	s_waitcnt lgkmcnt(0)
	v_mfma_f32_32x32x16_bf16 v[80:95], v[212:215], v[140:143], v[80:95]
	s_waitcnt vmcnt(4)
	s_barrier
.Lattn_tb40_B:
	ds_read_b128 v[216:219], v187 offset:49152
	ds_read_b128 v[220:223], v187 offset:53248
	ds_read_b128 v[224:227], v187 offset:57344
	ds_read_b128 v[228:231], v187 offset:61440
	ds_read_b128 v[208:211], v188 offset:49152
	ds_read_b128 v[212:215], v188 offset:53248
	v_exp_f32_e32 v171, v96
	v_exp_f32_e32 v173, v97
	v_exp_f32_e32 v179, v98
	s_add_i32 m0, s5, 49152
	v_exp_f32_e32 v180, v99
	v_exp_f32_e32 v232, v100
	v_exp_f32_e32 v233, v101
	global_load_lds_dwordx4 v170, s[48:49]
	v_exp_f32_e32 v234, v102
	v_exp_f32_e32 v235, v103
	v_add_f32_e32 v190, v171, v173
	s_add_i32 m0, s5, 57344
	v_add_f32_e32 v191, v179, v180
	v_add_f32_e32 v190, v190, v232
	v_add_f32_e32 v191, v191, v233
	global_load_lds_dwordx4 v170, s[50:51]
	v_add_f32_e32 v190, v190, v234
	v_add_f32_e32 v191, v191, v235
	v_cvt_pk_bf16_f32 v144, v171, v173
	s_add_i32 m0, s5, 81920
	v_cvt_pk_bf16_f32 v145, v179, v180
	v_cvt_pk_bf16_f32 v146, v232, v233
	v_cvt_pk_bf16_f32 v147, v234, v235
	global_load_lds_dwordx4 v172, s[52:53]
	v_exp_f32_e32 v171, v104
	v_exp_f32_e32 v173, v105
	v_exp_f32_e32 v179, v106
	s_add_i32 m0, s5, 90112
	v_exp_f32_e32 v180, v107
	v_exp_f32_e32 v232, v108
	v_exp_f32_e32 v233, v109
	global_load_lds_dwordx4 v172, s[54:55]
	v_exp_f32_e32 v234, v110
	v_exp_f32_e32 v235, v111
	v_add_f32_e32 v190, v190, v171
	v_add_f32_e32 v191, v191, v173
	v_add_f32_e32 v190, v190, v179
	v_add_f32_e32 v191, v191, v180
	v_add_f32_e32 v190, v190, v232
	v_add_f32_e32 v191, v191, v233
	v_add_f32_e32 v190, v190, v234
	v_add_f32_e32 v191, v191, v235
	v_cvt_pk_bf16_f32 v148, v171, v173
	v_cvt_pk_bf16_f32 v149, v179, v180
	v_cvt_pk_bf16_f32 v150, v232, v233
	v_cvt_pk_bf16_f32 v151, v234, v235
	v_exp_f32_e32 v171, v112
	v_exp_f32_e32 v173, v113
	v_exp_f32_e32 v179, v114
	v_exp_f32_e32 v180, v115
	v_exp_f32_e32 v232, v116
	v_exp_f32_e32 v233, v117
	v_exp_f32_e32 v234, v118
	v_exp_f32_e32 v235, v119
	v_add_f32_e32 v190, v190, v171
	v_add_f32_e32 v191, v191, v173
	v_add_f32_e32 v190, v190, v179
	v_add_f32_e32 v191, v191, v180
	v_add_f32_e32 v190, v190, v232
	v_add_f32_e32 v191, v191, v233
	v_add_f32_e32 v190, v190, v234
	v_add_f32_e32 v191, v191, v235
	v_cvt_pk_bf16_f32 v152, v171, v173
	v_cvt_pk_bf16_f32 v153, v179, v180
	v_cvt_pk_bf16_f32 v154, v232, v233
	v_cvt_pk_bf16_f32 v155, v234, v235
	v_exp_f32_e32 v171, v120
	v_exp_f32_e32 v173, v121
	v_exp_f32_e32 v179, v122
	v_exp_f32_e32 v180, v123
	v_exp_f32_e32 v232, v124
	v_exp_f32_e32 v233, v125
	v_exp_f32_e32 v234, v126
	v_exp_f32_e32 v235, v127
	v_add_f32_e32 v190, v190, v171
	v_add_f32_e32 v191, v191, v173
	v_add_f32_e32 v190, v190, v179
	v_add_f32_e32 v191, v191, v180
	v_add_f32_e32 v190, v190, v232
	v_add_f32_e32 v191, v191, v233
	v_add_f32_e32 v190, v190, v234
	v_add_f32_e32 v191, v191, v235
	v_add_f32_e32 v190, v190, v191
	v_cmp_ngt_f32_e32 vcc, 0x71800000, v190
	v_cvt_pk_bf16_f32 v156, v171, v173
	v_cvt_pk_bf16_f32 v157, v179, v180
	v_cvt_pk_bf16_f32 v158, v232, v233
	v_cvt_pk_bf16_f32 v159, v234, v235
	s_nop 0
	s_cbranch_vccnz .Lattn_redo_L2_B
	v_add_f32_e32 v167, v167, v190
	s_waitcnt lgkmcnt(5)
	v_mfma_f32_32x32x16_bf16 v[48:63], v[216:219], v[144:147], v[48:63]
	ds_read_b128 v[216:219], v188 offset:57344
	s_add_i32 s2, s42, 7
	s_waitcnt lgkmcnt(5)
	v_mfma_f32_32x32x16_bf16 v[32:47], v[220:223], v[144:147], v[32:47]
	ds_read_b128 v[220:223], v188 offset:61440
	s_and_b32 s2, s2, 31
	s_waitcnt lgkmcnt(5)
	v_mfma_f32_32x32x16_bf16 v[16:31], v[224:227], v[144:147], v[16:31]
	ds_read_b128 v[224:227], v186 offset:49152
	s_mul_i32 s2, s2, 0x44000
	s_waitcnt lgkmcnt(5)
	v_mfma_f32_32x32x16_bf16 v[0:15], v[228:231], v[144:147], v[0:15]
	ds_read_b128 v[228:231], v186 offset:53248
	s_add_u32 s48, s26, s2
	s_waitcnt lgkmcnt(5)
	v_mfma_f32_32x32x16_bf16 v[48:63], v[208:211], v[148:151], v[48:63]
	ds_read_b128 v[208:211], v186 offset:57344
	s_addc_u32 s49, s27, 0
	s_waitcnt lgkmcnt(5)
	v_mfma_f32_32x32x16_bf16 v[32:47], v[212:215], v[148:151], v[32:47]
	ds_read_b128 v[212:215], v186 offset:61440
	s_add_u32 s50, s48, 0x80
	s_waitcnt lgkmcnt(5)
	v_mfma_f32_32x32x16_bf16 v[16:31], v[216:219], v[148:151], v[16:31]
	ds_read_b128 v[216:219], v189 offset:49152
	s_addc_u32 s51, s49, 0
	s_waitcnt lgkmcnt(5)
	v_mfma_f32_32x32x16_bf16 v[0:15], v[220:223], v[148:151], v[0:15]
	ds_read_b128 v[220:223], v189 offset:53248
	s_add_i32 s2, s42, 5
	s_waitcnt lgkmcnt(5)
	v_mfma_f32_32x32x16_bf16 v[48:63], v[224:227], v[152:155], v[48:63]
	ds_read_b128 v[224:227], v189 offset:57344
	s_and_b32 s2, s2, 31
	s_waitcnt lgkmcnt(5)
	v_mfma_f32_32x32x16_bf16 v[32:47], v[228:231], v[152:155], v[32:47]
	ds_read_b128 v[228:231], v189 offset:61440
	s_lshl_b32 s2, s2, 7
	s_waitcnt lgkmcnt(5)
	v_mfma_f32_32x32x16_bf16 v[16:31], v[208:211], v[152:155], v[16:31]
	ds_read_b128 v[208:211], v182 offset:16384
	s_add_u32 s52, s10, s2
	s_waitcnt lgkmcnt(5)
	v_mfma_f32_32x32x16_bf16 v[0:15], v[212:215], v[152:155], v[0:15]
	ds_read_b128 v[212:215], v182 offset:20480
	s_addc_u32 s53, s11, 0
	s_waitcnt lgkmcnt(5)
	v_mfma_f32_32x32x16_bf16 v[48:63], v[216:219], v[156:159], v[48:63]
	ds_read_b128 v[216:219], v183 offset:16384
	s_add_u32 s54, s52, 0x204000
	s_waitcnt lgkmcnt(5)
	v_mfma_f32_32x32x16_bf16 v[32:47], v[220:223], v[156:159], v[32:47]
	ds_read_b128 v[220:223], v183 offset:20480
	s_addc_u32 s55, s53, 0
	s_waitcnt lgkmcnt(5)
	v_mfma_f32_32x32x16_bf16 v[16:31], v[224:227], v[156:159], v[16:31]
	ds_read_b128 v[224:227], v184 offset:16384
	s_waitcnt lgkmcnt(5)
	v_mfma_f32_32x32x16_bf16 v[0:15], v[228:231], v[156:159], v[0:15]
	ds_read_b128 v[228:231], v184 offset:20480
	s_waitcnt lgkmcnt(5)
	v_mfma_f32_32x32x16_bf16 v[96:111], v[208:211], v[128:131], 0
	ds_read_b128 v[208:211], v185 offset:16384
	s_waitcnt lgkmcnt(5)
	v_mfma_f32_32x32x16_bf16 v[112:127], v[212:215], v[128:131], 0
	ds_read_b128 v[212:215], v185 offset:20480
	s_waitcnt lgkmcnt(5)
	v_mfma_f32_32x32x16_bf16 v[96:111], v[216:219], v[132:135], v[96:111]
	s_waitcnt lgkmcnt(4)
	v_mfma_f32_32x32x16_bf16 v[112:127], v[220:223], v[132:135], v[112:127]
	s_waitcnt lgkmcnt(3)
	v_mfma_f32_32x32x16_bf16 v[96:111], v[224:227], v[136:139], v[96:111]
	s_waitcnt lgkmcnt(2)
	v_mfma_f32_32x32x16_bf16 v[112:127], v[228:231], v[136:139], v[112:127]
	s_waitcnt lgkmcnt(1)
	v_mfma_f32_32x32x16_bf16 v[96:111], v[208:211], v[140:143], v[96:111]
	s_waitcnt lgkmcnt(0)
	v_mfma_f32_32x32x16_bf16 v[112:127], v[212:215], v[140:143], v[112:127]
	s_waitcnt vmcnt(4)
	s_barrier
.Lattn_tb42_B:
	ds_read_b128 v[216:219], v187 offset:0
	ds_read_b128 v[220:223], v187 offset:4096
	ds_read_b128 v[224:227], v187 offset:8192
	ds_read_b128 v[228:231], v187 offset:12288
	ds_read_b128 v[208:211], v188 offset:0
	ds_read_b128 v[212:215], v188 offset:4096
	v_exp_f32_e32 v171, v64
	v_exp_f32_e32 v173, v65
	v_exp_f32_e32 v179, v66
	s_add_i32 m0, s5, 0
	v_exp_f32_e32 v180, v67
	v_exp_f32_e32 v232, v68
	v_exp_f32_e32 v233, v69
	global_load_lds_dwordx4 v170, s[48:49]
	v_exp_f32_e32 v234, v70
	v_exp_f32_e32 v235, v71
	v_add_f32_e32 v190, v171, v173
	s_add_i32 m0, s5, 8192
	v_add_f32_e32 v191, v179, v180
	v_add_f32_e32 v190, v190, v232
	v_add_f32_e32 v191, v191, v233
	global_load_lds_dwordx4 v170, s[50:51]
	v_add_f32_e32 v190, v190, v234
	v_add_f32_e32 v191, v191, v235
	v_cvt_pk_bf16_f32 v144, v171, v173
	s_add_i32 m0, s5, 98304
	v_cvt_pk_bf16_f32 v145, v179, v180
	v_cvt_pk_bf16_f32 v146, v232, v233
	v_cvt_pk_bf16_f32 v147, v234, v235
	global_load_lds_dwordx4 v172, s[52:53]
	v_exp_f32_e32 v171, v72
	v_exp_f32_e32 v173, v73
	v_exp_f32_e32 v179, v74
	s_add_i32 m0, s5, 106496
	v_exp_f32_e32 v180, v75
	v_exp_f32_e32 v232, v76
	v_exp_f32_e32 v233, v77
	global_load_lds_dwordx4 v172, s[54:55]
	v_exp_f32_e32 v234, v78
	v_exp_f32_e32 v235, v79
	v_add_f32_e32 v190, v190, v171
	v_add_f32_e32 v191, v191, v173
	v_add_f32_e32 v190, v190, v179
	v_add_f32_e32 v191, v191, v180
	v_add_f32_e32 v190, v190, v232
	v_add_f32_e32 v191, v191, v233
	v_add_f32_e32 v190, v190, v234
	v_add_f32_e32 v191, v191, v235
	v_cvt_pk_bf16_f32 v148, v171, v173
	v_cvt_pk_bf16_f32 v149, v179, v180
	v_cvt_pk_bf16_f32 v150, v232, v233
	v_cvt_pk_bf16_f32 v151, v234, v235
	v_exp_f32_e32 v171, v80
	v_exp_f32_e32 v173, v81
	v_exp_f32_e32 v179, v82
	v_exp_f32_e32 v180, v83
	v_exp_f32_e32 v232, v84
	v_exp_f32_e32 v233, v85
	v_exp_f32_e32 v234, v86
	v_exp_f32_e32 v235, v87
	v_add_f32_e32 v190, v190, v171
	v_add_f32_e32 v191, v191, v173
	v_add_f32_e32 v190, v190, v179
	v_add_f32_e32 v191, v191, v180
	v_add_f32_e32 v190, v190, v232
	v_add_f32_e32 v191, v191, v233
	v_add_f32_e32 v190, v190, v234
	v_add_f32_e32 v191, v191, v235
	v_cvt_pk_bf16_f32 v152, v171, v173
	v_cvt_pk_bf16_f32 v153, v179, v180
	v_cvt_pk_bf16_f32 v154, v232, v233
	v_cvt_pk_bf16_f32 v155, v234, v235
	v_exp_f32_e32 v171, v88
	v_exp_f32_e32 v173, v89
	v_exp_f32_e32 v179, v90
	v_exp_f32_e32 v180, v91
	v_exp_f32_e32 v232, v92
	v_exp_f32_e32 v233, v93
	v_exp_f32_e32 v234, v94
	v_exp_f32_e32 v235, v95
	v_add_f32_e32 v190, v190, v171
	v_add_f32_e32 v191, v191, v173
	v_add_f32_e32 v190, v190, v179
	v_add_f32_e32 v191, v191, v180
	v_add_f32_e32 v190, v190, v232
	v_add_f32_e32 v191, v191, v233
	v_add_f32_e32 v190, v190, v234
	v_add_f32_e32 v191, v191, v235
	v_add_f32_e32 v190, v190, v191
	v_cmp_ngt_f32_e32 vcc, 0x71800000, v190
	v_cvt_pk_bf16_f32 v156, v171, v173
	v_cvt_pk_bf16_f32 v157, v179, v180
	v_cvt_pk_bf16_f32 v158, v232, v233
	v_cvt_pk_bf16_f32 v159, v234, v235
	s_nop 0
	s_cbranch_vccnz .Lattn_redo_L3_B
	v_add_f32_e32 v167, v167, v190
	s_add_i32 s42, s42, 4
	s_add_i32 s47, s47, -1
	s_cmp_lg_u32 s47, 0
	s_cbranch_scc1 .Lattn_loop_f_B
	s_waitcnt lgkmcnt(5)
	v_mfma_f32_32x32x16_bf16 v[48:63], v[216:219], v[144:147], v[48:63]
	ds_read_b128 v[216:219], v188 offset:8192
	s_add_i32 s2, s42, 2
	s_waitcnt lgkmcnt(5)
	v_mfma_f32_32x32x16_bf16 v[32:47], v[220:223], v[144:147], v[32:47]
	ds_read_b128 v[220:223], v188 offset:12288
	s_and_b32 s2, s2, 31
	s_waitcnt lgkmcnt(5)
	v_mfma_f32_32x32x16_bf16 v[16:31], v[224:227], v[144:147], v[16:31]
	ds_read_b128 v[224:227], v186 offset:0
	s_lshl_b32 s2, s2, 7
	s_waitcnt lgkmcnt(5)
	v_mfma_f32_32x32x16_bf16 v[0:15], v[228:231], v[144:147], v[0:15]
	ds_read_b128 v[228:231], v186 offset:4096
	s_add_u32 s52, s10, s2
	s_waitcnt lgkmcnt(5)
	v_mfma_f32_32x32x16_bf16 v[48:63], v[208:211], v[148:151], v[48:63]
	ds_read_b128 v[208:211], v186 offset:8192
	s_addc_u32 s53, s11, 0
	s_waitcnt lgkmcnt(5)
	v_mfma_f32_32x32x16_bf16 v[32:47], v[212:215], v[148:151], v[32:47]
	ds_read_b128 v[212:215], v186 offset:12288
	s_add_u32 s54, s52, 0x204000
	s_waitcnt lgkmcnt(5)
	v_mfma_f32_32x32x16_bf16 v[16:31], v[216:219], v[148:151], v[16:31]
	ds_read_b128 v[216:219], v189 offset:0
	s_addc_u32 s55, s53, 0
	s_waitcnt lgkmcnt(5)
	v_mfma_f32_32x32x16_bf16 v[0:15], v[220:223], v[148:151], v[0:15]
	ds_read_b128 v[220:223], v189 offset:4096
	s_waitcnt lgkmcnt(5)
	v_mfma_f32_32x32x16_bf16 v[48:63], v[224:227], v[152:155], v[48:63]
	ds_read_b128 v[224:227], v189 offset:8192
	s_waitcnt lgkmcnt(5)
	v_mfma_f32_32x32x16_bf16 v[32:47], v[228:231], v[152:155], v[32:47]
	ds_read_b128 v[228:231], v189 offset:12288
	s_waitcnt lgkmcnt(5)
	v_mfma_f32_32x32x16_bf16 v[16:31], v[208:211], v[152:155], v[16:31]
	ds_read_b128 v[208:211], v182 offset:32768
	s_waitcnt lgkmcnt(5)
	v_mfma_f32_32x32x16_bf16 v[0:15], v[212:215], v[152:155], v[0:15]
	ds_read_b128 v[212:215], v182 offset:36864
	s_waitcnt lgkmcnt(5)
	v_mfma_f32_32x32x16_bf16 v[48:63], v[216:219], v[156:159], v[48:63]
	ds_read_b128 v[216:219], v183 offset:32768
	s_waitcnt lgkmcnt(5)
	v_mfma_f32_32x32x16_bf16 v[32:47], v[220:223], v[156:159], v[32:47]
	ds_read_b128 v[220:223], v183 offset:36864
	s_waitcnt lgkmcnt(5)
	v_mfma_f32_32x32x16_bf16 v[16:31], v[224:227], v[156:159], v[16:31]
	ds_read_b128 v[224:227], v184 offset:32768
	s_waitcnt lgkmcnt(5)
	v_mfma_f32_32x32x16_bf16 v[0:15], v[228:231], v[156:159], v[0:15]
	ds_read_b128 v[228:231], v184 offset:36864
	s_waitcnt lgkmcnt(5)
	v_mfma_f32_32x32x16_bf16 v[64:79], v[208:211], v[128:131], 0
	ds_read_b128 v[208:211], v185 offset:32768
	s_waitcnt lgkmcnt(5)
	v_mfma_f32_32x32x16_bf16 v[80:95], v[212:215], v[128:131], 0
	ds_read_b128 v[212:215], v185 offset:36864
	s_waitcnt lgkmcnt(5)
	v_mfma_f32_32x32x16_bf16 v[64:79], v[216:219], v[132:135], v[64:79]
	s_waitcnt lgkmcnt(4)
	v_mfma_f32_32x32x16_bf16 v[80:95], v[220:223], v[132:135], v[80:95]
	s_waitcnt lgkmcnt(3)
	v_mfma_f32_32x32x16_bf16 v[64:79], v[224:227], v[136:139], v[64:79]
	s_waitcnt lgkmcnt(2)
	v_mfma_f32_32x32x16_bf16 v[80:95], v[228:231], v[136:139], v[80:95]
	s_waitcnt lgkmcnt(1)
	v_mfma_f32_32x32x16_bf16 v[64:79], v[208:211], v[140:143], v[64:79]
	s_waitcnt lgkmcnt(0)
	v_mfma_f32_32x32x16_bf16 v[80:95], v[212:215], v[140:143], v[80:95]
	s_waitcnt vmcnt(4)
	s_barrier
.Lattn_tb44_B:
	ds_read_b128 v[216:219], v187 offset:16384
	ds_read_b128 v[220:223], v187 offset:20480
	ds_read_b128 v[224:227], v187 offset:24576
	ds_read_b128 v[228:231], v187 offset:28672
	ds_read_b128 v[208:211], v188 offset:16384
	ds_read_b128 v[212:215], v188 offset:20480
	v_exp_f32_e32 v171, v96
	v_exp_f32_e32 v173, v97
	v_exp_f32_e32 v179, v98
	s_add_i32 m0, s5, 114688
	v_exp_f32_e32 v180, v99
	v_exp_f32_e32 v232, v100
	v_exp_f32_e32 v233, v101
	global_load_lds_dwordx4 v172, s[52:53]
	v_exp_f32_e32 v234, v102
	v_exp_f32_e32 v235, v103
	v_add_f32_e32 v190, v171, v173
	s_add_i32 m0, s5, 122880
	v_add_f32_e32 v191, v179, v180
	v_add_f32_e32 v190, v190, v232
	v_add_f32_e32 v191, v191, v233
	global_load_lds_dwordx4 v172, s[54:55]
	v_add_f32_e32 v190, v190, v234
	v_add_f32_e32 v191, v191, v235
	v_cvt_pk_bf16_f32 v144, v171, v173
	v_cvt_pk_bf16_f32 v145, v179, v180
	v_cvt_pk_bf16_f32 v146, v232, v233
	v_cvt_pk_bf16_f32 v147, v234, v235
	v_exp_f32_e32 v171, v104
	v_exp_f32_e32 v173, v105
	v_exp_f32_e32 v179, v106
	v_exp_f32_e32 v180, v107
	v_exp_f32_e32 v232, v108
	v_exp_f32_e32 v233, v109
	v_exp_f32_e32 v234, v110
	v_exp_f32_e32 v235, v111
	v_add_f32_e32 v190, v190, v171
	v_add_f32_e32 v191, v191, v173
	v_add_f32_e32 v190, v190, v179
	v_add_f32_e32 v191, v191, v180
	v_add_f32_e32 v190, v190, v232
	v_add_f32_e32 v191, v191, v233
	v_add_f32_e32 v190, v190, v234
	v_add_f32_e32 v191, v191, v235
	v_cvt_pk_bf16_f32 v148, v171, v173
	v_cvt_pk_bf16_f32 v149, v179, v180
	v_cvt_pk_bf16_f32 v150, v232, v233
	v_cvt_pk_bf16_f32 v151, v234, v235
	v_exp_f32_e32 v171, v112
	v_exp_f32_e32 v173, v113
	v_exp_f32_e32 v179, v114
	v_exp_f32_e32 v180, v115
	v_exp_f32_e32 v232, v116
	v_exp_f32_e32 v233, v117
	v_exp_f32_e32 v234, v118
	v_exp_f32_e32 v235, v119
	v_add_f32_e32 v190, v190, v171
	v_add_f32_e32 v191, v191, v173
	v_add_f32_e32 v190, v190, v179
	v_add_f32_e32 v191, v191, v180
	v_add_f32_e32 v190, v190, v232
	v_add_f32_e32 v191, v191, v233
	v_add_f32_e32 v190, v190, v234
	v_add_f32_e32 v191, v191, v235
	v_cvt_pk_bf16_f32 v152, v171, v173
	v_cvt_pk_bf16_f32 v153, v179, v180
	v_cvt_pk_bf16_f32 v154, v232, v233
	v_cvt_pk_bf16_f32 v155, v234, v235
	v_exp_f32_e32 v171, v120
	v_exp_f32_e32 v173, v121
	v_exp_f32_e32 v179, v122
	v_exp_f32_e32 v180, v123
	v_exp_f32_e32 v232, v124
	v_exp_f32_e32 v233, v125
	v_exp_f32_e32 v234, v126
	v_exp_f32_e32 v235, v127
	v_add_f32_e32 v190, v190, v171
	v_add_f32_e32 v191, v191, v173
	v_add_f32_e32 v190, v190, v179
	v_add_f32_e32 v191, v191, v180
	v_add_f32_e32 v190, v190, v232
	v_add_f32_e32 v191, v191, v233
	v_add_f32_e32 v190, v190, v234
	v_add_f32_e32 v191, v191, v235
	v_add_f32_e32 v190, v190, v191
	v_cmp_ngt_f32_e32 vcc, 0x71800000, v190
	v_cvt_pk_bf16_f32 v156, v171, v173
	v_cvt_pk_bf16_f32 v157, v179, v180
	v_cvt_pk_bf16_f32 v158, v232, v233
	v_cvt_pk_bf16_f32 v159, v234, v235
	s_nop 0
	s_cbranch_vccnz .Lattn_redo_T29_B
	v_add_f32_e32 v167, v167, v190
	s_waitcnt lgkmcnt(5)
	v_mfma_f32_32x32x16_bf16 v[48:63], v[216:219], v[144:147], v[48:63]
	ds_read_b128 v[216:219], v188 offset:24576
	s_waitcnt lgkmcnt(5)
	v_mfma_f32_32x32x16_bf16 v[32:47], v[220:223], v[144:147], v[32:47]
	ds_read_b128 v[220:223], v188 offset:28672
	s_waitcnt lgkmcnt(5)
	v_mfma_f32_32x32x16_bf16 v[16:31], v[224:227], v[144:147], v[16:31]
	ds_read_b128 v[224:227], v186 offset:16384
	s_waitcnt lgkmcnt(5)
	v_mfma_f32_32x32x16_bf16 v[0:15], v[228:231], v[144:147], v[0:15]
	ds_read_b128 v[228:231], v186 offset:20480
	s_waitcnt lgkmcnt(5)
	v_mfma_f32_32x32x16_bf16 v[48:63], v[208:211], v[148:151], v[48:63]
	ds_read_b128 v[208:211], v186 offset:24576
	s_waitcnt lgkmcnt(5)
	v_mfma_f32_32x32x16_bf16 v[32:47], v[212:215], v[148:151], v[32:47]
	ds_read_b128 v[212:215], v186 offset:28672
	s_waitcnt lgkmcnt(5)
	v_mfma_f32_32x32x16_bf16 v[16:31], v[216:219], v[148:151], v[16:31]
	ds_read_b128 v[216:219], v189 offset:16384
	s_waitcnt lgkmcnt(5)
	v_mfma_f32_32x32x16_bf16 v[0:15], v[220:223], v[148:151], v[0:15]
	ds_read_b128 v[220:223], v189 offset:20480
	s_waitcnt lgkmcnt(5)
	v_mfma_f32_32x32x16_bf16 v[48:63], v[224:227], v[152:155], v[48:63]
	ds_read_b128 v[224:227], v189 offset:24576
	s_waitcnt lgkmcnt(5)
	v_mfma_f32_32x32x16_bf16 v[32:47], v[228:231], v[152:155], v[32:47]
	ds_read_b128 v[228:231], v189 offset:28672
	s_waitcnt lgkmcnt(5)
	v_mfma_f32_32x32x16_bf16 v[16:31], v[208:211], v[152:155], v[16:31]
	ds_read_b128 v[208:211], v182 offset:49152
	s_waitcnt lgkmcnt(5)
	v_mfma_f32_32x32x16_bf16 v[0:15], v[212:215], v[152:155], v[0:15]
	ds_read_b128 v[212:215], v182 offset:53248
	s_waitcnt lgkmcnt(5)
	v_mfma_f32_32x32x16_bf16 v[48:63], v[216:219], v[156:159], v[48:63]
	ds_read_b128 v[216:219], v183 offset:49152
	s_waitcnt lgkmcnt(5)
	v_mfma_f32_32x32x16_bf16 v[32:47], v[220:223], v[156:159], v[32:47]
	ds_read_b128 v[220:223], v183 offset:53248
	s_waitcnt lgkmcnt(5)
	v_mfma_f32_32x32x16_bf16 v[16:31], v[224:227], v[156:159], v[16:31]
	ds_read_b128 v[224:227], v184 offset:49152
	s_waitcnt lgkmcnt(5)
	v_mfma_f32_32x32x16_bf16 v[0:15], v[228:231], v[156:159], v[0:15]
	ds_read_b128 v[228:231], v184 offset:53248
	s_waitcnt lgkmcnt(5)
	v_mfma_f32_32x32x16_bf16 v[96:111], v[208:211], v[128:131], 0
	ds_read_b128 v[208:211], v185 offset:49152
	s_waitcnt lgkmcnt(5)
	v_mfma_f32_32x32x16_bf16 v[112:127], v[212:215], v[128:131], 0
	ds_read_b128 v[212:215], v185 offset:53248
	s_waitcnt lgkmcnt(5)
	v_mfma_f32_32x32x16_bf16 v[96:111], v[216:219], v[132:135], v[96:111]
	s_waitcnt lgkmcnt(4)
	v_mfma_f32_32x32x16_bf16 v[112:127], v[220:223], v[132:135], v[112:127]
	s_waitcnt lgkmcnt(3)
	v_mfma_f32_32x32x16_bf16 v[96:111], v[224:227], v[136:139], v[96:111]
	s_waitcnt lgkmcnt(2)
	v_mfma_f32_32x32x16_bf16 v[112:127], v[228:231], v[136:139], v[112:127]
	s_waitcnt lgkmcnt(1)
	v_mfma_f32_32x32x16_bf16 v[96:111], v[208:211], v[140:143], v[96:111]
	s_waitcnt lgkmcnt(0)
	v_mfma_f32_32x32x16_bf16 v[112:127], v[212:215], v[140:143], v[112:127]
	s_waitcnt vmcnt(2)
	s_barrier

.Lattn_pfvt_f_B:
	v_add_f32_e32 v190, v190, v234
	v_add_f32_e32 v191, v191, v235
	v_cvt_pk_bf16_f32 v144, v171, v173
	v_cvt_pk_bf16_f32 v145, v179, v180
	v_cvt_pk_bf16_f32 v146, v232, v233
	v_cvt_pk_bf16_f32 v147, v234, v235
	v_exp_f32_e32 v171, v72
	v_exp_f32_e32 v173, v73
	v_exp_f32_e32 v179, v74
	v_exp_f32_e32 v180, v75
	v_exp_f32_e32 v232, v76
	v_exp_f32_e32 v233, v77
	v_exp_f32_e32 v234, v78
	v_exp_f32_e32 v235, v79
	v_add_f32_e32 v190, v190, v171
	v_add_f32_e32 v191, v191, v173
	v_add_f32_e32 v190, v190, v179
	v_add_f32_e32 v191, v191, v180
	v_add_f32_e32 v190, v190, v232
	v_add_f32_e32 v191, v191, v233
	v_add_f32_e32 v190, v190, v234
	v_add_f32_e32 v191, v191, v235
	v_cvt_pk_bf16_f32 v148, v171, v173
	v_cvt_pk_bf16_f32 v149, v179, v180
	v_cvt_pk_bf16_f32 v150, v232, v233
	v_cvt_pk_bf16_f32 v151, v234, v235
	v_exp_f32_e32 v171, v80
	v_exp_f32_e32 v173, v81
	v_exp_f32_e32 v179, v82
	v_exp_f32_e32 v180, v83
	v_exp_f32_e32 v232, v84
	v_exp_f32_e32 v233, v85
	v_exp_f32_e32 v234, v86
	v_exp_f32_e32 v235, v87
	v_add_f32_e32 v190, v190, v171
	v_add_f32_e32 v191, v191, v173
	v_add_f32_e32 v190, v190, v179
	v_add_f32_e32 v191, v191, v180
	v_add_f32_e32 v190, v190, v232
	v_add_f32_e32 v191, v191, v233
	v_add_f32_e32 v190, v190, v234
	v_add_f32_e32 v191, v191, v235
	v_cvt_pk_bf16_f32 v152, v171, v173
	v_cvt_pk_bf16_f32 v153, v179, v180
	v_cvt_pk_bf16_f32 v154, v232, v233
	v_cvt_pk_bf16_f32 v155, v234, v235
	v_exp_f32_e32 v171, v88
	v_exp_f32_e32 v173, v89
	v_exp_f32_e32 v179, v90
	v_exp_f32_e32 v180, v91
	v_exp_f32_e32 v232, v92
	v_exp_f32_e32 v233, v93
	v_exp_f32_e32 v234, v94
	v_exp_f32_e32 v235, v95
	v_add_f32_e32 v190, v190, v171
	v_add_f32_e32 v191, v191, v173
	v_add_f32_e32 v190, v190, v179
	v_add_f32_e32 v191, v191, v180
	v_add_f32_e32 v190, v190, v232
	v_add_f32_e32 v191, v191, v233
	v_add_f32_e32 v190, v190, v234
	v_add_f32_e32 v191, v191, v235
	v_add_f32_e32 v190, v190, v191
	v_cmp_ngt_f32_e32 vcc, 0x71800000, v190
	v_cvt_pk_bf16_f32 v156, v171, v173
	v_cvt_pk_bf16_f32 v157, v179, v180
	v_cvt_pk_bf16_f32 v158, v232, v233
	v_cvt_pk_bf16_f32 v159, v234, v235
	s_nop 0
	s_cbranch_vccnz .Lattn_redo_T30_B
	v_add_f32_e32 v167, v167, v190
	s_waitcnt lgkmcnt(5)
	v_mfma_f32_32x32x16_bf16 v[48:63], v[216:219], v[144:147], v[48:63]
	ds_read_b128 v[216:219], v188 offset:40960
	s_waitcnt lgkmcnt(5)
	v_mfma_f32_32x32x16_bf16 v[32:47], v[220:223], v[144:147], v[32:47]
	ds_read_b128 v[220:223], v188 offset:45056
	s_waitcnt lgkmcnt(5)
	v_mfma_f32_32x32x16_bf16 v[16:31], v[224:227], v[144:147], v[16:31]
	ds_read_b128 v[224:227], v186 offset:32768
	s_waitcnt lgkmcnt(5)
	v_mfma_f32_32x32x16_bf16 v[0:15], v[228:231], v[144:147], v[0:15]
	ds_read_b128 v[228:231], v186 offset:36864
	s_waitcnt lgkmcnt(5)
	v_mfma_f32_32x32x16_bf16 v[48:63], v[208:211], v[148:151], v[48:63]
	ds_read_b128 v[208:211], v186 offset:40960
	s_waitcnt lgkmcnt(5)
	v_mfma_f32_32x32x16_bf16 v[32:47], v[212:215], v[148:151], v[32:47]
	ds_read_b128 v[212:215], v186 offset:45056
	s_waitcnt lgkmcnt(5)
	v_mfma_f32_32x32x16_bf16 v[16:31], v[216:219], v[148:151], v[16:31]
	ds_read_b128 v[216:219], v189 offset:32768
	s_waitcnt lgkmcnt(5)
	v_mfma_f32_32x32x16_bf16 v[0:15], v[220:223], v[148:151], v[0:15]
	ds_read_b128 v[220:223], v189 offset:36864
	s_waitcnt lgkmcnt(5)
	v_mfma_f32_32x32x16_bf16 v[48:63], v[224:227], v[152:155], v[48:63]
	ds_read_b128 v[224:227], v189 offset:40960
	s_waitcnt lgkmcnt(5)
	v_mfma_f32_32x32x16_bf16 v[32:47], v[228:231], v[152:155], v[32:47]
	ds_read_b128 v[228:231], v189 offset:45056
	s_waitcnt lgkmcnt(5)
	v_mfma_f32_32x32x16_bf16 v[16:31], v[208:211], v[152:155], v[16:31]
	s_waitcnt lgkmcnt(4)
	v_mfma_f32_32x32x16_bf16 v[0:15], v[212:215], v[152:155], v[0:15]
	s_waitcnt lgkmcnt(3)
	v_mfma_f32_32x32x16_bf16 v[48:63], v[216:219], v[156:159], v[48:63]
	s_waitcnt lgkmcnt(2)
	v_mfma_f32_32x32x16_bf16 v[32:47], v[220:223], v[156:159], v[32:47]
	s_waitcnt lgkmcnt(1)
	v_mfma_f32_32x32x16_bf16 v[16:31], v[224:227], v[156:159], v[16:31]
	s_waitcnt lgkmcnt(0)
	v_mfma_f32_32x32x16_bf16 v[0:15], v[228:231], v[156:159], v[0:15]
	s_cmp_lg_u32 s35, 0
	s_cbranch_scc1 .Lattn_tb48_w6_B
	s_waitcnt vmcnt(0)
	s_branch .Lattn_tb48_wd_B

.Lattn_loop_s_B:
.Lattn_top_L0_B:
	s_waitcnt lgkmcnt(5)
	v_mfma_f32_32x32x16_bf16 v[48:63], v[216:219], v[144:147], v[48:63]
	ds_read_b128 v[216:219], v188 offset:8192
	s_add_i32 s2, s42, 4
	s_waitcnt lgkmcnt(5)
	v_mfma_f32_32x32x16_bf16 v[32:47], v[220:223], v[144:147], v[32:47]
	ds_read_b128 v[220:223], v188 offset:12288
	s_and_b32 s2, s2, 31
	s_waitcnt lgkmcnt(5)
	v_mfma_f32_32x32x16_bf16 v[16:31], v[224:227], v[144:147], v[16:31]
	ds_read_b128 v[224:227], v186 offset:0
	s_mul_i32 s2, s2, 0x44000
	s_waitcnt lgkmcnt(5)
	v_mfma_f32_32x32x16_bf16 v[0:15], v[228:231], v[144:147], v[0:15]
	ds_read_b128 v[228:231], v186 offset:4096
	s_add_u32 s48, s26, s2
	s_waitcnt lgkmcnt(5)
	v_mfma_f32_32x32x16_bf16 v[48:63], v[208:211], v[148:151], v[48:63]
	ds_read_b128 v[208:211], v186 offset:8192
	s_addc_u32 s49, s27, 0
	s_waitcnt lgkmcnt(5)
	v_mfma_f32_32x32x16_bf16 v[32:47], v[212:215], v[148:151], v[32:47]
	ds_read_b128 v[212:215], v186 offset:12288
	s_add_u32 s50, s48, 0x80
	s_waitcnt lgkmcnt(5)
	v_mfma_f32_32x32x16_bf16 v[16:31], v[216:219], v[148:151], v[16:31]
	ds_read_b128 v[216:219], v189 offset:0
	s_addc_u32 s51, s49, 0
	s_waitcnt lgkmcnt(5)
	v_mfma_f32_32x32x16_bf16 v[0:15], v[220:223], v[148:151], v[0:15]
	ds_read_b128 v[220:223], v189 offset:4096
	s_add_i32 s2, s42, 2
	s_waitcnt lgkmcnt(5)
	v_mfma_f32_32x32x16_bf16 v[48:63], v[224:227], v[152:155], v[48:63]
	ds_read_b128 v[224:227], v189 offset:8192
	s_and_b32 s2, s2, 31
	s_waitcnt lgkmcnt(5)
	v_mfma_f32_32x32x16_bf16 v[32:47], v[228:231], v[152:155], v[32:47]
	ds_read_b128 v[228:231], v189 offset:12288
	s_lshl_b32 s2, s2, 7
	s_waitcnt lgkmcnt(5)
	v_mfma_f32_32x32x16_bf16 v[16:31], v[208:211], v[152:155], v[16:31]
	ds_read_b128 v[208:211], v182 offset:32768
	s_add_u32 s52, s10, s2
	s_waitcnt lgkmcnt(5)
	v_mfma_f32_32x32x16_bf16 v[0:15], v[212:215], v[152:155], v[0:15]
	ds_read_b128 v[212:215], v182 offset:36864
	s_addc_u32 s53, s11, 0
	s_waitcnt lgkmcnt(5)
	v_mfma_f32_32x32x16_bf16 v[48:63], v[216:219], v[156:159], v[48:63]
	ds_read_b128 v[216:219], v183 offset:32768
	s_add_u32 s54, s52, 0x204000
	s_waitcnt lgkmcnt(5)
	v_mfma_f32_32x32x16_bf16 v[32:47], v[220:223], v[156:159], v[32:47]
	ds_read_b128 v[220:223], v183 offset:36864
	s_addc_u32 s55, s53, 0
	s_waitcnt lgkmcnt(5)
	v_mfma_f32_32x32x16_bf16 v[16:31], v[224:227], v[156:159], v[16:31]
	ds_read_b128 v[224:227], v184 offset:32768
	s_waitcnt lgkmcnt(5)
	v_mfma_f32_32x32x16_bf16 v[0:15], v[228:231], v[156:159], v[0:15]
	ds_read_b128 v[228:231], v184 offset:36864
	s_waitcnt lgkmcnt(5)
	v_mfma_f32_32x32x16_bf16 v[64:79], v[208:211], v[128:131], 0
	ds_read_b128 v[208:211], v185 offset:32768
	s_waitcnt lgkmcnt(5)
	v_mfma_f32_32x32x16_bf16 v[80:95], v[212:215], v[128:131], 0
	ds_read_b128 v[212:215], v185 offset:36864
	s_waitcnt lgkmcnt(5)
	v_mfma_f32_32x32x16_bf16 v[64:79], v[216:219], v[132:135], v[64:79]
	s_waitcnt lgkmcnt(4)
	v_mfma_f32_32x32x16_bf16 v[80:95], v[220:223], v[132:135], v[80:95]
	s_waitcnt lgkmcnt(3)
	v_mfma_f32_32x32x16_bf16 v[64:79], v[224:227], v[136:139], v[64:79]
	s_waitcnt lgkmcnt(2)
	v_mfma_f32_32x32x16_bf16 v[80:95], v[228:231], v[136:139], v[80:95]
	s_waitcnt lgkmcnt(1)
	v_mfma_f32_32x32x16_bf16 v[64:79], v[208:211], v[140:143], v[64:79]
	s_waitcnt lgkmcnt(0)
	v_mfma_f32_32x32x16_bf16 v[80:95], v[212:215], v[140:143], v[80:95]
	s_waitcnt vmcnt(4)
	s_barrier

.Lattn_noresc_L0_B:
.Lattn_top_L1_B:
	s_waitcnt lgkmcnt(5)
	v_mfma_f32_32x32x16_bf16 v[48:63], v[216:219], v[144:147], v[48:63]
	ds_read_b128 v[216:219], v188 offset:24576
	s_add_i32 s2, s42, 5
	s_waitcnt lgkmcnt(5)
	v_mfma_f32_32x32x16_bf16 v[32:47], v[220:223], v[144:147], v[32:47]
	ds_read_b128 v[220:223], v188 offset:28672
	s_and_b32 s2, s2, 31
	s_waitcnt lgkmcnt(5)
	v_mfma_f32_32x32x16_bf16 v[16:31], v[224:227], v[144:147], v[16:31]
	ds_read_b128 v[224:227], v186 offset:16384
	s_mul_i32 s2, s2, 0x44000
	s_waitcnt lgkmcnt(5)
	v_mfma_f32_32x32x16_bf16 v[0:15], v[228:231], v[144:147], v[0:15]
	ds_read_b128 v[228:231], v186 offset:20480
	s_add_u32 s48, s26, s2
	s_waitcnt lgkmcnt(5)
	v_mfma_f32_32x32x16_bf16 v[48:63], v[208:211], v[148:151], v[48:63]
	ds_read_b128 v[208:211], v186 offset:24576
	s_addc_u32 s49, s27, 0
	s_waitcnt lgkmcnt(5)
	v_mfma_f32_32x32x16_bf16 v[32:47], v[212:215], v[148:151], v[32:47]
	ds_read_b128 v[212:215], v186 offset:28672
	s_add_u32 s50, s48, 0x80
	s_waitcnt lgkmcnt(5)
	v_mfma_f32_32x32x16_bf16 v[16:31], v[216:219], v[148:151], v[16:31]
	ds_read_b128 v[216:219], v189 offset:16384
	s_addc_u32 s51, s49, 0
	s_waitcnt lgkmcnt(5)
	v_mfma_f32_32x32x16_bf16 v[0:15], v[220:223], v[148:151], v[0:15]
	ds_read_b128 v[220:223], v189 offset:20480
	s_add_i32 s2, s42, 3
	s_waitcnt lgkmcnt(5)
	v_mfma_f32_32x32x16_bf16 v[48:63], v[224:227], v[152:155], v[48:63]
	ds_read_b128 v[224:227], v189 offset:24576
	s_and_b32 s2, s2, 31
	s_waitcnt lgkmcnt(5)
	v_mfma_f32_32x32x16_bf16 v[32:47], v[228:231], v[152:155], v[32:47]
	ds_read_b128 v[228:231], v189 offset:28672
	s_lshl_b32 s2, s2, 7
	s_waitcnt lgkmcnt(5)
	v_mfma_f32_32x32x16_bf16 v[16:31], v[208:211], v[152:155], v[16:31]
	ds_read_b128 v[208:211], v182 offset:49152
	s_add_u32 s52, s10, s2
	s_waitcnt lgkmcnt(5)
	v_mfma_f32_32x32x16_bf16 v[0:15], v[212:215], v[152:155], v[0:15]
	ds_read_b128 v[212:215], v182 offset:53248
	s_addc_u32 s53, s11, 0
	s_waitcnt lgkmcnt(5)
	v_mfma_f32_32x32x16_bf16 v[48:63], v[216:219], v[156:159], v[48:63]
	ds_read_b128 v[216:219], v183 offset:49152
	s_add_u32 s54, s52, 0x204000
	s_waitcnt lgkmcnt(5)
	v_mfma_f32_32x32x16_bf16 v[32:47], v[220:223], v[156:159], v[32:47]
	ds_read_b128 v[220:223], v183 offset:53248
	s_addc_u32 s55, s53, 0
	s_waitcnt lgkmcnt(5)
	v_mfma_f32_32x32x16_bf16 v[16:31], v[224:227], v[156:159], v[16:31]
	ds_read_b128 v[224:227], v184 offset:49152
	s_waitcnt lgkmcnt(5)
	v_mfma_f32_32x32x16_bf16 v[0:15], v[228:231], v[156:159], v[0:15]
	ds_read_b128 v[228:231], v184 offset:53248
	s_waitcnt lgkmcnt(5)
	v_mfma_f32_32x32x16_bf16 v[96:111], v[208:211], v[128:131], 0
	ds_read_b128 v[208:211], v185 offset:49152
	s_waitcnt lgkmcnt(5)
	v_mfma_f32_32x32x16_bf16 v[112:127], v[212:215], v[128:131], 0
	ds_read_b128 v[212:215], v185 offset:53248
	s_waitcnt lgkmcnt(5)
	v_mfma_f32_32x32x16_bf16 v[96:111], v[216:219], v[132:135], v[96:111]
	s_waitcnt lgkmcnt(4)
	v_mfma_f32_32x32x16_bf16 v[112:127], v[220:223], v[132:135], v[112:127]
	s_waitcnt lgkmcnt(3)
	v_mfma_f32_32x32x16_bf16 v[96:111], v[224:227], v[136:139], v[96:111]
	s_waitcnt lgkmcnt(2)
	v_mfma_f32_32x32x16_bf16 v[112:127], v[228:231], v[136:139], v[112:127]
	s_waitcnt lgkmcnt(1)
	v_mfma_f32_32x32x16_bf16 v[96:111], v[208:211], v[140:143], v[96:111]
	s_waitcnt lgkmcnt(0)
	v_mfma_f32_32x32x16_bf16 v[112:127], v[212:215], v[140:143], v[112:127]
	s_waitcnt vmcnt(4)
	s_barrier

.Lattn_noresc_L1_B:
.Lattn_top_L2_B:
	s_waitcnt lgkmcnt(5)
	v_mfma_f32_32x32x16_bf16 v[48:63], v[216:219], v[144:147], v[48:63]
	ds_read_b128 v[216:219], v188 offset:40960
	s_add_i32 s2, s42, 6
	s_waitcnt lgkmcnt(5)
	v_mfma_f32_32x32x16_bf16 v[32:47], v[220:223], v[144:147], v[32:47]
	ds_read_b128 v[220:223], v188 offset:45056
	s_and_b32 s2, s2, 31
	s_waitcnt lgkmcnt(5)
	v_mfma_f32_32x32x16_bf16 v[16:31], v[224:227], v[144:147], v[16:31]
	ds_read_b128 v[224:227], v186 offset:32768
	s_mul_i32 s2, s2, 0x44000
	s_waitcnt lgkmcnt(5)
	v_mfma_f32_32x32x16_bf16 v[0:15], v[228:231], v[144:147], v[0:15]
	ds_read_b128 v[228:231], v186 offset:36864
	s_add_u32 s48, s26, s2
	s_waitcnt lgkmcnt(5)
	v_mfma_f32_32x32x16_bf16 v[48:63], v[208:211], v[148:151], v[48:63]
	ds_read_b128 v[208:211], v186 offset:40960
	s_addc_u32 s49, s27, 0
	s_waitcnt lgkmcnt(5)
	v_mfma_f32_32x32x16_bf16 v[32:47], v[212:215], v[148:151], v[32:47]
	ds_read_b128 v[212:215], v186 offset:45056
	s_add_u32 s50, s48, 0x80
	s_waitcnt lgkmcnt(5)
	v_mfma_f32_32x32x16_bf16 v[16:31], v[216:219], v[148:151], v[16:31]
	ds_read_b128 v[216:219], v189 offset:32768
	s_addc_u32 s51, s49, 0
	s_waitcnt lgkmcnt(5)
	v_mfma_f32_32x32x16_bf16 v[0:15], v[220:223], v[148:151], v[0:15]
	ds_read_b128 v[220:223], v189 offset:36864
	s_add_i32 s2, s42, 4
	s_waitcnt lgkmcnt(5)
	v_mfma_f32_32x32x16_bf16 v[48:63], v[224:227], v[152:155], v[48:63]
	ds_read_b128 v[224:227], v189 offset:40960
	s_and_b32 s2, s2, 31
	s_waitcnt lgkmcnt(5)
	v_mfma_f32_32x32x16_bf16 v[32:47], v[228:231], v[152:155], v[32:47]
	ds_read_b128 v[228:231], v189 offset:45056
	s_lshl_b32 s2, s2, 7
	s_waitcnt lgkmcnt(5)
	v_mfma_f32_32x32x16_bf16 v[16:31], v[208:211], v[152:155], v[16:31]
	ds_read_b128 v[208:211], v182 offset:0
	s_add_u32 s52, s10, s2
	s_waitcnt lgkmcnt(5)
	v_mfma_f32_32x32x16_bf16 v[0:15], v[212:215], v[152:155], v[0:15]
	ds_read_b128 v[212:215], v182 offset:4096
	s_addc_u32 s53, s11, 0
	s_waitcnt lgkmcnt(5)
	v_mfma_f32_32x32x16_bf16 v[48:63], v[216:219], v[156:159], v[48:63]
	ds_read_b128 v[216:219], v183 offset:0
	s_add_u32 s54, s52, 0x204000
	s_waitcnt lgkmcnt(5)
	v_mfma_f32_32x32x16_bf16 v[32:47], v[220:223], v[156:159], v[32:47]
	ds_read_b128 v[220:223], v183 offset:4096
	s_addc_u32 s55, s53, 0
	s_waitcnt lgkmcnt(5)
	v_mfma_f32_32x32x16_bf16 v[16:31], v[224:227], v[156:159], v[16:31]
	ds_read_b128 v[224:227], v184 offset:0
	s_waitcnt lgkmcnt(5)
	v_mfma_f32_32x32x16_bf16 v[0:15], v[228:231], v[156:159], v[0:15]
	ds_read_b128 v[228:231], v184 offset:4096
	s_waitcnt lgkmcnt(5)
	v_mfma_f32_32x32x16_bf16 v[64:79], v[208:211], v[128:131], 0
	ds_read_b128 v[208:211], v185 offset:0
	s_waitcnt lgkmcnt(5)
	v_mfma_f32_32x32x16_bf16 v[80:95], v[212:215], v[128:131], 0
	ds_read_b128 v[212:215], v185 offset:4096
	s_waitcnt lgkmcnt(5)
	v_mfma_f32_32x32x16_bf16 v[64:79], v[216:219], v[132:135], v[64:79]
	s_waitcnt lgkmcnt(4)
	v_mfma_f32_32x32x16_bf16 v[80:95], v[220:223], v[132:135], v[80:95]
	s_waitcnt lgkmcnt(3)
	v_mfma_f32_32x32x16_bf16 v[64:79], v[224:227], v[136:139], v[64:79]
	s_waitcnt lgkmcnt(2)
	v_mfma_f32_32x32x16_bf16 v[80:95], v[228:231], v[136:139], v[80:95]
	s_waitcnt lgkmcnt(1)
	v_mfma_f32_32x32x16_bf16 v[64:79], v[208:211], v[140:143], v[64:79]
	s_waitcnt lgkmcnt(0)
	v_mfma_f32_32x32x16_bf16 v[80:95], v[212:215], v[140:143], v[80:95]
	s_waitcnt vmcnt(4)
	s_barrier

.Lattn_noresc_L2_B:
.Lattn_top_L3_B:
	s_waitcnt lgkmcnt(5)
	v_mfma_f32_32x32x16_bf16 v[48:63], v[216:219], v[144:147], v[48:63]
	ds_read_b128 v[216:219], v188 offset:57344
	s_add_i32 s2, s42, 7
	s_waitcnt lgkmcnt(5)
	v_mfma_f32_32x32x16_bf16 v[32:47], v[220:223], v[144:147], v[32:47]
	ds_read_b128 v[220:223], v188 offset:61440
	s_and_b32 s2, s2, 31
	s_waitcnt lgkmcnt(5)
	v_mfma_f32_32x32x16_bf16 v[16:31], v[224:227], v[144:147], v[16:31]
	ds_read_b128 v[224:227], v186 offset:49152
	s_mul_i32 s2, s2, 0x44000
	s_waitcnt lgkmcnt(5)
	v_mfma_f32_32x32x16_bf16 v[0:15], v[228:231], v[144:147], v[0:15]
	ds_read_b128 v[228:231], v186 offset:53248
	s_add_u32 s48, s26, s2
	s_waitcnt lgkmcnt(5)
	v_mfma_f32_32x32x16_bf16 v[48:63], v[208:211], v[148:151], v[48:63]
	ds_read_b128 v[208:211], v186 offset:57344
	s_addc_u32 s49, s27, 0
	s_waitcnt lgkmcnt(5)
	v_mfma_f32_32x32x16_bf16 v[32:47], v[212:215], v[148:151], v[32:47]
	ds_read_b128 v[212:215], v186 offset:61440
	s_add_u32 s50, s48, 0x80
	s_waitcnt lgkmcnt(5)
	v_mfma_f32_32x32x16_bf16 v[16:31], v[216:219], v[148:151], v[16:31]
	ds_read_b128 v[216:219], v189 offset:49152
	s_addc_u32 s51, s49, 0
	s_waitcnt lgkmcnt(5)
	v_mfma_f32_32x32x16_bf16 v[0:15], v[220:223], v[148:151], v[0:15]
	ds_read_b128 v[220:223], v189 offset:53248
	s_add_i32 s2, s42, 5
	s_waitcnt lgkmcnt(5)
	v_mfma_f32_32x32x16_bf16 v[48:63], v[224:227], v[152:155], v[48:63]
	ds_read_b128 v[224:227], v189 offset:57344
	s_and_b32 s2, s2, 31
	s_waitcnt lgkmcnt(5)
	v_mfma_f32_32x32x16_bf16 v[32:47], v[228:231], v[152:155], v[32:47]
	ds_read_b128 v[228:231], v189 offset:61440
	s_lshl_b32 s2, s2, 7
	s_waitcnt lgkmcnt(5)
	v_mfma_f32_32x32x16_bf16 v[16:31], v[208:211], v[152:155], v[16:31]
	ds_read_b128 v[208:211], v182 offset:16384
	s_add_u32 s52, s10, s2
	s_waitcnt lgkmcnt(5)
	v_mfma_f32_32x32x16_bf16 v[0:15], v[212:215], v[152:155], v[0:15]
	ds_read_b128 v[212:215], v182 offset:20480
	s_addc_u32 s53, s11, 0
	s_waitcnt lgkmcnt(5)
	v_mfma_f32_32x32x16_bf16 v[48:63], v[216:219], v[156:159], v[48:63]
	ds_read_b128 v[216:219], v183 offset:16384
	s_add_u32 s54, s52, 0x204000
	s_waitcnt lgkmcnt(5)
	v_mfma_f32_32x32x16_bf16 v[32:47], v[220:223], v[156:159], v[32:47]
	ds_read_b128 v[220:223], v183 offset:20480
	s_addc_u32 s55, s53, 0
	s_waitcnt lgkmcnt(5)
	v_mfma_f32_32x32x16_bf16 v[16:31], v[224:227], v[156:159], v[16:31]
	ds_read_b128 v[224:227], v184 offset:16384
	s_waitcnt lgkmcnt(5)
	v_mfma_f32_32x32x16_bf16 v[0:15], v[228:231], v[156:159], v[0:15]
	ds_read_b128 v[228:231], v184 offset:20480
	s_waitcnt lgkmcnt(5)
	v_mfma_f32_32x32x16_bf16 v[96:111], v[208:211], v[128:131], 0
	ds_read_b128 v[208:211], v185 offset:16384
	s_waitcnt lgkmcnt(5)
	v_mfma_f32_32x32x16_bf16 v[112:127], v[212:215], v[128:131], 0
	ds_read_b128 v[212:215], v185 offset:20480
	s_waitcnt lgkmcnt(5)
	v_mfma_f32_32x32x16_bf16 v[96:111], v[216:219], v[132:135], v[96:111]
	s_waitcnt lgkmcnt(4)
	v_mfma_f32_32x32x16_bf16 v[112:127], v[220:223], v[132:135], v[112:127]
	s_waitcnt lgkmcnt(3)
	v_mfma_f32_32x32x16_bf16 v[96:111], v[224:227], v[136:139], v[96:111]
	s_waitcnt lgkmcnt(2)
	v_mfma_f32_32x32x16_bf16 v[112:127], v[228:231], v[136:139], v[112:127]
	s_waitcnt lgkmcnt(1)
	v_mfma_f32_32x32x16_bf16 v[96:111], v[208:211], v[140:143], v[96:111]
	s_waitcnt lgkmcnt(0)
	v_mfma_f32_32x32x16_bf16 v[112:127], v[212:215], v[140:143], v[112:127]
	s_waitcnt vmcnt(4)
	s_barrier

.Lattn_top_T29_B:
	s_waitcnt lgkmcnt(5)
	v_mfma_f32_32x32x16_bf16 v[48:63], v[216:219], v[144:147], v[48:63]
	ds_read_b128 v[216:219], v188 offset:8192
	s_add_i32 s2, s42, 2
	s_waitcnt lgkmcnt(5)
	v_mfma_f32_32x32x16_bf16 v[32:47], v[220:223], v[144:147], v[32:47]
	ds_read_b128 v[220:223], v188 offset:12288
	s_and_b32 s2, s2, 31
	s_waitcnt lgkmcnt(5)
	v_mfma_f32_32x32x16_bf16 v[16:31], v[224:227], v[144:147], v[16:31]
	ds_read_b128 v[224:227], v186 offset:0
	s_lshl_b32 s2, s2, 7
	s_waitcnt lgkmcnt(5)
	v_mfma_f32_32x32x16_bf16 v[0:15], v[228:231], v[144:147], v[0:15]
	ds_read_b128 v[228:231], v186 offset:4096
	s_add_u32 s52, s10, s2
	s_waitcnt lgkmcnt(5)
	v_mfma_f32_32x32x16_bf16 v[48:63], v[208:211], v[148:151], v[48:63]
	ds_read_b128 v[208:211], v186 offset:8192
	s_addc_u32 s53, s11, 0
	s_waitcnt lgkmcnt(5)
	v_mfma_f32_32x32x16_bf16 v[32:47], v[212:215], v[148:151], v[32:47]
	ds_read_b128 v[212:215], v186 offset:12288
	s_add_u32 s54, s52, 0x204000
	s_waitcnt lgkmcnt(5)
	v_mfma_f32_32x32x16_bf16 v[16:31], v[216:219], v[148:151], v[16:31]
	ds_read_b128 v[216:219], v189 offset:0
	s_addc_u32 s55, s53, 0
	s_waitcnt lgkmcnt(5)
	v_mfma_f32_32x32x16_bf16 v[0:15], v[220:223], v[148:151], v[0:15]
	ds_read_b128 v[220:223], v189 offset:4096
	s_waitcnt lgkmcnt(5)
	v_mfma_f32_32x32x16_bf16 v[48:63], v[224:227], v[152:155], v[48:63]
	ds_read_b128 v[224:227], v189 offset:8192
	s_waitcnt lgkmcnt(5)
	v_mfma_f32_32x32x16_bf16 v[32:47], v[228:231], v[152:155], v[32:47]
	ds_read_b128 v[228:231], v189 offset:12288
	s_waitcnt lgkmcnt(5)
	v_mfma_f32_32x32x16_bf16 v[16:31], v[208:211], v[152:155], v[16:31]
	ds_read_b128 v[208:211], v182 offset:32768
	s_waitcnt lgkmcnt(5)
	v_mfma_f32_32x32x16_bf16 v[0:15], v[212:215], v[152:155], v[0:15]
	ds_read_b128 v[212:215], v182 offset:36864
	s_waitcnt lgkmcnt(5)
	v_mfma_f32_32x32x16_bf16 v[48:63], v[216:219], v[156:159], v[48:63]
	ds_read_b128 v[216:219], v183 offset:32768
	s_waitcnt lgkmcnt(5)
	v_mfma_f32_32x32x16_bf16 v[32:47], v[220:223], v[156:159], v[32:47]
	ds_read_b128 v[220:223], v183 offset:36864
	s_waitcnt lgkmcnt(5)
	v_mfma_f32_32x32x16_bf16 v[16:31], v[224:227], v[156:159], v[16:31]
	ds_read_b128 v[224:227], v184 offset:32768
	s_waitcnt lgkmcnt(5)
	v_mfma_f32_32x32x16_bf16 v[0:15], v[228:231], v[156:159], v[0:15]
	ds_read_b128 v[228:231], v184 offset:36864
	s_waitcnt lgkmcnt(5)
	v_mfma_f32_32x32x16_bf16 v[64:79], v[208:211], v[128:131], 0
	ds_read_b128 v[208:211], v185 offset:32768
	s_waitcnt lgkmcnt(5)
	v_mfma_f32_32x32x16_bf16 v[80:95], v[212:215], v[128:131], 0
	ds_read_b128 v[212:215], v185 offset:36864
	s_waitcnt lgkmcnt(5)
	v_mfma_f32_32x32x16_bf16 v[64:79], v[216:219], v[132:135], v[64:79]
	s_waitcnt lgkmcnt(4)
	v_mfma_f32_32x32x16_bf16 v[80:95], v[220:223], v[132:135], v[80:95]
	s_waitcnt lgkmcnt(3)
	v_mfma_f32_32x32x16_bf16 v[64:79], v[224:227], v[136:139], v[64:79]
	s_waitcnt lgkmcnt(2)
	v_mfma_f32_32x32x16_bf16 v[80:95], v[228:231], v[136:139], v[80:95]
	s_waitcnt lgkmcnt(1)
	v_mfma_f32_32x32x16_bf16 v[64:79], v[208:211], v[140:143], v[64:79]
	s_waitcnt lgkmcnt(0)
	v_mfma_f32_32x32x16_bf16 v[80:95], v[212:215], v[140:143], v[80:95]
	s_waitcnt vmcnt(4)
	s_barrier

.Lattn_noresc_T29_B:
.Lattn_top_T30_B:
	s_waitcnt lgkmcnt(5)
	v_mfma_f32_32x32x16_bf16 v[48:63], v[216:219], v[144:147], v[48:63]
	ds_read_b128 v[216:219], v188 offset:24576
	s_waitcnt lgkmcnt(5)
	v_mfma_f32_32x32x16_bf16 v[32:47], v[220:223], v[144:147], v[32:47]
	ds_read_b128 v[220:223], v188 offset:28672
	s_waitcnt lgkmcnt(5)
	v_mfma_f32_32x32x16_bf16 v[16:31], v[224:227], v[144:147], v[16:31]
	ds_read_b128 v[224:227], v186 offset:16384
	s_waitcnt lgkmcnt(5)
	v_mfma_f32_32x32x16_bf16 v[0:15], v[228:231], v[144:147], v[0:15]
	ds_read_b128 v[228:231], v186 offset:20480
	s_waitcnt lgkmcnt(5)
	v_mfma_f32_32x32x16_bf16 v[48:63], v[208:211], v[148:151], v[48:63]
	ds_read_b128 v[208:211], v186 offset:24576
	s_waitcnt lgkmcnt(5)
	v_mfma_f32_32x32x16_bf16 v[32:47], v[212:215], v[148:151], v[32:47]
	ds_read_b128 v[212:215], v186 offset:28672
	s_waitcnt lgkmcnt(5)
	v_mfma_f32_32x32x16_bf16 v[16:31], v[216:219], v[148:151], v[16:31]
	ds_read_b128 v[216:219], v189 offset:16384
	s_waitcnt lgkmcnt(5)
	v_mfma_f32_32x32x16_bf16 v[0:15], v[220:223], v[148:151], v[0:15]
	ds_read_b128 v[220:223], v189 offset:20480
	s_waitcnt lgkmcnt(5)
	v_mfma_f32_32x32x16_bf16 v[48:63], v[224:227], v[152:155], v[48:63]
	ds_read_b128 v[224:227], v189 offset:24576
	s_waitcnt lgkmcnt(5)
	v_mfma_f32_32x32x16_bf16 v[32:47], v[228:231], v[152:155], v[32:47]
	ds_read_b128 v[228:231], v189 offset:28672
	s_waitcnt lgkmcnt(5)
	v_mfma_f32_32x32x16_bf16 v[16:31], v[208:211], v[152:155], v[16:31]
	ds_read_b128 v[208:211], v182 offset:49152
	s_waitcnt lgkmcnt(5)
	v_mfma_f32_32x32x16_bf16 v[0:15], v[212:215], v[152:155], v[0:15]
	ds_read_b128 v[212:215], v182 offset:53248
	s_waitcnt lgkmcnt(5)
	v_mfma_f32_32x32x16_bf16 v[48:63], v[216:219], v[156:159], v[48:63]
	ds_read_b128 v[216:219], v183 offset:49152
	s_waitcnt lgkmcnt(5)
	v_mfma_f32_32x32x16_bf16 v[32:47], v[220:223], v[156:159], v[32:47]
	ds_read_b128 v[220:223], v183 offset:53248
	s_waitcnt lgkmcnt(5)
	v_mfma_f32_32x32x16_bf16 v[16:31], v[224:227], v[156:159], v[16:31]
	ds_read_b128 v[224:227], v184 offset:49152
	s_waitcnt lgkmcnt(5)
	v_mfma_f32_32x32x16_bf16 v[0:15], v[228:231], v[156:159], v[0:15]
	ds_read_b128 v[228:231], v184 offset:53248
	s_waitcnt lgkmcnt(5)
	v_mfma_f32_32x32x16_bf16 v[96:111], v[208:211], v[128:131], 0
	ds_read_b128 v[208:211], v185 offset:49152
	s_waitcnt lgkmcnt(5)
	v_mfma_f32_32x32x16_bf16 v[112:127], v[212:215], v[128:131], 0
	ds_read_b128 v[212:215], v185 offset:53248
	s_waitcnt lgkmcnt(5)
	v_mfma_f32_32x32x16_bf16 v[96:111], v[216:219], v[132:135], v[96:111]
	s_waitcnt lgkmcnt(4)
	v_mfma_f32_32x32x16_bf16 v[112:127], v[220:223], v[132:135], v[112:127]
	s_waitcnt lgkmcnt(3)
	v_mfma_f32_32x32x16_bf16 v[96:111], v[224:227], v[136:139], v[96:111]
	s_waitcnt lgkmcnt(2)
	v_mfma_f32_32x32x16_bf16 v[112:127], v[228:231], v[136:139], v[112:127]
	s_waitcnt lgkmcnt(1)
	v_mfma_f32_32x32x16_bf16 v[96:111], v[208:211], v[140:143], v[96:111]
	s_waitcnt lgkmcnt(0)
	v_mfma_f32_32x32x16_bf16 v[112:127], v[212:215], v[140:143], v[112:127]
	s_waitcnt vmcnt(2)
	s_barrier

.Lattn_noresc_T30_B:
.Lattn_top_T31_B:
	s_waitcnt lgkmcnt(5)
	v_mfma_f32_32x32x16_bf16 v[48:63], v[216:219], v[144:147], v[48:63]
	ds_read_b128 v[216:219], v188 offset:40960
	s_waitcnt lgkmcnt(5)
	v_mfma_f32_32x32x16_bf16 v[32:47], v[220:223], v[144:147], v[32:47]
	ds_read_b128 v[220:223], v188 offset:45056
	s_waitcnt lgkmcnt(5)
	v_mfma_f32_32x32x16_bf16 v[16:31], v[224:227], v[144:147], v[16:31]
	ds_read_b128 v[224:227], v186 offset:32768
	s_waitcnt lgkmcnt(5)
	v_mfma_f32_32x32x16_bf16 v[0:15], v[228:231], v[144:147], v[0:15]
	ds_read_b128 v[228:231], v186 offset:36864
	s_waitcnt lgkmcnt(5)
	v_mfma_f32_32x32x16_bf16 v[48:63], v[208:211], v[148:151], v[48:63]
	ds_read_b128 v[208:211], v186 offset:40960
	s_waitcnt lgkmcnt(5)
	v_mfma_f32_32x32x16_bf16 v[32:47], v[212:215], v[148:151], v[32:47]
	ds_read_b128 v[212:215], v186 offset:45056
	s_waitcnt lgkmcnt(5)
	v_mfma_f32_32x32x16_bf16 v[16:31], v[216:219], v[148:151], v[16:31]
	ds_read_b128 v[216:219], v189 offset:32768
	s_waitcnt lgkmcnt(5)
	v_mfma_f32_32x32x16_bf16 v[0:15], v[220:223], v[148:151], v[0:15]
	ds_read_b128 v[220:223], v189 offset:36864
	s_waitcnt lgkmcnt(5)
	v_mfma_f32_32x32x16_bf16 v[48:63], v[224:227], v[152:155], v[48:63]
	ds_read_b128 v[224:227], v189 offset:40960
	s_waitcnt lgkmcnt(5)
	v_mfma_f32_32x32x16_bf16 v[32:47], v[228:231], v[152:155], v[32:47]
	ds_read_b128 v[228:231], v189 offset:45056
	s_waitcnt lgkmcnt(5)
	v_mfma_f32_32x32x16_bf16 v[16:31], v[208:211], v[152:155], v[16:31]
	s_waitcnt lgkmcnt(4)
	v_mfma_f32_32x32x16_bf16 v[0:15], v[212:215], v[152:155], v[0:15]
	s_waitcnt lgkmcnt(3)
	v_mfma_f32_32x32x16_bf16 v[48:63], v[216:219], v[156:159], v[48:63]
	s_waitcnt lgkmcnt(2)
	v_mfma_f32_32x32x16_bf16 v[32:47], v[220:223], v[156:159], v[32:47]
	s_waitcnt lgkmcnt(1)
	v_mfma_f32_32x32x16_bf16 v[16:31], v[224:227], v[156:159], v[16:31]
	s_waitcnt lgkmcnt(0)
	v_mfma_f32_32x32x16_bf16 v[0:15], v[228:231], v[156:159], v[0:15]
	s_cmp_lg_u32 s35, 0
	s_cbranch_scc1 .Lattn_tb64_w6_B
	s_waitcnt vmcnt(0)
	s_branch .Lattn_tb64_wd_B
